# LDS reads hoisted (renamed to dead registers, waits re-counted) inside the straight-line blocks of ssd_passB tile epilogues, hg_unit steps, hg_passB tail, ssd_passA and attention
# speedup vs baseline: 1.0034x; 1.0034x over previous
; __device__ __forceinline__ float shx(float v, int o, int lane) { return __builtin_bit_cast(float, __builtin_amdgcn_ds_bpermute((lane ^ o) << 2, __builtin_bit_cast(int, v))); }
; __device__ __forceinline__ void attn_unit(const Ptrs& P, int l, int b, int gk, int n, unsigned char* lds, int tid, bool dost) {
;     ...
;         float mx = sink;
; #pragma unroll
;         for (int kt = 0; kt < 9; ++kt)
; #pragma unroll
;             for (int r = 0; r < 4; ++r) { const int dist = 128 + lc - 16 * kt - 4 * g - r; const int j = 16 * (qs + kt) + 4 * g + r;
;                 const bool valid = (dist >= 0) && (dist < 128) && (n >= 1) && (n >= 2 || j >= 128);
;                 const float lg = valid ? (st[kt][r] * 0.125f + hb[w * 128 + (dist & 127)]) : NEGV; st[kt][r] = lg; mx = fmaxf(mx, lg); }
; #pragma unroll
;         for (int r = 0; r < 4; ++r) { const int dist = tq - (4 * g + r); const bool valid = dist >= 0; const int bk = (dist >= 0 && dist < 128) ? bkt[dist & 127] : 31;
;             const float lg = valid ? (st[9][r] * 0.125f + rb[bk * 16 + head]) : NEGV; st[9][r] = lg; mx = fmaxf(mx, lg); }
;         mx = fmaxf(mx, shx(mx, 16, lane)); mx = fmaxf(mx, shx(mx, 32, lane));
;         float sum = 0.f;
; #pragma unroll
;         for (int kt = 0; kt < 10; ++kt)
; #pragma unroll
;             for (int r = 0; r < 4; ++r) { const float p = __expf(st[kt][r] - mx); st[kt][r] = p; sum += p; }
;         sum += shx(sum, 16, lane); sum += shx(sum, 32, lane);
;         const float inv = 1.0f / (sum + __expf(sink - mx));
.LBB0_320:
	s_or_b64 exec, exec, s[12:13]
	v_max3_f32 v41, v17, v73, v70
	v_max3_f32 v41, v41, v78, v72
	v_max3_f32 v41, v41, v79, v22
	v_max3_f32 v41, v41, v27, v23
	v_max3_f32 v41, v41, v71, v26
	v_max3_f32 v41, v41, v67, v66
	v_max3_f32 v41, v41, v69, v68
	v_max3_f32 v41, v41, v63, v62
	v_max3_f32 v41, v41, v65, v64
	v_max3_f32 v41, v41, v59, v58
	v_max3_f32 v41, v41, v61, v60
	v_max3_f32 v41, v41, v55, v54
	v_max3_f32 v41, v41, v57, v56
	v_max3_f32 v41, v41, v51, v50
	v_max3_f32 v41, v41, v53, v52
	v_max3_f32 v41, v41, v74, v47
	v_max3_f32 v41, v41, v49, v48
	v_max3_f32 v41, v41, v43, v42
	s_cmpk_lt_u32 s17, 0x80
	v_max3_f32 v41, v41, v44, v38
	s_cselect_b64 vcc, -1, 0
	v_cndmask_b32_e32 v45, v121, v124, vcc
	v_max3_f32 v41, v41, v39, v40
	v_add_u32_e32 v46, s15, v45
	ds_bpermute_b32 v45, v109, v41
	v_add_u32_e32 v147, 0, v119
	v_add_u32_e32 v130, 0x100, v147
	v_add_u32_e32 v148, 0x2000, v147
	s_add_i32 s12, s19, 1
	s_waitcnt lgkmcnt(0)
	v_max_f32_e32 v45, v45, v45
	v_max_f32_e32 v41, v41, v45
	ds_bpermute_b32 v45, v110, v41
	ds_read2_b64 v[216:219], v148 offset0:100 offset1:104
	s_add_i32 s15, s15, 16
	v_add_u32_e32 v118, 0x900, v118
	v_add_u32_e32 v119, 32, v119
	v_add_u32_e32 v122, 64, v122
	s_waitcnt lgkmcnt(1)
	v_max_f32_e32 v45, v45, v45
	v_max_f32_e32 v41, v41, v45
	v_sub_f32_e32 v23, v23, v41
	v_mul_f32_e32 v23, 0x3fb8aa3b, v23
	v_sub_f32_e32 v75, v78, v41
	v_exp_f32_e32 v78, v23
	v_sub_f32_e32 v23, v71, v41
	v_mul_f32_e32 v23, 0x3fb8aa3b, v23
	v_exp_f32_e32 v80, v23
	v_sub_f32_e32 v23, v26, v41
	v_mul_f32_e32 v23, 0x3fb8aa3b, v23
	v_exp_f32_e32 v81, v23
	v_sub_f32_e32 v23, v67, v41
	v_mul_f32_e32 v23, 0x3fb8aa3b, v23
	v_exp_f32_e32 v125, v23
	v_sub_f32_e32 v23, v66, v41
	v_mul_f32_e32 v23, 0x3fb8aa3b, v23
	v_exp_f32_e32 v138, v23
	v_sub_f32_e32 v23, v69, v41
	v_mul_f32_e32 v23, 0x3fb8aa3b, v23
	v_exp_f32_e32 v139, v23
	v_sub_f32_e32 v23, v68, v41
	v_mul_f32_e32 v23, 0x3fb8aa3b, v23
	v_sub_f32_e32 v45, v73, v41
	v_exp_f32_e32 v140, v23
	v_sub_f32_e32 v23, v63, v41
	v_mul_f32_e32 v45, 0x3fb8aa3b, v45
	v_sub_f32_e32 v70, v70, v41
	v_mul_f32_e32 v23, 0x3fb8aa3b, v23
	v_exp_f32_e32 v45, v45
	v_mul_f32_e32 v70, 0x3fb8aa3b, v70
	v_exp_f32_e32 v141, v23
	v_sub_f32_e32 v23, v62, v41
	v_exp_f32_e32 v70, v70
	v_mul_f32_e32 v75, 0x3fb8aa3b, v75
	v_sub_f32_e32 v72, v72, v41
	v_mul_f32_e32 v23, 0x3fb8aa3b, v23
	v_exp_f32_e32 v75, v75
	v_mul_f32_e32 v72, 0x3fb8aa3b, v72
	v_sub_f32_e32 v76, v79, v41
	v_exp_f32_e32 v142, v23
	v_sub_f32_e32 v23, v65, v41
	v_exp_f32_e32 v72, v72
	v_mul_f32_e32 v76, 0x3fb8aa3b, v76
	v_sub_f32_e32 v22, v22, v41
	v_mul_f32_e32 v23, 0x3fb8aa3b, v23
	v_add_f32_e32 v73, 0, v45
	v_exp_f32_e32 v76, v76
	v_mul_f32_e32 v22, 0x3fb8aa3b, v22
	v_exp_f32_e32 v62, v23
	v_sub_f32_e32 v23, v64, v41
	v_add_f32_e32 v73, v70, v73
	v_exp_f32_e32 v77, v22
	v_mul_f32_e32 v23, 0x3fb8aa3b, v23
	v_add_f32_e32 v73, v75, v73
	v_exp_f32_e32 v63, v23
	v_sub_f32_e32 v23, v59, v41
	v_add_f32_e32 v73, v72, v73
	v_sub_f32_e32 v27, v27, v41
	v_mul_f32_e32 v23, 0x3fb8aa3b, v23
	v_add_f32_e32 v73, v76, v73
	v_mul_f32_e32 v27, 0x3fb8aa3b, v27
	v_exp_f32_e32 v59, v23
	v_sub_f32_e32 v23, v58, v41
	v_add_f32_e32 v22, v77, v73
	v_exp_f32_e32 v73, v27
	v_mul_f32_e32 v23, 0x3fb8aa3b, v23
	v_exp_f32_e32 v143, v23
	v_sub_f32_e32 v23, v61, v41
	v_mul_f32_e32 v23, 0x3fb8aa3b, v23
	v_exp_f32_e32 v61, v23
	v_sub_f32_e32 v23, v60, v41
	v_add_f32_e32 v22, v73, v22
	v_mul_f32_e32 v23, 0x3fb8aa3b, v23
	v_add_f32_e32 v22, v78, v22
	v_exp_f32_e32 v144, v23
	v_sub_f32_e32 v23, v55, v41
	v_add_f32_e32 v22, v80, v22
	v_mul_f32_e32 v23, 0x3fb8aa3b, v23
	v_add_f32_e32 v22, v81, v22
	v_exp_f32_e32 v145, v23
	v_sub_f32_e32 v23, v54, v41
	v_add_f32_e32 v22, v125, v22
	v_mul_f32_e32 v23, 0x3fb8aa3b, v23
	v_add_f32_e32 v22, v138, v22
	v_exp_f32_e32 v146, v23
	v_sub_f32_e32 v23, v57, v41
	v_add_f32_e32 v22, v139, v22
	v_mul_f32_e32 v23, 0x3fb8aa3b, v23
	v_add_f32_e32 v22, v140, v22
	v_exp_f32_e32 v54, v23
	v_sub_f32_e32 v23, v56, v41
	v_add_f32_e32 v22, v141, v22
	v_mul_f32_e32 v23, 0x3fb8aa3b, v23
	v_add_f32_e32 v22, v142, v22
	v_exp_f32_e32 v55, v23
	v_sub_f32_e32 v23, v51, v41
	v_add_f32_e32 v22, v62, v22
	v_mul_f32_e32 v23, 0x3fb8aa3b, v23
	v_add_f32_e32 v22, v63, v22
	v_exp_f32_e32 v56, v23
	v_sub_f32_e32 v23, v50, v41
	v_add_f32_e32 v22, v59, v22
	v_mul_f32_e32 v23, 0x3fb8aa3b, v23
	v_add_f32_e32 v22, v143, v22
	v_exp_f32_e32 v57, v23
	v_sub_f32_e32 v23, v53, v41
	v_add_f32_e32 v22, v61, v22
	v_mul_f32_e32 v23, 0x3fb8aa3b, v23
	v_add_f32_e32 v22, v144, v22
	v_exp_f32_e32 v53, v23
	v_sub_f32_e32 v23, v52, v41
	v_add_f32_e32 v22, v145, v22
	v_mul_f32_e32 v23, 0x3fb8aa3b, v23
	v_add_f32_e32 v22, v146, v22
	v_exp_f32_e32 v52, v23
	v_sub_f32_e32 v23, v74, v41
	v_add_f32_e32 v22, v54, v22
	v_mul_f32_e32 v23, 0x3fb8aa3b, v23
	v_add_f32_e32 v22, v55, v22
	v_exp_f32_e32 v58, v23
	v_sub_f32_e32 v23, v47, v41
	v_add_f32_e32 v22, v56, v22
	v_mul_f32_e32 v23, 0x3fb8aa3b, v23
	v_add_f32_e32 v22, v57, v22
	v_exp_f32_e32 v60, v23
	v_add_f32_e32 v22, v53, v22
	v_add_f32_e32 v22, v52, v22
	v_add_f32_e32 v22, v58, v22
	v_add_f32_e32 v23, v60, v22
	v_sub_f32_e32 v22, v49, v41
	v_mul_f32_e32 v22, 0x3fb8aa3b, v22
	v_exp_f32_e32 v22, v22
	v_sub_f32_e32 v38, v38, v41
	v_sub_f32_e32 v39, v39, v41
	v_mul_f32_e32 v38, 0x3fb8aa3b, v38
	v_add_f32_e32 v26, v22, v23
	v_sub_f32_e32 v23, v48, v41
	v_mul_f32_e32 v23, 0x3fb8aa3b, v23
	v_exp_f32_e32 v23, v23
	v_mul_f32_e32 v39, 0x3fb8aa3b, v39
	v_exp_f32_e32 v49, v38
	v_exp_f32_e32 v50, v39
	v_add_f32_e32 v27, v23, v26
	v_sub_f32_e32 v26, v43, v41
	v_mul_f32_e32 v26, 0x3fb8aa3b, v26
	v_exp_f32_e32 v26, v26
	v_sub_f32_e32 v39, v40, v41
	v_mul_f32_e32 v39, 0x3fb8aa3b, v39
	v_exp_f32_e32 v51, v39
	v_add_f32_e32 v43, v26, v27
	v_sub_f32_e32 v27, v42, v41
	v_mul_f32_e32 v27, 0x3fb8aa3b, v27
	v_exp_f32_e32 v27, v27
	v_cvt_pk_bf16_f32 v64, v45, v70
	v_cvt_pk_bf16_f32 v65, v75, v72
	v_cvt_pk_bf16_f32 v67, v73, v78
	v_add_f32_e32 v42, v27, v43
	v_sub_f32_e32 v43, v44, v41
	v_mul_f32_e32 v43, 0x3fb8aa3b, v43
	v_exp_f32_e32 v48, v43
	s_nop 0
	v_cvt_pk_bf16_f32 v66, v76, v77
	v_cvt_pk_bf16_f32 v54, v54, v55
	v_add_f32_e32 v42, v48, v42
	v_add_f32_e32 v38, v49, v42
	v_add_f32_e32 v38, v50, v38
	v_add_f32_e32 v38, v51, v38
	ds_bpermute_b32 v39, v109, v38
	ds_read2st64_b64 v[42:45], v130 offset1:17
	v_cvt_pk_bf16_f32 v55, v56, v57
	v_cvt_pk_bf16_f32 v57, v58, v60
	v_cvt_pk_bf16_f32 v56, v53, v52
	s_waitcnt lgkmcnt(1)
; __device__ __forceinline__ unsigned pk2(float lo, float hi) { f32x2_t v = {lo, hi}; bf16x2_t b = __builtin_convertvector(v, bf16x2_t); return __builtin_bit_cast(unsigned, b); }
; __device__ __forceinline__ float shx(float v, int o, int lane) { return __builtin_bit_cast(float, __builtin_amdgcn_ds_bpermute((lane ^ o) << 2, __builtin_bit_cast(int, v))); }
; __device__ __forceinline__ f32x4 mfma32(bf16x8 a, bf16x8 b, f32x4 c) { return __builtin_amdgcn_mfma_f32_16x16x32_bf16(a, b, c, 0, 0, 0); }
; __device__ __forceinline__ bf16x8 pack8(f32x4 a, f32x4 b) { u32x4 w; w.x = pk2(a[0], a[1]); w.y = pk2(a[2], a[3]); w.z = pk2(b[0], b[1]); w.w = pk2(b[2], b[3]); return __builtin_bit_cast(bf16x8, w); }
; __device__ __forceinline__ void attn_unit(const Ptrs& P, int l, int b, int gk, int n, unsigned char* lds, int tid, bool dost) {
;     ...
;             for (int r = 0; r < 4; ++r) { const float p = __expf(st[kt][r] - mx); st[kt][r] = p; sum += p; }
;         sum += shx(sum, 16, lane); sum += shx(sum, 32, lane);
;         const float inv = 1.0f / (sum + __expf(sink - mx));
;         f32x4 o[4];
; #pragma unroll
;         for (int dt = 0; dt < 4; ++dt) o[dt] = (f32x4){0.f, 0.f, 0.f, 0.f};
; #pragma unroll
;         for (int j = 0; j < 5; ++j) {
;             const bf16x8 pb = pack8(st[2 * j], st[2 * j + 1]);
;             const int colA = 16 * (qs + 2 * j) + 4 * g; const int colB = (j < 4) ? (16 * (qs + 2 * j + 1) + 4 * g) : (256 + 4 * g);
; #pragma unroll
;             for (int dt = 0; dt < 4; ++dt) { const int d = 16 * dt + lc;
;                 const u32x2 lo = *(const u32x2*)(Vt + d * 280 + colA), hi = *(const u32x2*)(Vt + d * 280 + colB);
;                 o[dt] = mfma32(cat8(lo, hi), pb, o[dt]); }
;         }
; #pragma unroll
;         for (int dt = 0; dt < 4; ++dt) { u32x2 wv; wv.x = pk2(o[dt][0] * inv, o[dt][1] * inv); wv.y = pk2(o[dt][2] * inv, o[dt][3] * inv); if (dost) *(u32x2*)(qp + 16 * dt + 4 * g) = wv; }
	v_add_f32_e32 v38, v38, v39
	ds_bpermute_b32 v39, v110, v38
	ds_read2_b64 v[220:223], v147 offset1:4
	s_cmp_lt_u32 s19, 7
	s_mov_b32 s19, s12
	s_waitcnt lgkmcnt(1)
	v_add_f32_e32 v38, v38, v39
	v_sub_f32_e32 v39, v17, v41
	v_mul_f32_e32 v39, 0x3fb8aa3b, v39
	v_exp_f32_e32 v39, v39
	s_nop 0
	v_add_f32_e32 v47, v39, v38
	s_nop 0
	s_waitcnt lgkmcnt(0)
	v_mfma_f32_16x16x32_bf16 v[68:71], v[220:223], v[64:67], 0
	v_mov_b32_e32 v38, v44
	v_mov_b32_e32 v39, v45
	v_mov_b32_e32 v40, v216
	v_mov_b32_e32 v41, v217
	v_add_u32_e32 v44, 0x4000, v147
	ds_read2_b64 v[224:227], v44 offset0:192 offset1:196
	v_add_u32_e32 v45, 0x6800, v147
	v_mfma_f32_16x16x32_bf16 v[76:79], v[38:41], v[64:67], 0
	s_nop 0
	v_mov_b32_e32 v72, v218
	v_mov_b32_e32 v73, v219
	s_waitcnt lgkmcnt(0)
	v_mfma_f32_16x16x32_bf16 v[126:129], v[224:227], v[64:67], 0
	ds_read2st64_b64 v[38:41], v130 offset0:35 offset1:52
	ds_read2_b64 v[228:231], v45 offset0:36 offset1:40
	ds_read2_b64 v[244:247], v147 offset0:8 offset1:12
	ds_read2_b64 v[248:251], v148 offset0:108 offset1:112
	s_nop 0
	s_nop 0
	ds_read2_b64 v[174:177], v44 offset0:200 offset1:204
	ds_read2_b64 v[178:181], v45 offset0:44 offset1:48
	ds_read2_b64 v[182:185], v147 offset0:16 offset1:20
	ds_read2_b64 v[186:189], v147 offset0:24 offset1:28
	ds_read2_b64 v[190:193], v148 offset0:116 offset1:120
	ds_read2_b64 v[196:199], v44 offset0:208 offset1:212
	ds_read2_b64 v[200:203], v45 offset0:52 offset1:56
	s_waitcnt lgkmcnt(10)
	v_mov_b32_e32 v134, v40
	v_mov_b32_e32 v135, v41
	s_waitcnt lgkmcnt(9)
	v_mov_b32_e32 v136, v228
	v_mov_b32_e32 v137, v229
	v_mov_b32_e32 v130, v230
	v_mov_b32_e32 v131, v231
	v_mfma_f32_16x16x32_bf16 v[64:67], v[134:137], v[64:67], 0
	v_cvt_pk_bf16_f32 v135, v125, v138
	v_cvt_pk_bf16_f32 v136, v139, v140
	v_cvt_pk_bf16_f32 v137, v141, v142
	s_nop 0
	v_cvt_pk_bf16_f32 v134, v80, v81
	v_mov_b32_e32 v40, v102
	v_mov_b32_e32 v41, v103
	s_waitcnt lgkmcnt(8)
	v_mfma_f32_16x16x32_bf16 v[68:71], v[244:247], v[134:137], v[68:71]
	s_nop 0
	s_waitcnt lgkmcnt(7)
	v_mov_b32_e32 v74, v248
	v_mov_b32_e32 v75, v249
	v_mov_b32_e32 v138, v250
	v_mov_b32_e32 v139, v251
	v_mfma_f32_16x16x32_bf16 v[72:75], v[72:75], v[134:137], v[76:79]
	s_nop 2
	s_nop 0
	s_waitcnt lgkmcnt(6)
	v_mfma_f32_16x16x32_bf16 v[76:79], v[174:177], v[134:137], v[126:129]
	s_nop 2
	s_nop 0
	s_waitcnt lgkmcnt(5)
	v_mov_b32_e32 v132, v178
	v_mov_b32_e32 v133, v179
	v_mov_b32_e32 v126, v180
	v_mov_b32_e32 v127, v181
	v_mfma_f32_16x16x32_bf16 v[64:67], v[130:133], v[134:137], v[64:67]
	s_nop 0
	v_cvt_pk_bf16_f32 v130, v62, v63
	v_cvt_pk_bf16_f32 v131, v59, v143
	v_cvt_pk_bf16_f32 v132, v61, v144
	v_cvt_pk_bf16_f32 v133, v145, v146
	s_nop 0
	s_waitcnt lgkmcnt(4)
	v_mfma_f32_16x16x32_bf16 v[68:71], v[182:185], v[130:133], v[68:71]
	s_nop 0
	s_waitcnt lgkmcnt(2)
	v_mov_b32_e32 v140, v190
	v_mov_b32_e32 v141, v191
	v_mfma_f32_16x16x32_bf16 v[58:61], v[186:189], v[54:57], v[68:71]
	s_nop 0
	v_mfma_f32_16x16x32_bf16 v[72:75], v[138:141], v[130:133], v[72:75]
	s_nop 0
	s_waitcnt lgkmcnt(1)
	v_mfma_f32_16x16x32_bf16 v[76:79], v[196:199], v[130:133], v[76:79]
	s_nop 0
	s_waitcnt lgkmcnt(0)
	v_mov_b32_e32 v128, v200
	v_mov_b32_e32 v129, v201
	s_nop 1
	v_mfma_f32_16x16x32_bf16 v[62:65], v[126:129], v[130:133], v[64:67]
	v_mov_b32_e32 v126, v192
	s_nop 1
	ds_read2_b64 v[66:69], v148 offset0:124 offset1:128
	ds_read2_b64 v[204:207], v44 offset0:216 offset1:220
	ds_read2_b64 v[208:211], v45 offset0:60 offset1:64
	v_mov_b32_e32 v127, v193
	s_waitcnt lgkmcnt(2)
	v_mov_b32_e32 v128, v66
	v_mov_b32_e32 v129, v67
	s_nop 1
	v_mfma_f32_16x16x32_bf16 v[70:73], v[126:129], v[54:57], v[72:75]
	s_nop 0
	v_mov_b32_e32 v44, v100
	s_waitcnt lgkmcnt(1)
	v_mfma_f32_16x16x32_bf16 v[74:77], v[204:207], v[54:57], v[76:79]
	s_nop 2
	s_nop 0
	v_mov_b32_e32 v126, v202
	v_mov_b32_e32 v127, v203
	v_mov_b32_e32 v45, v101
	s_waitcnt lgkmcnt(0)
	v_mov_b32_e32 v128, v208
	v_mov_b32_e32 v129, v209
	s_nop 1
	v_mfma_f32_16x16x32_bf16 v[52:55], v[126:129], v[54:57], v[62:65]
	s_nop 2
	v_cvt_pk_bf16_f32 v62, v22, v23
	v_mov_b32_e32 v22, v68
	v_mov_b32_e32 v23, v69
	v_cvt_pk_bf16_f32 v63, v26, v27
	v_cvt_pk_bf16_f32 v64, v48, v49
	v_cvt_pk_bf16_f32 v65, v50, v51
	v_mov_b32_e32 v26, v210
	v_mov_b32_e32 v27, v211
	v_mfma_f32_16x16x32_bf16 v[48:51], v[22:25], v[62:65], v[70:73]
	v_div_scale_f32 v22, s[20:21], v47, v47, 1.0
	v_rcp_f32_e32 v23, v22
	v_mfma_f32_16x16x32_bf16 v[52:55], v[26:29], v[62:65], v[52:55]
	s_waitcnt vmcnt(0)
	v_mov_b64_e32 v[72:73], v[32:33]
	v_mov_b64_e32 v[70:71], v[30:31]
	v_fma_f32 v26, -v22, v23, 1.0
	v_fmac_f32_e32 v23, v26, v23
	v_div_scale_f32 v26, vcc, 1.0, v47, 1.0
	v_mul_f32_e32 v27, v26, v23
	v_fma_f32 v56, -v22, v27, v26
	v_mfma_f32_16x16x32_bf16 v[42:45], v[42:45], v[62:65], v[58:61]
	v_fmac_f32_e32 v27, v56, v23
	v_fma_f32 v22, -v22, v27, v26
	v_div_fmas_f32 v22, v22, v23, v27
	v_mfma_f32_16x16x32_bf16 v[38:41], v[38:41], v[62:65], v[74:77]
	v_div_fixup_f32 v22, v22, v47, 1.0
	s_nop 2
	v_pk_mul_f32 v[42:43], v[22:23], v[42:43] op_sel_hi:[0,1]
	v_pk_mul_f32 v[44:45], v[22:23], v[44:45] op_sel_hi:[0,1]
	v_mad_i64_i32 v[26:27], s[20:21], v46, s34, v[82:83]
	v_cvt_pk_bf16_f32 v42, v42, v43
	v_pk_mul_f32 v[38:39], v[22:23], v[38:39] op_sel_hi:[0,1]
	v_pk_mul_f32 v[40:41], v[22:23], v[40:41] op_sel_hi:[0,1]
	v_cvt_pk_bf16_f32 v43, v44, v45
	v_cvt_pk_bf16_f32 v38, v38, v39
	v_cvt_pk_bf16_f32 v39, v40, v41
	global_store_dwordx2 v[26:27], v[42:43], off
	v_pk_mul_f32 v[42:43], v[22:23], v[48:49] op_sel_hi:[0,1]
	v_pk_mul_f32 v[44:45], v[22:23], v[50:51] op_sel_hi:[0,1]
	global_store_dwordx2 v[26:27], v[38:39], off offset:64
	v_pk_mul_f32 v[38:39], v[22:23], v[52:53] op_sel_hi:[0,1]
	v_pk_mul_f32 v[22:23], v[22:23], v[54:55] op_sel_hi:[0,1]
	v_cvt_pk_bf16_f32 v38, v38, v39
	v_cvt_pk_bf16_f32 v39, v22, v23
	global_store_dwordx2 v[26:27], v[38:39], off offset:96
	v_mov_b64_e32 v[40:41], v[36:37]
	v_cvt_pk_bf16_f32 v42, v42, v43
	v_cvt_pk_bf16_f32 v43, v44, v45
	v_mov_b64_e32 v[38:39], v[34:35]
	global_store_dwordx2 v[26:27], v[42:43], off offset:32
	s_cbranch_scc0 .LBB0_429

; __device__ __forceinline__ f32x4 mfma32(bf16x8 a, bf16x8 b, f32x4 c) { return __builtin_amdgcn_mfma_f32_16x16x32_bf16(a, b, c, 0, 0, 0); }
; __device__ __forceinline__ void attn_unit(const Ptrs& P, int l, int b, int gk, int n, unsigned char* lds, int tid, bool dost) {
;     ...
;         for (int kt = 0; kt < 9; ++kt) { const unsigned char* kp = lds + AT_KS + (16 * (qs + kt) + lc) * 144 + 16 * g;
;             const bf16x8 a0 = *(const bf16x8*)kp, a1 = *(const bf16x8*)(kp + 64);
;             f32x4 z = {0.f, 0.f, 0.f, 0.f}; z = mfma32(a0, q0, z); st[kt] = mfma32(a1, q1, z); }
;         { const unsigned char* kp = lds + AT_KM + lc * 144 + 16 * g; const bf16x8 a0 = *(const bf16x8*)kp, a1 = *(const bf16x8*)(kp + 64);
;             f32x4 z = {0.f, 0.f, 0.f, 0.f}; z = mfma32(a0, q0, z); st[9] = mfma32(a1, q1, z); }
;         float mx = sink;
; #pragma unroll
;         for (int kt = 0; kt < 9; ++kt)
; #pragma unroll
;             for (int r = 0; r < 4; ++r) { const int dist = 128 + lc - 16 * kt - 4 * g - r; const int j = 16 * (qs + kt) + 4 * g + r;
;                 const bool valid = (dist >= 0) && (dist < 128) && (n >= 1) && (n >= 2 || j >= 128);
;                 const float lg = valid ? (st[kt][r] * 0.125f + hb[w * 128 + (dist & 127)]) : NEGV; st[kt][r] = lg; mx = fmaxf(mx, lg); }
; #pragma unroll
;         for (int r = 0; r < 4; ++r) { const int dist = tq - (4 * g + r); const bool valid = dist >= 0; const int bk = (dist >= 0 && dist < 128) ? bkt[dist & 127] : 31;
;             const float lg = valid ? (st[9][r] * 0.125f + rb[bk * 16 + head]) : NEGV; st[9][r] = lg; mx = fmaxf(mx, lg); }
.LBB0_323:
	v_add_u32_e32 v22, 0, v118
	ds_read_b128 v[226:229], v22
	ds_read_b128 v[230:233], v22 offset:64
	ds_read_b128 v[244:247], v22 offset:2304
	ds_read_b128 v[248:251], v22 offset:2368
	s_nop 0
	s_nop 0
	s_nop 0
	ds_read_b128 v[166:169], v22 offset:4608
	ds_read_b128 v[170:173], v22 offset:4672
	ds_read_b128 v[174:177], v22 offset:6912
	ds_read_b128 v[178:181], v22 offset:6976
	ds_read_b128 v[182:185], v22 offset:9216
	ds_read_b128 v[186:189], v22 offset:9280
	ds_read_b128 v[190:193], v22 offset:11520
	ds_read_b128 v[196:199], v22 offset:11584
	ds_read_b128 v[200:203], v22 offset:13824
	s_nop 0
	ds_read_b128 v[204:207], v22 offset:13888
	s_waitcnt lgkmcnt(13)
	v_mfma_f32_16x16x32_bf16 v[42:45], v[226:229], v[38:41], 0
	s_waitcnt lgkmcnt(12)
	v_mfma_f32_16x16x32_bf16 v[78:81], v[230:233], v[70:73], v[42:45]
	s_nop 5
	s_nop 0
	ds_read_b128 v[208:211], v22 offset:16128
	s_nop 0
	ds_read_b128 v[214:217], v22 offset:16192
	s_waitcnt lgkmcnt(13)
	v_mfma_f32_16x16x32_bf16 v[42:45], v[244:247], v[38:41], 0
	s_waitcnt lgkmcnt(12)
	v_mfma_f32_16x16x32_bf16 v[74:77], v[248:251], v[70:73], v[42:45]
	s_nop 5
	s_nop 0
	ds_read_b128 v[218:221], v22 offset:18432
	s_nop 0
	ds_read_b128 v[222:225], v22 offset:18496
	s_waitcnt lgkmcnt(13)
	v_mfma_f32_16x16x32_bf16 v[42:45], v[166:169], v[38:41], 0
	s_waitcnt lgkmcnt(12)
	v_mfma_f32_16x16x32_bf16 v[66:69], v[170:173], v[70:73], v[42:45]
	s_nop 5
	s_nop 0
	s_nop 0
	s_waitcnt lgkmcnt(11)
	v_mfma_f32_16x16x32_bf16 v[42:45], v[174:177], v[38:41], 0
	s_waitcnt lgkmcnt(10)
	v_mfma_f32_16x16x32_bf16 v[62:65], v[178:181], v[70:73], v[42:45]
	s_nop 5
	s_nop 0
	s_nop 0
	s_waitcnt lgkmcnt(9)
	v_mfma_f32_16x16x32_bf16 v[42:45], v[182:185], v[38:41], 0
	s_waitcnt lgkmcnt(8)
	v_mfma_f32_16x16x32_bf16 v[58:61], v[186:189], v[70:73], v[42:45]
	s_nop 5
	s_nop 0
	s_nop 0
	s_waitcnt lgkmcnt(7)
	v_mfma_f32_16x16x32_bf16 v[42:45], v[190:193], v[38:41], 0
	s_waitcnt lgkmcnt(6)
	v_mfma_f32_16x16x32_bf16 v[54:57], v[196:199], v[70:73], v[42:45]
	s_nop 5
	s_nop 0
	s_nop 0
	s_waitcnt lgkmcnt(5)
	v_mfma_f32_16x16x32_bf16 v[42:45], v[200:203], v[38:41], 0
	s_waitcnt lgkmcnt(4)
	v_mfma_f32_16x16x32_bf16 v[50:53], v[204:207], v[70:73], v[42:45]
	s_nop 5
	s_nop 0
	s_nop 0
	s_waitcnt lgkmcnt(3)
	v_mfma_f32_16x16x32_bf16 v[42:45], v[208:211], v[38:41], 0
	s_waitcnt lgkmcnt(2)
	v_mfma_f32_16x16x32_bf16 v[46:49], v[214:217], v[70:73], v[42:45]
	s_nop 5
	s_nop 0
	s_nop 0
	s_waitcnt lgkmcnt(1)
	v_mfma_f32_16x16x32_bf16 v[42:45], v[218:221], v[38:41], 0
	v_mfma_f32_16x16x32_bf16 v[38:41], v[10:13], v[38:41], 0
	s_waitcnt lgkmcnt(0)
	v_mfma_f32_16x16x32_bf16 v[42:45], v[222:225], v[70:73], v[42:45]
	v_mfma_f32_16x16x32_bf16 v[38:41], v[18:21], v[70:73], v[38:41]
	ds_read_b32 v128, v111 offset:512
	ds_read_b32 v129, v112 offset:512
	ds_read_b32 v130, v113 offset:512
	ds_read_b32 v131, v114 offset:512
	ds_read_b32 v132, v111 offset:436
	ds_read_b32 v133, v111 offset:384
	ds_read_b32 v134, v111 offset:380
	ds_read_b32 v135, v111 offset:376
	ds_read_b32 v136, v111 offset:372
	ds_read_b32 v137, v111 offset:320
	ds_read_b32 v138, v111 offset:316
	ds_read_b32 v139, v111 offset:312
	ds_read_b32 v140, v111 offset:308
	ds_read_b32 v141, v111 offset:256
	ds_read_b32 v142, v111 offset:252
	ds_read_b32 v143, v111 offset:248
	ds_read_b32 v144, v111 offset:244
	ds_read_b32 v145, v111 offset:192
	ds_read_b32 v146, v111 offset:188
	ds_read_b32 v147, v111 offset:184
	ds_read_b32 v148, v111 offset:180
	ds_read_b32 v149, v111 offset:128
	ds_read_b32 v150, v111 offset:124
	ds_read_b32 v151, v111 offset:120
	ds_read_b32 v152, v111 offset:116
	ds_read_b32 v153, v111 offset:64
	ds_read_b32 v154, v111 offset:60
	ds_read_b32 v155, v111 offset:56
	ds_read_b32 v156, v111 offset:52
	ds_read_b32 v157, v111
	ds_read_b32 v158, v115 offset:512
	ds_read_b32 v159, v116 offset:512
	ds_read_b32 v160, v117 offset:512
	ds_read_b32 v161, v111 offset:448
	ds_read_b32 v162, v111 offset:444
	ds_read_b32 v163, v111 offset:440
	s_waitcnt lgkmcnt(0)
	v_mov_b32_e32 v70, 0xf149f2ca
	v_mov_b32_e32 v73, 0xf149f2ca
	s_and_saveexec_b64 s[12:13], s[8:9]
	s_cbranch_execz .LBB0_325
	v_fmamk_f32 v73, v78, 0x3e000000, v128

; __device__ __forceinline__ unsigned pk2(float lo, float hi) { f32x2_t v = {lo, hi}; bf16x2_t b = __builtin_convertvector(v, bf16x2_t); return __builtin_bit_cast(unsigned, b); }
; __device__ __forceinline__ void unpack8(const u32x4 w, float* f) { f[0] = bflo(w.x); f[1] = bfhi(w.x); f[2] = bflo(w.y); f[3] = bfhi(w.y); f[4] = bflo(w.z); f[5] = bfhi(w.z); f[6] = bflo(w.w); f[7] = bfhi(w.w); }
; __device__ __forceinline__ void ssd_passA(const Ptrs& P, int l, int b, int ch, int gg, unsigned char* lds, int tid) {
;     ...
;     { const int h2 = tid >> 7, s = tid & 127; WSg[h2 * 128 + s] = __expf(ACS[h2 * 128 + 127] - ACS[h2 * 128 + s]) * DTS[h2 * 128 + s]; }
;     __syncthreads();
;     bf16x8 af[4][4];
; #pragma unroll
;     for (int pt = 0; pt < 4; ++pt)
; #pragma unroll
;         for (int ks = 0; ks < 4; ++ks) { const u32x4 raw = *(const u32x4*)(Xt + sdz(hh * 64 + 16 * pt + lc, 32 * ks + 8 * g)); float f[8]; unpack8(raw, f);
;             const float* wp = WSg + hh * 128 + 32 * ks + 8 * g;
;             u32x4 o; o.x = pk2(f[0] * wp[0], f[1] * wp[1]); o.y = pk2(f[2] * wp[2], f[3] * wp[3]); o.z = pk2(f[4] * wp[4], f[5] * wp[5]); o.w = pk2(f[6] * wp[6], f[7] * wp[7]);
;             af[pt][ks] = __builtin_bit_cast(bf16x8, o); }
.LBB0_499:
	s_or_b64 exec, exec, s[4:5]
	v_lshlrev_b32_e32 v12, 2, v98
	v_or_b32_e32 v13, 0x1fc, v12
	v_add_u32_e32 v13, 0, v13
	v_add_u32_e32 v13, 0x22000, v13
	s_waitcnt lgkmcnt(0)
	s_barrier
	ds_read_b32 v110, v13
	ds_read_b32 v111, v11
	ds_read_b32 v112, v10
	s_nop 0
	s_nop 0
	v_readlane_b32 s3, v255, 26
	v_bfe_u32 v99, v98, 4, 2
	v_bfe_u32 v78, v98, 6, 2
	s_waitcnt lgkmcnt(1)
	v_sub_f32_e32 v11, v110, v111
	v_mul_f32_e32 v11, 0x3fb8aa3b, v11
	v_exp_f32_e32 v11, v11
	v_and_b32_e32 v83, 15, v98
	v_lshlrev_b32_e32 v17, 3, v99
	v_lshl_or_b32 v26, v78, 6, v83
	s_waitcnt lgkmcnt(0)
	v_mul_f32_e32 v10, v112, v11
	v_add_u32_e32 v11, s3, v12
	ds_write_b32 v11, v10
	v_lshlrev_b32_e32 v10, 9, v78
	v_lshlrev_b32_e32 v11, 5, v99
	v_add3_u32 v79, s3, v10, v11
	s_movk_i32 s3, 0x48
	v_or_b32_e32 v80, 32, v17
	v_mad_u32_u24 v27, v26, s26, 0
	v_bitop3_b32 v10, v26, v17, s3 bitop3:0x6c
	v_bitop3_b32 v18, v26, v80, s3 bitop3:0x6c
	v_lshl_add_u32 v10, v10, 1, v27
	v_lshl_add_u32 v18, v18, 1, v27
	v_or_b32_e32 v81, 64, v17
	s_waitcnt lgkmcnt(0)
	s_barrier
	ds_read_b128 v[114:117], v10
	ds_read_b128 v[118:121], v18
	s_nop 0
	v_bitop3_b32 v18, v26, v81, s3 bitop3:0x6c
	v_lshl_add_u32 v18, v18, 1, v27
	ds_read_b128 v[122:125], v18
	v_or_b32_e32 v82, 0x60, v17
	s_nop 0
	v_bitop3_b32 v18, v26, v82, s3 bitop3:0x6c
	v_or_b32_e32 v22, 16, v26
	s_movk_i32 s3, 0x58
	v_add_u32_e32 v23, 0x1100, v27
	v_bitop3_b32 v24, v22, v80, s3 bitop3:0x6c
	v_lshl_add_u32 v18, v18, 1, v27
	ds_read_b128 v[126:129], v18
	v_lshl_add_u32 v24, v24, 1, v23
	ds_read_b128 v[130:133], v24
	s_nop 0
	s_nop 0
	v_bitop3_b32 v18, v22, v17, s3 bitop3:0x6c
	v_bitop3_b32 v24, v22, v81, s3 bitop3:0x6c
	v_bitop3_b32 v22, v22, v82, s3 bitop3:0x6c
	v_lshl_add_u32 v18, v18, 1, v23
	ds_read_b128 v[134:137], v18
	v_lshl_add_u32 v22, v22, 1, v23
	ds_read_b128 v[138:141], v22
	v_or_b32_e32 v28, 32, v26
	s_movk_i32 s3, 0x68
	v_or_b32_e32 v74, 48, v26
	s_nop 0
	s_nop 0
	v_add_u32_e32 v29, 0x2200, v27
	v_bitop3_b32 v22, v28, v17, s3 bitop3:0x6c
	v_bitop3_b32 v38, v28, v80, s3 bitop3:0x6c
	v_bitop3_b32 v42, v28, v81, s3 bitop3:0x6c
	v_bitop3_b32 v28, v28, v82, s3 bitop3:0x6c
	v_add_u32_e32 v75, 0x3300, v27
	v_bitop3_b32 v26, v74, v17, s16 bitop3:0x6c
	v_lshl_add_u32 v24, v24, 1, v23
	ds_read_b128 v[142:145], v24
	v_lshl_add_u32 v22, v22, 1, v29
	v_lshl_add_u32 v38, v38, 1, v29
	ds_read_b128 v[146:149], v38
	ds_read_b128 v[150:153], v22
	v_lshl_add_u32 v42, v42, 1, v29
	v_lshl_add_u32 v28, v28, 1, v29
	ds_read_b128 v[154:157], v28
	ds_read_b128 v[158:161], v42
	v_lshl_add_u32 v26, v26, 1, v75
	ds_read_b128 v[162:165], v26
	ds_read_b128 v[166:169], v79
	ds_read_b128 v[170:173], v79 offset:16
	s_nop 0
	s_nop 0
	s_nop 0
	s_nop 0
	s_nop 0
	s_nop 0
	s_nop 0
	s_nop 0
	s_waitcnt lgkmcnt(14)
	v_lshlrev_b32_e32 v76, 16, v114
	v_and_b32_e32 v77, 0xffff0000, v114
	s_waitcnt lgkmcnt(11)
	v_lshlrev_b32_e32 v104, 16, v126
	s_waitcnt lgkmcnt(1)
	v_pk_mul_f32 v[76:77], v[166:167], v[76:77]
	v_and_b32_e32 v105, 0xffff0000, v126
	v_cvt_pk_bf16_f32 v10, v76, v77
	v_lshlrev_b32_e32 v76, 16, v134
	v_and_b32_e32 v77, 0xffff0000, v134
	v_pk_mul_f32 v[76:77], v[166:167], v[76:77]
	s_mul_i32 s3, s13, 0x81
	v_cvt_pk_bf16_f32 v18, v76, v77
	v_lshlrev_b32_e32 v76, 16, v150
	v_and_b32_e32 v77, 0xffff0000, v150
	v_pk_mul_f32 v[76:77], v[166:167], v[76:77]
	s_add_i32 s3, s3, s12
	v_cvt_pk_bf16_f32 v22, v76, v77
	v_lshlrev_b32_e32 v76, 16, v162
	v_and_b32_e32 v77, 0xffff0000, v162
	v_pk_mul_f32 v[42:43], v[166:167], v[76:77]
	v_lshlrev_b32_e32 v76, 16, v118
	v_cvt_pk_bf16_f32 v26, v42, v43
	v_lshlrev_b32_e32 v42, 16, v115
	v_and_b32_e32 v43, 0xffff0000, v115
	v_pk_mul_f32 v[42:43], v[168:169], v[42:43]
	v_and_b32_e32 v77, 0xffff0000, v118
	v_cvt_pk_bf16_f32 v11, v42, v43
	v_lshlrev_b32_e32 v42, 16, v135
	v_and_b32_e32 v43, 0xffff0000, v135
	v_pk_mul_f32 v[42:43], v[168:169], v[42:43]
	v_or_b32_e32 v78, s10, v78
	v_cvt_pk_bf16_f32 v19, v42, v43
	v_lshlrev_b32_e32 v42, 16, v151
	v_and_b32_e32 v43, 0xffff0000, v151
	v_pk_mul_f32 v[42:43], v[168:169], v[42:43]
	s_lshl_b32 s3, s3, 4
	v_cvt_pk_bf16_f32 v23, v42, v43
	v_lshlrev_b32_e32 v42, 16, v163
	v_and_b32_e32 v43, 0xffff0000, v163
	v_pk_mul_f32 v[42:43], v[168:169], v[42:43]
	v_or_b32_e32 v78, s3, v78
	v_cvt_pk_bf16_f32 v27, v42, v43
	v_lshlrev_b32_e32 v42, 16, v116
	v_and_b32_e32 v43, 0xffff0000, v116
	s_waitcnt lgkmcnt(0)
	v_pk_mul_f32 v[42:43], v[170:171], v[42:43]
	s_movk_i32 s4, 0x4400
	v_cvt_pk_bf16_f32 v12, v42, v43
	v_lshlrev_b32_e32 v42, 16, v136
	v_and_b32_e32 v43, 0xffff0000, v136
	v_pk_mul_f32 v[42:43], v[170:171], v[42:43]
	v_lshlrev_b32_e32 v78, 14, v78
	v_cvt_pk_bf16_f32 v20, v42, v43
	v_lshlrev_b32_e32 v42, 16, v152
	v_and_b32_e32 v43, 0xffff0000, v152
	v_pk_mul_f32 v[42:43], v[170:171], v[42:43]
	v_lshlrev_b32_e32 v99, 9, v99
	v_cvt_pk_bf16_f32 v24, v42, v43
	v_lshlrev_b32_e32 v42, 16, v164
	v_and_b32_e32 v43, 0xffff0000, v164
	v_pk_mul_f32 v[42:43], v[170:171], v[42:43]
	s_nop 0
	v_cvt_pk_bf16_f32 v28, v42, v43
	v_lshlrev_b32_e32 v42, 16, v117
	v_and_b32_e32 v43, 0xffff0000, v117
	v_pk_mul_f32 v[42:43], v[172:173], v[42:43]
	s_nop 0
	v_cvt_pk_bf16_f32 v13, v42, v43
	v_lshlrev_b32_e32 v42, 16, v137
	v_and_b32_e32 v43, 0xffff0000, v137
	v_pk_mul_f32 v[42:43], v[172:173], v[42:43]
	s_nop 0
	v_cvt_pk_bf16_f32 v21, v42, v43
	v_lshlrev_b32_e32 v42, 16, v153
	v_and_b32_e32 v43, 0xffff0000, v153
	v_pk_mul_f32 v[42:43], v[172:173], v[42:43]
	s_nop 0
	v_cvt_pk_bf16_f32 v25, v42, v43
	v_lshlrev_b32_e32 v42, 16, v165
	v_and_b32_e32 v43, 0xffff0000, v165
	v_pk_mul_f32 v[42:43], v[172:173], v[42:43]
	s_nop 0
	v_cvt_pk_bf16_f32 v29, v42, v43
	v_bitop3_b32 v42, v74, v80, s16 bitop3:0x6c
	v_lshl_add_u32 v42, v42, 1, v75
	ds_read_b128 v[174:177], v42
	ds_read_b128 v[178:181], v79 offset:128
	ds_read_b128 v[182:185], v79 offset:144
	s_nop 0
	s_waitcnt lgkmcnt(1)
; __device__ __forceinline__ unsigned pk2(float lo, float hi) { f32x2_t v = {lo, hi}; bf16x2_t b = __builtin_convertvector(v, bf16x2_t); return __builtin_bit_cast(unsigned, b); }
; __device__ __forceinline__ void unpack8(const u32x4 w, float* f) { f[0] = bflo(w.x); f[1] = bfhi(w.x); f[2] = bflo(w.y); f[3] = bfhi(w.y); f[4] = bflo(w.z); f[5] = bfhi(w.z); f[6] = bflo(w.w); f[7] = bfhi(w.w); }
; __device__ __forceinline__ void ssd_passA(const Ptrs& P, int l, int b, int ch, int gg, unsigned char* lds, int tid) {
;     ...
;         for (int ks = 0; ks < 4; ++ks) { const u32x4 raw = *(const u32x4*)(Xt + sdz(hh * 64 + 16 * pt + lc, 32 * ks + 8 * g)); float f[8]; unpack8(raw, f);
;             const float* wp = WSg + hh * 128 + 32 * ks + 8 * g;
;             u32x4 o; o.x = pk2(f[0] * wp[0], f[1] * wp[1]); o.y = pk2(f[2] * wp[2], f[3] * wp[3]); o.z = pk2(f[4] * wp[4], f[5] * wp[5]); o.w = pk2(f[6] * wp[6], f[7] * wp[7]);
;             af[pt][ks] = __builtin_bit_cast(bf16x8, o); }
	v_pk_mul_f32 v[76:77], v[178:179], v[76:77]
	s_nop 0
	v_cvt_pk_bf16_f32 v30, v76, v77
	v_lshlrev_b32_e32 v76, 16, v130
	v_and_b32_e32 v77, 0xffff0000, v130
	v_pk_mul_f32 v[76:77], v[178:179], v[76:77]
	s_nop 0
	v_cvt_pk_bf16_f32 v34, v76, v77
	v_lshlrev_b32_e32 v76, 16, v146
	v_and_b32_e32 v77, 0xffff0000, v146
	v_pk_mul_f32 v[76:77], v[178:179], v[76:77]
	s_nop 0
	v_cvt_pk_bf16_f32 v38, v76, v77
	v_lshlrev_b32_e32 v76, 16, v174
	v_and_b32_e32 v77, 0xffff0000, v174
	v_pk_mul_f32 v[58:59], v[178:179], v[76:77]
	v_lshlrev_b32_e32 v76, 16, v120
	v_cvt_pk_bf16_f32 v42, v58, v59
	v_lshlrev_b32_e32 v58, 16, v119
	v_and_b32_e32 v59, 0xffff0000, v119
	v_pk_mul_f32 v[58:59], v[180:181], v[58:59]
	v_and_b32_e32 v77, 0xffff0000, v120
	v_cvt_pk_bf16_f32 v31, v58, v59
	v_lshlrev_b32_e32 v58, 16, v131
	v_and_b32_e32 v59, 0xffff0000, v131
	v_pk_mul_f32 v[58:59], v[180:181], v[58:59]
	s_nop 0
	v_cvt_pk_bf16_f32 v35, v58, v59
	v_lshlrev_b32_e32 v58, 16, v147
	v_and_b32_e32 v59, 0xffff0000, v147
	v_pk_mul_f32 v[58:59], v[180:181], v[58:59]
	s_nop 0
	v_cvt_pk_bf16_f32 v39, v58, v59
	v_lshlrev_b32_e32 v58, 16, v175
	v_and_b32_e32 v59, 0xffff0000, v175
	v_pk_mul_f32 v[58:59], v[180:181], v[58:59]
	s_nop 0
	v_cvt_pk_bf16_f32 v43, v58, v59
	s_nop 0
	s_waitcnt lgkmcnt(0)
	v_pk_mul_f32 v[76:77], v[182:183], v[76:77]
	s_nop 0
	v_cvt_pk_bf16_f32 v32, v76, v77
	v_lshlrev_b32_e32 v76, 16, v132
	v_and_b32_e32 v77, 0xffff0000, v132
	v_pk_mul_f32 v[76:77], v[182:183], v[76:77]
	s_nop 0
	v_cvt_pk_bf16_f32 v36, v76, v77
	v_lshlrev_b32_e32 v76, 16, v148
	v_and_b32_e32 v77, 0xffff0000, v148
	v_pk_mul_f32 v[76:77], v[182:183], v[76:77]
	s_nop 0
	v_cvt_pk_bf16_f32 v40, v76, v77
	v_lshlrev_b32_e32 v76, 16, v176
	v_and_b32_e32 v77, 0xffff0000, v176
	v_pk_mul_f32 v[58:59], v[182:183], v[76:77]
	v_lshlrev_b32_e32 v76, 16, v122
	v_cvt_pk_bf16_f32 v44, v58, v59
	v_lshlrev_b32_e32 v58, 16, v121
	v_and_b32_e32 v59, 0xffff0000, v121
	v_pk_mul_f32 v[58:59], v[184:185], v[58:59]
	v_and_b32_e32 v77, 0xffff0000, v122
	v_cvt_pk_bf16_f32 v33, v58, v59
	v_lshlrev_b32_e32 v58, 16, v133
	v_and_b32_e32 v59, 0xffff0000, v133
	v_pk_mul_f32 v[58:59], v[184:185], v[58:59]
	s_nop 0
	v_cvt_pk_bf16_f32 v37, v58, v59
	v_lshlrev_b32_e32 v58, 16, v149
	v_and_b32_e32 v59, 0xffff0000, v149
	v_pk_mul_f32 v[58:59], v[184:185], v[58:59]
	s_nop 0
	v_cvt_pk_bf16_f32 v41, v58, v59
	v_lshlrev_b32_e32 v58, 16, v177
	v_and_b32_e32 v59, 0xffff0000, v177
	v_pk_mul_f32 v[58:59], v[184:185], v[58:59]
	s_nop 0
	v_cvt_pk_bf16_f32 v45, v58, v59
	v_bitop3_b32 v58, v74, v81, s16 bitop3:0x6c
	v_lshl_add_u32 v58, v58, 1, v75
	ds_read_b128 v[186:189], v58
	ds_read_b128 v[190:193], v79 offset:256
	ds_read_b128 v[196:199], v79 offset:272
	s_nop 0
	v_bitop3_b32 v74, v74, v82, s16 bitop3:0x6c
	v_lshl_add_u32 v74, v74, 1, v75
	ds_read_b128 v[200:203], v74
	ds_read_b128 v[204:207], v79 offset:384
	ds_read_b128 v[208:211], v79 offset:400
	s_waitcnt lgkmcnt(4)
	v_pk_mul_f32 v[76:77], v[190:191], v[76:77]
	s_nop 0
	v_cvt_pk_bf16_f32 v46, v76, v77
	v_lshlrev_b32_e32 v76, 16, v142
	v_and_b32_e32 v77, 0xffff0000, v142
	v_pk_mul_f32 v[76:77], v[190:191], v[76:77]
	s_nop 0
	v_cvt_pk_bf16_f32 v50, v76, v77
	v_lshlrev_b32_e32 v76, 16, v158
	v_and_b32_e32 v77, 0xffff0000, v158
	v_pk_mul_f32 v[76:77], v[190:191], v[76:77]
	s_nop 0
	v_cvt_pk_bf16_f32 v54, v76, v77
	v_lshlrev_b32_e32 v76, 16, v186
	v_and_b32_e32 v77, 0xffff0000, v186
	v_pk_mul_f32 v[76:77], v[190:191], v[76:77]
	s_nop 0
	v_cvt_pk_bf16_f32 v58, v76, v77
	v_lshlrev_b32_e32 v76, 16, v123
	v_and_b32_e32 v77, 0xffff0000, v123
	v_pk_mul_f32 v[76:77], v[192:193], v[76:77]
	s_nop 0
	v_cvt_pk_bf16_f32 v47, v76, v77
	v_lshlrev_b32_e32 v76, 16, v143
	v_and_b32_e32 v77, 0xffff0000, v143
	v_pk_mul_f32 v[76:77], v[192:193], v[76:77]
	s_nop 0
	v_cvt_pk_bf16_f32 v51, v76, v77
	v_lshlrev_b32_e32 v76, 16, v159
	v_and_b32_e32 v77, 0xffff0000, v159
	v_pk_mul_f32 v[76:77], v[192:193], v[76:77]
	s_nop 0
	v_cvt_pk_bf16_f32 v55, v76, v77
	v_lshlrev_b32_e32 v76, 16, v187
	v_and_b32_e32 v77, 0xffff0000, v187
	v_pk_mul_f32 v[76:77], v[192:193], v[76:77]
	s_nop 0
	v_cvt_pk_bf16_f32 v59, v76, v77
	v_lshlrev_b32_e32 v76, 16, v124
	v_and_b32_e32 v77, 0xffff0000, v124
	s_waitcnt lgkmcnt(3)
	v_pk_mul_f32 v[76:77], v[196:197], v[76:77]
	s_nop 0
	v_cvt_pk_bf16_f32 v48, v76, v77
	v_lshlrev_b32_e32 v76, 16, v144
	v_and_b32_e32 v77, 0xffff0000, v144
	v_pk_mul_f32 v[76:77], v[196:197], v[76:77]
	s_nop 0
	v_cvt_pk_bf16_f32 v52, v76, v77
	v_lshlrev_b32_e32 v76, 16, v160
	v_and_b32_e32 v77, 0xffff0000, v160
	v_pk_mul_f32 v[76:77], v[196:197], v[76:77]
	s_nop 0
	v_cvt_pk_bf16_f32 v56, v76, v77
	v_lshlrev_b32_e32 v76, 16, v188
	v_and_b32_e32 v77, 0xffff0000, v188
	v_pk_mul_f32 v[76:77], v[196:197], v[76:77]
	s_nop 0
	v_cvt_pk_bf16_f32 v60, v76, v77
	v_lshlrev_b32_e32 v76, 16, v125
	v_and_b32_e32 v77, 0xffff0000, v125
	v_pk_mul_f32 v[76:77], v[198:199], v[76:77]
	s_nop 0
	v_cvt_pk_bf16_f32 v49, v76, v77
	v_lshlrev_b32_e32 v76, 16, v145
	v_and_b32_e32 v77, 0xffff0000, v145
	v_pk_mul_f32 v[76:77], v[198:199], v[76:77]
	s_nop 0
	v_cvt_pk_bf16_f32 v53, v76, v77
	v_lshlrev_b32_e32 v76, 16, v161
	v_and_b32_e32 v77, 0xffff0000, v161
	v_pk_mul_f32 v[76:77], v[198:199], v[76:77]
	s_nop 0
	v_cvt_pk_bf16_f32 v57, v76, v77
	v_lshlrev_b32_e32 v76, 16, v189
	v_and_b32_e32 v77, 0xffff0000, v189
	v_pk_mul_f32 v[76:77], v[198:199], v[76:77]
	s_nop 0
	v_cvt_pk_bf16_f32 v61, v76, v77
	s_nop 0
	s_nop 0
	s_waitcnt lgkmcnt(1)
; __device__ __forceinline__ unsigned pk2(float lo, float hi) { f32x2_t v = {lo, hi}; bf16x2_t b = __builtin_convertvector(v, bf16x2_t); return __builtin_bit_cast(unsigned, b); }
; __device__ __forceinline__ void unpack8(const u32x4 w, float* f) { f[0] = bflo(w.x); f[1] = bfhi(w.x); f[2] = bflo(w.y); f[3] = bfhi(w.y); f[4] = bflo(w.z); f[5] = bfhi(w.z); f[6] = bflo(w.w); f[7] = bfhi(w.w); }
; __device__ __forceinline__ void ssd_passA(const Ptrs& P, int l, int b, int ch, int gg, unsigned char* lds, int tid) {
;     ...
;         for (int ks = 0; ks < 4; ++ks) { const u32x4 raw = *(const u32x4*)(Xt + sdz(hh * 64 + 16 * pt + lc, 32 * ks + 8 * g)); float f[8]; unpack8(raw, f);
;             const float* wp = WSg + hh * 128 + 32 * ks + 8 * g;
;             u32x4 o; o.x = pk2(f[0] * wp[0], f[1] * wp[1]); o.y = pk2(f[2] * wp[2], f[3] * wp[3]); o.z = pk2(f[4] * wp[4], f[5] * wp[5]); o.w = pk2(f[6] * wp[6], f[7] * wp[7]);
;             af[pt][ks] = __builtin_bit_cast(bf16x8, o); }
;     bf16_t* ST = (bf16_t*)(P.ws + WS_X) + (size_t)((b * NCH + ch) * 16 + h) * 8192;
; #pragma unroll 1
;     for (int nt = 4 * half; nt < 4 * half + 4; ++nt) {
	v_pk_mul_f32 v[104:105], v[204:205], v[104:105]
	s_nop 0
	v_cvt_pk_bf16_f32 v62, v104, v105
	v_lshlrev_b32_e32 v104, 16, v138
	v_and_b32_e32 v105, 0xffff0000, v138
	v_pk_mul_f32 v[104:105], v[204:205], v[104:105]
	s_nop 0
	v_cvt_pk_bf16_f32 v66, v104, v105
	v_lshlrev_b32_e32 v104, 16, v154
	v_and_b32_e32 v105, 0xffff0000, v154
	v_pk_mul_f32 v[104:105], v[204:205], v[104:105]
	s_nop 0
	v_cvt_pk_bf16_f32 v70, v104, v105
	v_lshlrev_b32_e32 v104, 16, v200
	v_and_b32_e32 v105, 0xffff0000, v200
	v_pk_mul_f32 v[100:101], v[204:205], v[104:105]
	v_lshlrev_b32_e32 v104, 16, v128
	v_cvt_pk_bf16_f32 v74, v100, v101
	v_lshlrev_b32_e32 v100, 16, v127
	v_and_b32_e32 v101, 0xffff0000, v127
	v_pk_mul_f32 v[100:101], v[206:207], v[100:101]
	v_and_b32_e32 v105, 0xffff0000, v128
	v_cvt_pk_bf16_f32 v63, v100, v101
	v_lshlrev_b32_e32 v100, 16, v139
	v_and_b32_e32 v101, 0xffff0000, v139
	v_pk_mul_f32 v[100:101], v[206:207], v[100:101]
	s_nop 0
	v_cvt_pk_bf16_f32 v67, v100, v101
	v_lshlrev_b32_e32 v100, 16, v155
	v_and_b32_e32 v101, 0xffff0000, v155
	v_pk_mul_f32 v[100:101], v[206:207], v[100:101]
	s_nop 0
	v_cvt_pk_bf16_f32 v71, v100, v101
	v_lshlrev_b32_e32 v100, 16, v201
	v_and_b32_e32 v101, 0xffff0000, v201
	v_pk_mul_f32 v[100:101], v[206:207], v[100:101]
	s_nop 0
	v_cvt_pk_bf16_f32 v75, v100, v101
	s_nop 0
	v_mov_b32_e32 v79, v16
	v_lshl_add_u64 v[78:79], v[14:15], 0, v[78:79]
	s_waitcnt lgkmcnt(0)
	v_pk_mul_f32 v[104:105], v[208:209], v[104:105]
	s_nop 0
	v_cvt_pk_bf16_f32 v64, v104, v105
	v_lshlrev_b32_e32 v104, 16, v140
	v_and_b32_e32 v105, 0xffff0000, v140
	v_pk_mul_f32 v[104:105], v[208:209], v[104:105]
	s_nop 0
	v_cvt_pk_bf16_f32 v68, v104, v105
	v_lshlrev_b32_e32 v104, 16, v156
	v_and_b32_e32 v105, 0xffff0000, v156
	v_pk_mul_f32 v[104:105], v[208:209], v[104:105]
	s_nop 0
	v_cvt_pk_bf16_f32 v72, v104, v105
	v_lshlrev_b32_e32 v104, 16, v202
	v_and_b32_e32 v105, 0xffff0000, v202
	v_pk_mul_f32 v[100:101], v[208:209], v[104:105]
	s_nop 0
	v_cvt_pk_bf16_f32 v76, v100, v101
	v_lshlrev_b32_e32 v100, 16, v129
	v_and_b32_e32 v101, 0xffff0000, v129
	v_pk_mul_f32 v[100:101], v[210:211], v[100:101]
	s_nop 0
	v_cvt_pk_bf16_f32 v65, v100, v101
	v_lshlrev_b32_e32 v100, 16, v141
	v_and_b32_e32 v101, 0xffff0000, v141
	v_pk_mul_f32 v[100:101], v[210:211], v[100:101]
	s_nop 0
	v_cvt_pk_bf16_f32 v69, v100, v101
	v_lshlrev_b32_e32 v100, 16, v157
	v_and_b32_e32 v101, 0xffff0000, v157
	v_pk_mul_f32 v[100:101], v[210:211], v[100:101]
	s_nop 0
	v_cvt_pk_bf16_f32 v73, v100, v101
	v_lshlrev_b32_e32 v100, 16, v203
	v_and_b32_e32 v101, 0xffff0000, v203
	v_pk_mul_f32 v[100:101], v[210:211], v[100:101]
	v_lshrrev_b32_e32 v103, 2, v107
	v_cvt_pk_bf16_f32 v77, v100, v101
	v_and_b32_e32 v101, -4, v107
	v_lshl_or_b32 v102, v103, 6, v83
	v_mul_lo_u32 v103, v103, s4
	v_mul_u32_u24_e32 v83, 0x110, v83
	v_readlane_b32 s4, v255, 25
	v_or_b32_e32 v100, 3, v107
	v_add_u32_e32 v101, -1, v101
	v_add3_u32 v83, v103, v83, s4
	s_mov_b64 s[4:5], 0
; __device__ __forceinline__ unsigned f2bf(float f) { return pk2(f, 0.f) & 0xffffu; }
; __device__ __forceinline__ f32x4 mfma32(bf16x8 a, bf16x8 b, f32x4 c) { return __builtin_amdgcn_mfma_f32_16x16x32_bf16(a, b, c, 0, 0, 0); }
; __device__ __forceinline__ void ssd_passA(const Ptrs& P, int l, int b, int ch, int gg, unsigned char* lds, int tid) {
;     ...
;     for (int nt = 4 * half; nt < 4 * half + 4; ++nt) {
;         f32x4 st[4];
; #pragma unroll
;         for (int pt = 0; pt < 4; ++pt) st[pt] = (f32x4){0.f, 0.f, 0.f, 0.f};
; #pragma unroll
;         for (int ks = 0; ks < 4; ++ks) { const bf16x8 bfr = *(const bf16x8*)(Bt + sdz(16 * nt + lc, 32 * ks + 8 * g));
; #pragma unroll
;             for (int pt = 0; pt < 4; ++pt) st[pt] = mfma32(af[pt][ks], bfr, st[pt]); }
; #pragma unroll
;         for (int pt = 0; pt < 4; ++pt)
; #pragma unroll
;             for (int r = 0; r < 4; ++r) ST[(16 * pt + 4 * g + r) * 128 + 16 * nt + lc] = (bf16_t)f2bf(st[pt][r]);
;     }
;     if (tid < 4) { float* dec = (float*)((unsigned char*)P.out + DO_SSDDEC); dec[(b * NCH + ch) * 16 + gg * 4 + tid] = __expf(ACS[tid * 128 + 127]); }
.LBB0_500:
	v_bitop3_b32 v103, v102, v17, s16 bitop3:0x6c
	v_lshl_add_u32 v103, v103, 1, v83
	ds_read_b128 v[130:133], v103
	v_bitop3_b32 v103, v102, v80, s16 bitop3:0x6c
	v_lshl_add_u32 v103, v103, 1, v83
	ds_read_b128 v[134:137], v103
	v_bitop3_b32 v103, v102, v81, s16 bitop3:0x6c
	s_waitcnt lgkmcnt(1)
	v_mfma_f32_16x16x32_bf16 v[114:117], v[10:13], v[130:133], 0
	v_lshl_add_u32 v103, v103, 1, v83
	ds_read_b128 v[138:141], v103
	v_add_u32_e32 v104, v99, v102
	v_ashrrev_i32_e32 v105, 31, v104
	v_mfma_f32_16x16x32_bf16 v[118:121], v[18:21], v[130:133], 0
	v_add_u32_e32 v101, 1, v101
	v_cmp_ge_i32_e32 vcc, v101, v100
	s_or_b64 s[4:5], vcc, s[4:5]
	v_mfma_f32_16x16x32_bf16 v[122:125], v[22:25], v[130:133], 0
	v_mfma_f32_16x16x32_bf16 v[110:113], v[26:29], v[130:133], 0
	s_waitcnt lgkmcnt(1)
	v_mfma_f32_16x16x32_bf16 v[114:117], v[30:33], v[134:137], v[114:117]
	v_mfma_f32_16x16x32_bf16 v[118:121], v[34:37], v[134:137], v[118:121]
	v_mfma_f32_16x16x32_bf16 v[122:125], v[38:41], v[134:137], v[122:125]
	v_mfma_f32_16x16x32_bf16 v[110:113], v[42:45], v[134:137], v[110:113]
	s_nop 0
	v_bitop3_b32 v103, v102, v82, s16 bitop3:0x6c
	v_lshl_add_u32 v103, v103, 1, v83
	ds_read_b128 v[142:145], v103
	s_waitcnt lgkmcnt(1)
	v_mfma_f32_16x16x32_bf16 v[114:117], v[46:49], v[138:141], v[114:117]
	v_add_u32_e32 v102, 16, v102
	v_add_u32_e32 v83, 0x1100, v83
	v_mfma_f32_16x16x32_bf16 v[118:121], v[50:53], v[138:141], v[118:121]
	v_mfma_f32_16x16x32_bf16 v[122:125], v[54:57], v[138:141], v[122:125]
	v_mfma_f32_16x16x32_bf16 v[110:113], v[58:61], v[138:141], v[110:113]
	s_nop 0
	s_waitcnt lgkmcnt(0)
	v_mfma_f32_16x16x32_bf16 v[114:117], v[62:65], v[142:145], v[114:117]
	v_mfma_f32_16x16x32_bf16 v[118:121], v[66:69], v[142:145], v[118:121]
	s_nop 6
	v_cvt_pk_bf16_f32 v103, v114, s0
	v_add_u32_e32 v114, 0x80, v104
	v_mfma_f32_16x16x32_bf16 v[122:125], v[70:73], v[142:145], v[122:125]
	v_mfma_f32_16x16x32_bf16 v[110:113], v[74:77], v[142:145], v[110:113]
	v_lshl_add_u64 v[126:127], v[104:105], 1, v[78:79]
	global_store_short v[126:127], v103, off
	v_cvt_pk_bf16_f32 v103, v115, s0
	v_ashrrev_i32_e32 v115, 31, v114
	v_lshl_add_u64 v[114:115], v[114:115], 1, v[78:79]
	global_store_short v[114:115], v103, off
	v_add_u32_e32 v114, 0x100, v104
	v_ashrrev_i32_e32 v115, 31, v114
	v_cvt_pk_bf16_f32 v103, v116, s0
	v_lshl_add_u64 v[114:115], v[114:115], 1, v[78:79]
	global_store_short v[114:115], v103, off
	v_add_u32_e32 v114, 0x180, v104
	v_ashrrev_i32_e32 v115, 31, v114
	v_cvt_pk_bf16_f32 v103, v117, s0
	v_lshl_add_u64 v[114:115], v[114:115], 1, v[78:79]
	global_store_short v[114:115], v103, off
	v_add_u32_e32 v114, 0x800, v104
	v_ashrrev_i32_e32 v115, 31, v114
	v_cvt_pk_bf16_f32 v103, v118, s0
	v_lshl_add_u64 v[114:115], v[114:115], 1, v[78:79]
	global_store_short v[114:115], v103, off
	v_add_u32_e32 v114, 0x880, v104
	v_ashrrev_i32_e32 v115, 31, v114
	v_cvt_pk_bf16_f32 v103, v119, s0
	v_lshl_add_u64 v[114:115], v[114:115], 1, v[78:79]
	global_store_short v[114:115], v103, off
	v_add_u32_e32 v114, 0x900, v104
	v_ashrrev_i32_e32 v115, 31, v114
	v_cvt_pk_bf16_f32 v103, v120, s0
	v_lshl_add_u64 v[114:115], v[114:115], 1, v[78:79]
	global_store_short v[114:115], v103, off
	v_add_u32_e32 v114, 0x980, v104
	v_ashrrev_i32_e32 v115, 31, v114
	v_cvt_pk_bf16_f32 v103, v121, s0
	v_lshl_add_u64 v[114:115], v[114:115], 1, v[78:79]
	global_store_short v[114:115], v103, off
	v_add_u32_e32 v114, 0x1000, v104
	v_ashrrev_i32_e32 v115, 31, v114
	v_cvt_pk_bf16_f32 v103, v122, s0
	v_lshl_add_u64 v[114:115], v[114:115], 1, v[78:79]
	global_store_short v[114:115], v103, off
	v_add_u32_e32 v114, 0x1080, v104
	v_ashrrev_i32_e32 v115, 31, v114
	v_cvt_pk_bf16_f32 v103, v123, s0
	v_lshl_add_u64 v[114:115], v[114:115], 1, v[78:79]
	global_store_short v[114:115], v103, off
	v_add_u32_e32 v114, 0x1100, v104
	v_ashrrev_i32_e32 v115, 31, v114
	v_cvt_pk_bf16_f32 v103, v124, s0
	v_lshl_add_u64 v[114:115], v[114:115], 1, v[78:79]
	global_store_short v[114:115], v103, off
	v_add_u32_e32 v114, 0x1180, v104
	v_ashrrev_i32_e32 v115, 31, v114
	v_cvt_pk_bf16_f32 v103, v125, s0
	v_lshl_add_u64 v[114:115], v[114:115], 1, v[78:79]
	global_store_short v[114:115], v103, off
	v_add_u32_e32 v114, 0x1800, v104
	v_ashrrev_i32_e32 v115, 31, v114
	v_cvt_pk_bf16_f32 v103, v110, s0
	v_lshl_add_u64 v[114:115], v[114:115], 1, v[78:79]
	v_add_u32_e32 v110, 0x1880, v104
	global_store_short v[114:115], v103, off
	v_cvt_pk_bf16_f32 v103, v111, s0
	v_ashrrev_i32_e32 v111, 31, v110
	v_lshl_add_u64 v[110:111], v[110:111], 1, v[78:79]
	global_store_short v[110:111], v103, off
	v_add_u32_e32 v110, 0x1900, v104
	v_ashrrev_i32_e32 v111, 31, v110
	v_add_u32_e32 v104, 0x1980, v104
	v_cvt_pk_bf16_f32 v103, v112, s0
	v_lshl_add_u64 v[110:111], v[110:111], 1, v[78:79]
	v_ashrrev_i32_e32 v105, 31, v104
	global_store_short v[110:111], v103, off
	v_cvt_pk_bf16_f32 v103, v113, s0
	v_lshl_add_u64 v[104:105], v[104:105], 1, v[78:79]
	global_store_short v[104:105], v103, off
	s_andn2_b64 exec, exec, s[4:5]
	s_cbranch_execnz .LBB0_500
	s_or_b64 exec, exec, s[4:5]
	v_cmp_gt_i32_e32 vcc, 4, v98
	s_and_saveexec_b64 s[4:5], vcc
	s_cbranch_execz .LBB0_503
	s_or_b32 s3, s3, s10
	v_add_u32_e32 v10, s3, v98
	s_add_i32 s3, 0, 0x22000
	v_lshl_add_u32 v12, v98, 9, s3
	ds_read_b32 v146, v12 offset:508
	v_ashrrev_i32_e32 v11, 31, v10
	v_lshl_add_u64 v[10:11], v[10:11], 2, v[92:93]
	s_waitcnt lgkmcnt(0)
	v_mul_f32_e32 v12, 0x3fb8aa3b, v146
	v_exp_f32_e32 v12, v12
	global_store_dword v[10:11], v12, off

; __device__ __forceinline__ f32x4 mfma32(bf16x8 a, bf16x8 b, f32x4 c) { return __builtin_amdgcn_mfma_f32_16x16x32_bf16(a, b, c, 0, 0, 0); }
; __device__ __forceinline__ bf16x4 pack4(f32x4 v) { u32x2 w; w.x = pk2(v[0], v[1]); w.y = pk2(v[2], v[3]); return __builtin_bit_cast(bf16x4, w); }
; __device__ __forceinline__ void hg_unit(const Ptrs& P, int l, int b, int hd, int ch, unsigned char* lds, int tid) {
;     ...
;     if (w < nsub) {
;         f32x4 at = {0.f, 0.f, 0.f, 0.f};
; #pragma unroll
;         for (int ks = 0; ks < 4; ++ks) { const bf16x8 a = *(const bf16x8*)(Kb + (16 * w + lc) * 136 + 32 * ks + 8 * g), bq = *(const bf16x8*)(Qb + (16 * w + lc) * 136 + 32 * ks + 8 * g); at = mfma32(a, bq, at); }
; #pragma unroll
;         for (int r = 0; r < 4; ++r) at[r] = (4 * g + r <= lc) ? at[r] : 0.f;
;         *(bf16x4*)HG_ATT_SLOT(w) = pack4(at);
.LBB0_595:
	v_lshrrev_b32_e32 v13, 4, v108
	v_and_b32_e32 v10, 4, v17
	v_and_b32_e32 v48, 15, v98
	v_cmp_gt_i32_e32 vcc, s6, v107
	v_lshlrev_b32_e32 v50, 2, v13
	v_lshlrev_b32_e32 v12, 1, v10
	s_waitcnt lgkmcnt(0)
	s_barrier
	s_and_saveexec_b64 s[4:5], vcc
	s_cbranch_execz .LBB0_597
	v_or_b32_e32 v10, v46, v48
	v_mul_lo_u32 v10, v10, s26
	v_lshlrev_b32_e32 v11, 4, v13
	v_add3_u32 v10, 0, v10, v11
	ds_read_b128 v[34:37], v10 offset:34816
	ds_read_b128 v[38:41], v10
	ds_read_b128 v[42:45], v10 offset:34880
	ds_read_b128 v[56:59], v10 offset:64
	ds_read_b128 v[60:63], v10 offset:34944
	ds_read_b128 v[64:67], v10 offset:128
	ds_read_b128 v[76:79], v10 offset:35008
	ds_read_b128 v[80:83], v10 offset:192
	s_nop 0
	v_cmp_le_u32_e32 vcc, v50, v48
	v_readlane_b32 s7, v255, 27
	s_waitcnt lgkmcnt(6)
	v_mfma_f32_16x16x32_bf16 v[18:21], v[34:37], v[38:41], 0
	s_nop 0
	s_nop 0
	s_waitcnt lgkmcnt(4)
	v_mfma_f32_16x16x32_bf16 v[18:21], v[42:45], v[56:59], v[18:21]
	s_nop 0
	s_nop 0
	s_waitcnt lgkmcnt(2)
	v_mfma_f32_16x16x32_bf16 v[18:21], v[60:63], v[64:67], v[18:21]
	s_nop 0
	s_nop 0
	s_waitcnt lgkmcnt(0)
	v_mfma_f32_16x16x32_bf16 v[18:21], v[76:79], v[80:83], v[18:21]
	s_nop 7
	v_cndmask_b32_e32 v10, 0, v18, vcc
	v_cmp_lt_u32_e32 vcc, v50, v48
	v_or_b32_e32 v18, 2, v50
	s_nop 0
	v_cndmask_b32_e32 v11, 0, v19, vcc
	v_cmp_le_u32_e32 vcc, v18, v48
	v_or_b32_e32 v19, 3, v50
	v_cvt_pk_bf16_f32 v10, v10, v11
	v_cndmask_b32_e32 v18, 0, v20, vcc
	v_cmp_le_u32_e32 vcc, v19, v48
	s_nop 1
	v_cndmask_b32_e32 v19, 0, v21, vcc
	v_cvt_pk_bf16_f32 v11, v18, v19
	v_lshrrev_b32_e32 v19, 1, v98
	v_cmp_gt_u32_e32 vcc, 32, v108
	v_mov_b32_e32 v18, s7
	v_and_or_b32 v19, v19, 15, v46
	v_cndmask_b32_e64 v18, v18, 0, vcc
	v_mul_lo_u32 v19, v19, s26
	v_add3_u32 v18, v18, v19, v12
	ds_write_b64 v18, v[10:11] offset:256

; __device__ __forceinline__ unsigned pk2(float lo, float hi) { f32x2_t v = {lo, hi}; bf16x2_t b = __builtin_convertvector(v, bf16x2_t); return __builtin_bit_cast(unsigned, b); }
; __device__ __forceinline__ void unpack8(const u32x4 w, float* f) { f[0] = bflo(w.x); f[1] = bfhi(w.x); f[2] = bflo(w.y); f[3] = bfhi(w.y); f[4] = bflo(w.z); f[5] = bfhi(w.z); f[6] = bflo(w.w); f[7] = bfhi(w.w); }
; __device__ __forceinline__ void hg_unit(const Ptrs& P, int l, int b, int hd, int ch, unsigned char* lds, int tid) {
;     ...
;         const int t = tid >> 2, sgm = tid & 3;
;         if (t < 16 * nsub) { const int j = t >> 4; bf16_t* qo = PJ + (row0 + t) * PW + C_HQ + hd * 128 + 32 * sgm;
; #pragma unroll
;             for (int c8 = 0; c8 < 4; ++c8) { const u32x4 qw = *(const u32x4*)(Qb + t * 136 + 32 * sgm + 8 * c8); float f[8]; unpack8(qw, f);
;                 const f32x4 d0 = *(const f32x4*)(DT + j * 128 + 32 * sgm + 8 * c8), d1 = *(const f32x4*)(DT + j * 128 + 32 * sgm + 8 * c8 + 4);
;                 u32x4 o; o.x = pk2(f[0] * d0[0], f[1] * d0[1]); o.y = pk2(f[2] * d0[2], f[3] * d0[3]); o.z = pk2(f[4] * d1[0], f[5] * d1[1]); o.w = pk2(f[6] * d1[2], f[7] * d1[3]);
;                 *(u32x4*)(qo + 8 * c8) = o; } }
.LBB0_601:
	s_or_b64 exec, exec, s[4:5]
	v_ashrrev_i32_e32 v10, 2, v98
	s_lshl_b32 s3, s6, 4
	v_cmp_gt_i32_e32 vcc, s3, v10
	s_waitcnt lgkmcnt(0)
	s_barrier
	s_and_saveexec_b64 s[4:5], vcc
	s_cbranch_execz .LBB0_603
	v_ashrrev_i32_e32 v11, 31, v10
	v_lshl_add_u64 v[18:19], s[44:45], 0, v[10:11]
	v_mad_u64_u32 v[20:21], s[6:7], v18, s34, v[86:87]
	v_lshlrev_b32_e32 v11, 3, v98
	v_mad_i32_i24 v21, v19, s34, v21
	v_and_b32_e32 v11, 0x18, v11
	v_lshl_add_u64 v[18:19], v[20:21], 0, s[96:97]
	v_lshlrev_b32_e32 v20, 1, v11
	v_mul_lo_u32 v10, v10, s26
	v_lshlrev_b32_e32 v17, 3, v98
	v_mov_b32_e32 v21, v16
	v_add3_u32 v10, 0, v10, v20
	ds_read_b128 v[62:65], v10
	ds_read_b128 v[66:69], v10 offset:64
	ds_read_b128 v[76:79], v10 offset:128
	ds_read_b128 v[80:83], v10 offset:192
	v_and_b32_e32 v17, 0xfffffe00, v17
	v_lshlrev_b32_e32 v11, 2, v11
	v_readlane_b32 s3, v255, 28
	v_lshl_add_u64 v[30:31], v[18:19], 0, v[20:21]
	s_mov_b64 s[6:7], 0x2a00
	v_add3_u32 v17, s3, v17, v11
	ds_read_b128 v[100:103], v17
	ds_read_b128 v[112:115], v17 offset:16
	s_nop 0
	s_nop 0
	s_nop 0
	s_nop 0
	s_nop 0
	s_nop 0
	ds_read_b128 v[52:55], v17 offset:128
	ds_read_b128 v[116:119], v17 offset:144
	ds_read_b128 v[120:123], v17 offset:256
	ds_read_b128 v[128:131], v17 offset:272
	ds_read_b128 v[132:135], v17 offset:384
	ds_read_b128 v[136:139], v17 offset:400
	s_waitcnt lgkmcnt(11)
	v_lshlrev_b32_e32 v10, 16, v62
	v_and_b32_e32 v11, 0xffff0000, v62
	s_waitcnt lgkmcnt(7)
	v_pk_mul_f32 v[10:11], v[100:101], v[10:11]
	s_movk_i32 s3, 0x2000
	v_cvt_pk_bf16_f32 v18, v10, v11
	v_lshlrev_b32_e32 v10, 16, v63
	v_and_b32_e32 v11, 0xffff0000, v63
	v_pk_mul_f32 v[10:11], v[102:103], v[10:11]
	v_lshl_add_u64 v[60:61], v[30:31], 0, s[6:7]
	v_cvt_pk_bf16_f32 v19, v10, v11
	v_lshlrev_b32_e32 v10, 16, v64
	v_and_b32_e32 v11, 0xffff0000, v64
	s_waitcnt lgkmcnt(6)
	v_pk_mul_f32 v[10:11], v[112:113], v[10:11]
	s_nop 0
	v_cvt_pk_bf16_f32 v20, v10, v11
	v_lshlrev_b32_e32 v10, 16, v65
	v_and_b32_e32 v11, 0xffff0000, v65
	v_pk_mul_f32 v[10:11], v[114:115], v[10:11]
	s_nop 0
	v_cvt_pk_bf16_f32 v21, v10, v11
	v_add_co_u32_e32 v10, vcc, s3, v30
	s_nop 1
	v_addc_co_u32_e32 v11, vcc, 0, v31, vcc
	global_store_dwordx4 v[10:11], v[18:21], off offset:2560
	v_lshlrev_b32_e32 v10, 16, v66
	v_and_b32_e32 v11, 0xffff0000, v66
	s_waitcnt lgkmcnt(5)
	v_pk_mul_f32 v[10:11], v[52:53], v[10:11]
	s_nop 0
	v_cvt_pk_bf16_f32 v18, v10, v11
	v_lshlrev_b32_e32 v10, 16, v67
	v_and_b32_e32 v11, 0xffff0000, v67
	v_pk_mul_f32 v[10:11], v[54:55], v[10:11]
	s_nop 0
	v_cvt_pk_bf16_f32 v19, v10, v11
	v_lshlrev_b32_e32 v10, 16, v68
	v_and_b32_e32 v11, 0xffff0000, v68
	s_waitcnt lgkmcnt(4)
	v_pk_mul_f32 v[10:11], v[116:117], v[10:11]
	s_nop 0
	v_cvt_pk_bf16_f32 v20, v10, v11
	v_lshlrev_b32_e32 v10, 16, v69
	v_and_b32_e32 v11, 0xffff0000, v69
	s_nop 0
	v_pk_mul_f32 v[10:11], v[118:119], v[10:11]
	s_nop 0
	v_cvt_pk_bf16_f32 v21, v10, v11
	global_store_dwordx4 v[60:61], v[18:21], off offset:64
	s_nop 0
	v_lshlrev_b32_e32 v10, 16, v76
	v_and_b32_e32 v11, 0xffff0000, v76
	s_waitcnt lgkmcnt(3)
	v_pk_mul_f32 v[10:11], v[120:121], v[10:11]
	s_nop 0
	v_cvt_pk_bf16_f32 v22, v10, v11
	v_lshlrev_b32_e32 v10, 16, v77
	v_and_b32_e32 v11, 0xffff0000, v77
	v_pk_mul_f32 v[10:11], v[122:123], v[10:11]
	s_nop 0
	v_cvt_pk_bf16_f32 v23, v10, v11
	v_lshlrev_b32_e32 v10, 16, v78
	v_and_b32_e32 v11, 0xffff0000, v78
	s_waitcnt lgkmcnt(2)
	v_pk_mul_f32 v[10:11], v[128:129], v[10:11]
	s_nop 0
	v_cvt_pk_bf16_f32 v24, v10, v11
	v_lshlrev_b32_e32 v10, 16, v79
	v_and_b32_e32 v11, 0xffff0000, v79
	v_pk_mul_f32 v[10:11], v[130:131], v[10:11]
	s_nop 0
	v_cvt_pk_bf16_f32 v25, v10, v11
	global_store_dwordx4 v[60:61], v[22:25], off offset:128
	s_nop 0
	v_lshlrev_b32_e32 v10, 16, v80
	v_and_b32_e32 v11, 0xffff0000, v80
	s_waitcnt lgkmcnt(1)
	v_pk_mul_f32 v[10:11], v[132:133], v[10:11]
	s_nop 0
	v_cvt_pk_bf16_f32 v18, v10, v11
	v_lshlrev_b32_e32 v10, 16, v81
	v_and_b32_e32 v11, 0xffff0000, v81
	v_pk_mul_f32 v[10:11], v[134:135], v[10:11]
	s_nop 0
	v_cvt_pk_bf16_f32 v19, v10, v11
	v_lshlrev_b32_e32 v10, 16, v82
	v_and_b32_e32 v11, 0xffff0000, v82
	s_waitcnt lgkmcnt(0)
	v_pk_mul_f32 v[10:11], v[136:137], v[10:11]
	s_nop 0
	v_cvt_pk_bf16_f32 v20, v10, v11
	v_lshlrev_b32_e32 v10, 16, v83
	v_and_b32_e32 v11, 0xffff0000, v83
	v_pk_mul_f32 v[10:11], v[138:139], v[10:11]
	s_nop 0
	v_cvt_pk_bf16_f32 v21, v10, v11
	global_store_dwordx4 v[60:61], v[18:21], off offset:192
; __device__ __forceinline__ unsigned pk2(float lo, float hi) { f32x2_t v = {lo, hi}; bf16x2_t b = __builtin_convertvector(v, bf16x2_t); return __builtin_bit_cast(unsigned, b); }
; __device__ __forceinline__ f32x4 mfma16(bf16x4 a, bf16x4 b, f32x4 c) { return __builtin_amdgcn_mfma_f32_16x16x16bf16_1k(a, b, c, 0, 0, 0); }
; __device__ __forceinline__ bf16x4 pack4(f32x4 v) { u32x2 w; w.x = pk2(v[0], v[1]); w.y = pk2(v[2], v[3]); return __builtin_bit_cast(bf16x4, w); }
; __device__ __forceinline__ void hg_unit(const Ptrs& P, int l, int b, int hd, int ch, unsigned char* lds, int tid) {
;     ...
;     f32x4 S[8];
; #pragma unroll
;     for (int kt = 0; kt < 8; ++kt) S[kt] = (f32x4){0.f, 0.f, 0.f, 0.f};
; #pragma unroll
;     for (int j = 0; j < 8; ++j) {
;         if (j < nsub) {
;             const bf16x4 vf = *(const bf16x4*)(Vt + (j * 16 + lc) * 20 + 4 * g);
;             const bf16x4 atj = *(const bf16x4*)HG_ATT_SLOT(j);
;             f32x4 o = mfma16(vf, atj, (f32x4){0.f, 0.f, 0.f, 0.f});
;             if (j > 0) {
; #pragma unroll
;                 for (int kt = 0; kt < 8; ++kt) { const bf16x4 qf = *(const bf16x4*)(Qb + (16 * j + lc) * 136 + 16 * kt + 4 * g); o = mfma16(pack4(S[kt]), qf, o); } }
;             { u32x2 wv; wv.x = pk2(o[0], o[1]); wv.y = pk2(o[2], o[3]); *(u32x2*)(PJ + (row0 + 16 * j + lc) * PW + C_HI + hd * 128 + 16 * w + 4 * g) = wv; }
; #pragma unroll
;             for (int kt = 0; kt < 8; ++kt) { const f32x4 eb = *(const f32x4*)(EBE + j * 128 + 16 * kt + 4 * g);
;                 const bf16x4 kf = *(const bf16x4*)(Ket + (j * 128 + 16 * kt + lc) * 20 + 4 * g);
;                 S[kt] = mfma16(kf, vf, S[kt] * eb); }
.LBB0_603:
	s_or_b64 exec, exec, s[4:5]
	s_nop 0
	v_lshlrev_b32_e32 v18, 3, v13
	v_add_u32_e32 v58, v32, v18
	v_lshl_add_u32 v13, v13, 4, 0
	v_add_u32_e32 v17, 0x1b000, v13
	v_mad_u32_u24 v13, v48, 40, v58
	ds_read_b64 v[72:73], v13
	v_readlane_b32 s3, v255, 27
	s_nop 0
	ds_read_b128 v[22:25], v17 offset:64
	v_cmp_gt_u32_e32 vcc, 32, v108
	v_mov_b32_e32 v10, s3
	v_bfe_u32 v11, v98, 1, 4
	v_cndmask_b32_e64 v10, v10, 0, vcc
	v_mul_u32_u24_e32 v11, 0x110, v11
	v_add3_u32 v61, v10, v11, v12
	ds_read_b64 v[76:77], v61 offset:256
	v_mov_b32_e32 v49, v16
	s_waitcnt lgkmcnt(0)
	v_mfma_f32_16x16x16_bf16 v[10:13], v[72:73], v[76:77], 0
	v_lshl_add_u64 v[20:21], s[44:45], 0, v[48:49]
	v_mad_u64_u32 v[52:53], s[4:5], v20, s34, v[86:87]
	v_mad_i32_i24 v53, v21, s34, v53
	s_nop 4
	v_cvt_pk_bf16_f32 v10, v10, v11
	v_cvt_pk_bf16_f32 v11, v12, v13
	v_lshl_add_u64 v[12:13], v[52:53], 0, s[96:97]
	v_lshl_add_u64 v[56:57], v[46:47], 1, v[12:13]
	v_mov_b32_e32 v19, v16
	v_lshl_add_u64 v[12:13], v[56:57], 0, v[18:19]
	s_movk_i32 s3, 0x3000
	v_mul_u32_u24_e32 v60, 40, v48
	v_add_co_u32_e32 v12, vcc, s3, v12
	v_readlane_b32 s3, v255, 25
	v_add_u32_e32 v59, 0, v18
	v_addc_co_u32_e32 v13, vcc, 0, v13, vcc
	v_add3_u32 v49, s3, v18, v60
	ds_read2_b64 v[78:81], v49 offset1:80
	global_store_dwordx2 v[12:13], v[10:11], off offset:2560
	ds_read_b128 v[10:13], v17
	v_pk_mul_f32 v[24:25], v[24:25], 0 op_sel_hi:[1,0]
	v_pk_mul_f32 v[22:23], v[22:23], 0 op_sel_hi:[1,0]
	v_add_u32_e32 v34, 0x800, v49
	v_add_u32_e32 v44, 0xc00, v49
	s_waitcnt lgkmcnt(0)
	v_pk_mul_f32 v[12:13], v[12:13], 0 op_sel_hi:[1,0]
	v_pk_mul_f32 v[10:11], v[10:11], 0 op_sel_hi:[1,0]
	s_and_b64 vcc, exec, s[38:39]
	v_lshlrev_b32_e32 v50, 1, v50
	v_mfma_f32_16x16x16_bf16 v[10:13], v[78:79], v[72:73], v[10:13]
	v_mfma_f32_16x16x16_bf16 v[18:21], v[80:81], v[72:73], v[22:25]
	s_nop 2
	ds_read_b128 v[22:25], v17 offset:128
	ds_read2_b64 v[100:103], v49 offset0:160 offset1:240
	ds_read_b128 v[30:33], v17 offset:192
	ds_read_b128 v[38:41], v17 offset:320
	ds_read2_b64 v[112:115], v34 offset0:64 offset1:144
	s_waitcnt lgkmcnt(4)
	v_pk_mul_f32 v[24:25], v[24:25], 0 op_sel_hi:[1,0]
	v_pk_mul_f32 v[22:23], v[22:23], 0 op_sel_hi:[1,0]
	s_waitcnt lgkmcnt(2)
	v_pk_mul_f32 v[32:33], v[32:33], 0 op_sel_hi:[1,0]
	v_pk_mul_f32 v[30:31], v[30:31], 0 op_sel_hi:[1,0]
	v_mfma_f32_16x16x16_bf16 v[22:25], v[100:101], v[72:73], v[22:25]
	ds_read2_b64 v[62:65], v44 offset0:96 offset1:176
	s_waitcnt lgkmcnt(2)
	v_pk_mul_f32 v[40:41], v[40:41], 0 op_sel_hi:[1,0]
	v_pk_mul_f32 v[38:39], v[38:39], 0 op_sel_hi:[1,0]
	v_mfma_f32_16x16x16_bf16 v[26:29], v[102:103], v[72:73], v[30:33]
	ds_read_b128 v[66:69], v17 offset:448
	s_waitcnt lgkmcnt(0)
	v_pk_mul_f32 v[68:69], v[68:69], 0 op_sel_hi:[1,0]
	ds_read_b128 v[30:33], v17 offset:256
	v_pk_mul_f32 v[66:67], v[66:67], 0 op_sel_hi:[1,0]
	s_waitcnt lgkmcnt(0)
	v_pk_mul_f32 v[32:33], v[32:33], 0 op_sel_hi:[1,0]
	v_pk_mul_f32 v[30:31], v[30:31], 0 op_sel_hi:[1,0]
	s_nop 1
	v_mfma_f32_16x16x16_bf16 v[30:33], v[112:113], v[72:73], v[30:33]
	v_mfma_f32_16x16x16_bf16 v[34:37], v[114:115], v[72:73], v[38:41]
	s_nop 2
	ds_read_b128 v[38:41], v17 offset:384
	s_waitcnt lgkmcnt(0)
	v_pk_mul_f32 v[40:41], v[40:41], 0 op_sel_hi:[1,0]
	v_pk_mul_f32 v[38:39], v[38:39], 0 op_sel_hi:[1,0]
	s_nop 1
	v_mfma_f32_16x16x16_bf16 v[38:41], v[62:63], v[72:73], v[38:41]
	v_mfma_f32_16x16x16_bf16 v[42:45], v[64:65], v[72:73], v[66:69]
	s_cbranch_vccz .LBB0_613
	s_and_b64 vcc, exec, s[38:39]
	s_cbranch_vccz .LBB0_614

; __device__ __forceinline__ unsigned pk2(float lo, float hi) { f32x2_t v = {lo, hi}; bf16x2_t b = __builtin_convertvector(v, bf16x2_t); return __builtin_bit_cast(unsigned, b); }
; __device__ __forceinline__ f32x4 mfma16(bf16x4 a, bf16x4 b, f32x4 c) { return __builtin_amdgcn_mfma_f32_16x16x16bf16_1k(a, b, c, 0, 0, 0); }
; __device__ __forceinline__ bf16x4 pack4(f32x4 v) { u32x2 w; w.x = pk2(v[0], v[1]); w.y = pk2(v[2], v[3]); return __builtin_bit_cast(bf16x4, w); }
; __device__ __forceinline__ void hg_unit(const Ptrs& P, int l, int b, int hd, int ch, unsigned char* lds, int tid) {
;     ...
;     for (int j = 0; j < 8; ++j) {
;         if (j < nsub) {
;             const bf16x4 vf = *(const bf16x4*)(Vt + (j * 16 + lc) * 20 + 4 * g);
;             const bf16x4 atj = *(const bf16x4*)HG_ATT_SLOT(j);
;             f32x4 o = mfma16(vf, atj, (f32x4){0.f, 0.f, 0.f, 0.f});
;             if (j > 0) {
; #pragma unroll
;                 for (int kt = 0; kt < 8; ++kt) { const bf16x4 qf = *(const bf16x4*)(Qb + (16 * j + lc) * 136 + 16 * kt + 4 * g); o = mfma16(pack4(S[kt]), qf, o); } }
;             { u32x2 wv; wv.x = pk2(o[0], o[1]); wv.y = pk2(o[2], o[3]); *(u32x2*)(PJ + (row0 + 16 * j + lc) * PW + C_HI + hd * 128 + 16 * w + 4 * g) = wv; }
; #pragma unroll
;             for (int kt = 0; kt < 8; ++kt) { const f32x4 eb = *(const f32x4*)(EBE + j * 128 + 16 * kt + 4 * g);
;                 const bf16x4 kf = *(const bf16x4*)(Ket + (j * 128 + 16 * kt + lc) * 20 + 4 * g);
;                 S[kt] = mfma16(kf, vf, S[kt] * eb); }
.LBB0_610:
	v_add_u32_e32 v54, v60, v58
	ds_read_b64 v[54:55], v54 offset:4480
	ds_read_b64 v[72:73], v61 offset:30720
	v_or_b32_e32 v51, 0x70, v48
	v_mad_u32_u24 v51, v51, s26, v59
	ds_read2_b64 v[76:79], v51 offset1:4
	ds_read2_b64 v[80:83], v51 offset0:8 offset1:12
	ds_read2_b64 v[98:101], v51 offset0:16 offset1:20
	ds_read2_b64 v[102:105], v51 offset0:24 offset1:28
	ds_read_b128 v[112:115], v17 offset:3584
	s_nop 0
	s_nop 0
	s_nop 0
	s_nop 0
	v_cvt_pk_bf16_f32 v64, v10, v11
	v_cvt_pk_bf16_f32 v65, v12, v13
	s_waitcnt lgkmcnt(5)
	v_mfma_f32_16x16x16_bf16 v[60:63], v[54:55], v[72:73], 0
	s_nop 0
	v_lshl_add_u64 v[52:53], v[52:53], 0, s[96:97]
	v_lshl_add_u64 v[46:47], v[46:47], 1, v[52:53]
	s_mov_b32 s3, 0x1d1000
	s_waitcnt lgkmcnt(4)
	v_mfma_f32_16x16x16_bf16 v[60:63], v[64:65], v[76:77], v[60:63]
	v_cvt_pk_bf16_f32 v56, v18, v19
	v_cvt_pk_bf16_f32 v57, v20, v21
	v_cvt_pk_bf16_f32 v64, v22, v23
	v_cvt_pk_bf16_f32 v65, v24, v25
	v_mfma_f32_16x16x16_bf16 v[56:59], v[56:57], v[78:79], v[60:63]
	s_nop 2
	s_nop 0
	s_waitcnt lgkmcnt(3)
	v_mfma_f32_16x16x16_bf16 v[56:59], v[64:65], v[80:81], v[56:59]
	v_cvt_pk_bf16_f32 v60, v26, v27
	v_cvt_pk_bf16_f32 v61, v28, v29
	v_cvt_pk_bf16_f32 v64, v30, v31
	v_cvt_pk_bf16_f32 v65, v32, v33
	v_mfma_f32_16x16x16_bf16 v[56:59], v[60:61], v[82:83], v[56:59]
	s_nop 0
	s_waitcnt lgkmcnt(2)
	v_mfma_f32_16x16x16_bf16 v[56:59], v[64:65], v[98:99], v[56:59]
	v_cvt_pk_bf16_f32 v60, v34, v35
	v_cvt_pk_bf16_f32 v61, v36, v37
	v_cvt_pk_bf16_f32 v64, v38, v39
	v_cvt_pk_bf16_f32 v65, v40, v41
	v_mfma_f32_16x16x16_bf16 v[56:59], v[60:61], v[100:101], v[56:59]
	s_nop 0
	v_mov_b32_e32 v51, v16
	v_lshl_add_u64 v[46:47], v[46:47], 0, v[50:51]
	s_waitcnt lgkmcnt(1)
	v_mfma_f32_16x16x16_bf16 v[56:59], v[64:65], v[102:103], v[56:59]
	v_cvt_pk_bf16_f32 v60, v42, v43
	v_cvt_pk_bf16_f32 v61, v44, v45
	v_add_co_u32_e32 v46, vcc, s3, v46
	s_nop 0
	v_mfma_f32_16x16x16_bf16 v[56:59], v[60:61], v[104:105], v[56:59]
	v_addc_co_u32_e32 v47, vcc, 0, v47, vcc
	s_nop 6
	v_cvt_pk_bf16_f32 v56, v56, v57
	v_cvt_pk_bf16_f32 v57, v58, v59
	global_store_dwordx2 v[46:47], v[56:57], off offset:2560
	s_nop 0
	v_add_u32_e32 v46, 0x8800, v49
	ds_read2_b64 v[116:119], v46 offset0:128 offset1:208
	ds_read_b128 v[120:123], v17 offset:3648
	ds_read_b128 v[128:131], v17 offset:3712
	s_nop 0
	s_nop 0
	v_add_u32_e32 v46, 0x9000, v49
	ds_read2_b64 v[132:135], v46 offset0:32 offset1:112
	ds_read_b128 v[136:139], v17 offset:3776
	ds_read_b128 v[140:143], v17 offset:3840
	s_nop 0
	s_nop 0
	s_waitcnt lgkmcnt(6)
	v_pk_mul_f32 v[12:13], v[12:13], v[114:115]
	v_pk_mul_f32 v[10:11], v[10:11], v[112:113]
	s_nop 0
	s_waitcnt lgkmcnt(4)
	v_pk_mul_f32 v[20:21], v[20:21], v[122:123]
	v_pk_mul_f32 v[18:19], v[18:19], v[120:121]
	s_nop 0
	v_mfma_f32_16x16x16_bf16 v[10:13], v[116:117], v[54:55], v[10:13]
	s_waitcnt lgkmcnt(3)
	v_pk_mul_f32 v[24:25], v[24:25], v[130:131]
	v_mfma_f32_16x16x16_bf16 v[18:21], v[118:119], v[54:55], v[18:21]
	s_nop 0
	v_pk_mul_f32 v[22:23], v[22:23], v[128:129]
	s_nop 0
	v_add_u32_e32 v46, 0x9400, v49
	ds_read2_b64 v[144:147], v46 offset0:64 offset1:144
	ds_read_b128 v[216:219], v17 offset:3904
	ds_read_b128 v[220:223], v17 offset:3968
	s_nop 0
	s_nop 0
	s_waitcnt lgkmcnt(5)
	v_mfma_f32_16x16x16_bf16 v[22:25], v[132:133], v[54:55], v[22:25]
	s_waitcnt lgkmcnt(4)
	v_pk_mul_f32 v[28:29], v[28:29], v[138:139]
	v_pk_mul_f32 v[26:27], v[26:27], v[136:137]
	s_nop 0
	s_waitcnt lgkmcnt(3)
	v_pk_mul_f32 v[32:33], v[32:33], v[142:143]
	v_mfma_f32_16x16x16_bf16 v[26:29], v[134:135], v[54:55], v[26:29]
	s_nop 0
	v_pk_mul_f32 v[30:31], v[30:31], v[140:141]
	s_nop 0
	v_add_u32_e32 v46, 0x9800, v49
	s_waitcnt lgkmcnt(2)
	v_mfma_f32_16x16x16_bf16 v[30:33], v[144:145], v[54:55], v[30:33]
	s_waitcnt lgkmcnt(1)
	v_pk_mul_f32 v[36:37], v[36:37], v[218:219]
	v_pk_mul_f32 v[34:35], v[34:35], v[216:217]
	s_nop 0
	s_waitcnt lgkmcnt(0)
	v_pk_mul_f32 v[40:41], v[40:41], v[222:223]
	v_mfma_f32_16x16x16_bf16 v[34:37], v[146:147], v[54:55], v[34:37]
	ds_read2_b64 v[60:63], v46 offset0:96 offset1:176
	v_pk_mul_f32 v[38:39], v[38:39], v[220:221]
	ds_read_b128 v[56:59], v17 offset:4032
	s_waitcnt lgkmcnt(0)
	v_pk_mul_f32 v[44:45], v[44:45], v[58:59]
	v_pk_mul_f32 v[42:43], v[42:43], v[56:57]
	v_mfma_f32_16x16x16_bf16 v[38:41], v[60:61], v[54:55], v[38:41]
	s_nop 0
	v_mfma_f32_16x16x16_bf16 v[42:45], v[62:63], v[54:55], v[42:45]

; __device__ __forceinline__ unsigned pk2(float lo, float hi) { f32x2_t v = {lo, hi}; bf16x2_t b = __builtin_convertvector(v, bf16x2_t); return __builtin_bit_cast(unsigned, b); }
; __device__ __forceinline__ f32x4 mfma16(bf16x4 a, bf16x4 b, f32x4 c) { return __builtin_amdgcn_mfma_f32_16x16x16bf16_1k(a, b, c, 0, 0, 0); }
; __device__ __forceinline__ bf16x4 pack4(f32x4 v) { u32x2 w; w.x = pk2(v[0], v[1]); w.y = pk2(v[2], v[3]); return __builtin_bit_cast(bf16x4, w); }
; __device__ __forceinline__ void hg_unit(const Ptrs& P, int l, int b, int hd, int ch, unsigned char* lds, int tid) {
;     ...
;     for (int j = 0; j < 8; ++j) {
;         if (j < nsub) {
;             const bf16x4 vf = *(const bf16x4*)(Vt + (j * 16 + lc) * 20 + 4 * g);
;             const bf16x4 atj = *(const bf16x4*)HG_ATT_SLOT(j);
;             f32x4 o = mfma16(vf, atj, (f32x4){0.f, 0.f, 0.f, 0.f});
;             if (j > 0) {
; #pragma unroll
;                 for (int kt = 0; kt < 8; ++kt) { const bf16x4 qf = *(const bf16x4*)(Qb + (16 * j + lc) * 136 + 16 * kt + 4 * g); o = mfma16(pack4(S[kt]), qf, o); } }
;             { u32x2 wv; wv.x = pk2(o[0], o[1]); wv.y = pk2(o[2], o[3]); *(u32x2*)(PJ + (row0 + 16 * j + lc) * PW + C_HI + hd * 128 + 16 * w + 4 * g) = wv; }
; #pragma unroll
;             for (int kt = 0; kt < 8; ++kt) { const f32x4 eb = *(const f32x4*)(EBE + j * 128 + 16 * kt + 4 * g);
;                 const bf16x4 kf = *(const bf16x4*)(Ket + (j * 128 + 16 * kt + lc) * 20 + 4 * g);
;                 S[kt] = mfma16(kf, vf, S[kt] * eb); }
;         }
;     }
.LBB0_613:
	v_or_b32_e32 v51, 16, v48
	v_mad_u32_u24 v54, v51, 40, v58
	ds_read_b64 v[54:55], v54
	ds_read_b64 v[72:73], v61 offset:4608
	v_mad_u32_u24 v51, v51, s26, v59
	ds_read2_b64 v[76:79], v51 offset1:4
	ds_read2_b64 v[80:83], v51 offset0:8 offset1:12
	ds_read2_b64 v[98:101], v51 offset0:16 offset1:20
	ds_read2_b64 v[102:105], v51 offset0:24 offset1:28
	ds_read_b128 v[112:115], v17 offset:512
	s_nop 0
	s_nop 0
	s_nop 0
	s_nop 0
	v_cvt_pk_bf16_f32 v70, v10, v11
	v_cvt_pk_bf16_f32 v71, v12, v13
	s_nop 0
	s_waitcnt lgkmcnt(5)
	v_mfma_f32_16x16x16_bf16 v[62:65], v[54:55], v[72:73], 0
	s_mov_b32 s3, 0x45000
	s_waitcnt lgkmcnt(4)
	v_mfma_f32_16x16x16_bf16 v[62:65], v[70:71], v[76:77], v[62:65]
	v_cvt_pk_bf16_f32 v66, v18, v19
	v_cvt_pk_bf16_f32 v67, v20, v21
	v_cvt_pk_bf16_f32 v70, v22, v23
	v_cvt_pk_bf16_f32 v71, v24, v25
	v_mfma_f32_16x16x16_bf16 v[62:65], v[66:67], v[78:79], v[62:65]
	s_nop 0
	s_waitcnt lgkmcnt(3)
	v_mfma_f32_16x16x16_bf16 v[62:65], v[70:71], v[80:81], v[62:65]
	v_cvt_pk_bf16_f32 v66, v26, v27
	v_cvt_pk_bf16_f32 v67, v28, v29
	v_cvt_pk_bf16_f32 v70, v30, v31
	v_cvt_pk_bf16_f32 v71, v32, v33
	v_mfma_f32_16x16x16_bf16 v[62:65], v[66:67], v[82:83], v[62:65]
	s_nop 0
	s_waitcnt lgkmcnt(2)
	v_mfma_f32_16x16x16_bf16 v[62:65], v[70:71], v[98:99], v[62:65]
	v_cvt_pk_bf16_f32 v66, v34, v35
	v_cvt_pk_bf16_f32 v67, v36, v37
	v_cvt_pk_bf16_f32 v70, v38, v39
	v_cvt_pk_bf16_f32 v71, v40, v41
	v_mfma_f32_16x16x16_bf16 v[62:65], v[66:67], v[100:101], v[62:65]
	s_nop 0
	v_mov_b32_e32 v51, v16
	v_lshl_add_u64 v[56:57], v[56:57], 0, v[50:51]
	s_waitcnt lgkmcnt(1)
	v_mfma_f32_16x16x16_bf16 v[62:65], v[70:71], v[102:103], v[62:65]
	v_cvt_pk_bf16_f32 v66, v42, v43
	v_cvt_pk_bf16_f32 v67, v44, v45
	v_add_co_u32_e32 v56, vcc, s3, v56
	s_nop 0
	v_mfma_f32_16x16x16_bf16 v[62:65], v[66:67], v[104:105], v[62:65]
	v_addc_co_u32_e32 v57, vcc, 0, v57, vcc
	v_add_u32_e32 v51, 0x1000, v49
	ds_read2_b64 v[116:119], v51 offset0:128 offset1:208
	ds_read_b128 v[120:123], v17 offset:576
	ds_read_b128 v[128:131], v17 offset:640
	s_nop 0
	s_nop 0
	s_nop 5
	v_cvt_pk_bf16_f32 v62, v62, v63
	v_cvt_pk_bf16_f32 v63, v64, v65
	global_store_dwordx2 v[56:57], v[62:63], off offset:2560
	s_nop 0
	s_nop 0
	v_add_u32_e32 v51, 0x1800, v49
	ds_read2_b64 v[132:135], v51 offset0:32 offset1:112
	ds_read_b128 v[136:139], v17 offset:704
	ds_read_b128 v[140:143], v17 offset:768
	s_nop 0
	s_nop 0
	s_waitcnt lgkmcnt(6)
	v_pk_mul_f32 v[12:13], v[12:13], v[114:115]
	v_pk_mul_f32 v[10:11], v[10:11], v[112:113]
	s_nop 0
	s_waitcnt lgkmcnt(4)
	v_pk_mul_f32 v[20:21], v[20:21], v[122:123]
	v_pk_mul_f32 v[18:19], v[18:19], v[120:121]
	s_nop 0
	v_mfma_f32_16x16x16_bf16 v[10:13], v[116:117], v[54:55], v[10:13]
	s_waitcnt lgkmcnt(3)
	v_pk_mul_f32 v[24:25], v[24:25], v[130:131]
	v_mfma_f32_16x16x16_bf16 v[18:21], v[118:119], v[54:55], v[18:21]
	s_nop 0
	v_pk_mul_f32 v[22:23], v[22:23], v[128:129]
	s_nop 0
	v_add_u32_e32 v51, 0x1c00, v49
	ds_read2_b64 v[144:147], v51 offset0:64 offset1:144
	ds_read_b128 v[216:219], v17 offset:832
	ds_read_b128 v[220:223], v17 offset:896
	s_nop 0
	s_nop 0
	s_waitcnt lgkmcnt(5)
	v_mfma_f32_16x16x16_bf16 v[22:25], v[132:133], v[54:55], v[22:25]
	s_waitcnt lgkmcnt(4)
	v_pk_mul_f32 v[28:29], v[28:29], v[138:139]
	v_pk_mul_f32 v[26:27], v[26:27], v[136:137]
	s_nop 0
	s_waitcnt lgkmcnt(3)
	v_pk_mul_f32 v[32:33], v[32:33], v[142:143]
	v_mfma_f32_16x16x16_bf16 v[26:29], v[134:135], v[54:55], v[26:29]
	s_nop 0
	v_pk_mul_f32 v[30:31], v[30:31], v[140:141]
	s_nop 0
	v_add_u32_e32 v51, 0x2000, v49
	s_waitcnt lgkmcnt(2)
	v_mfma_f32_16x16x16_bf16 v[30:33], v[144:145], v[54:55], v[30:33]
	s_waitcnt lgkmcnt(1)
	v_pk_mul_f32 v[36:37], v[36:37], v[218:219]
	v_pk_mul_f32 v[34:35], v[34:35], v[216:217]
	s_nop 0
	s_waitcnt lgkmcnt(0)
	v_pk_mul_f32 v[40:41], v[40:41], v[222:223]
	v_mfma_f32_16x16x16_bf16 v[34:37], v[146:147], v[54:55], v[34:37]
	ds_read2_b64 v[66:69], v51 offset0:96 offset1:176
	v_pk_mul_f32 v[38:39], v[38:39], v[220:221]
	ds_read_b128 v[62:65], v17 offset:960
	s_waitcnt lgkmcnt(0)
	v_pk_mul_f32 v[44:45], v[44:45], v[64:65]
	v_pk_mul_f32 v[42:43], v[42:43], v[62:63]
	v_mfma_f32_16x16x16_bf16 v[38:41], v[66:67], v[54:55], v[38:41]
	s_nop 0
	v_mfma_f32_16x16x16_bf16 v[42:45], v[68:69], v[54:55], v[42:45]
	s_and_b64 vcc, exec, s[38:39]
	s_cbranch_vccnz .LBB0_605
; __device__ __forceinline__ unsigned pk2(float lo, float hi) { f32x2_t v = {lo, hi}; bf16x2_t b = __builtin_convertvector(v, bf16x2_t); return __builtin_bit_cast(unsigned, b); }
; __device__ __forceinline__ f32x4 mfma16(bf16x4 a, bf16x4 b, f32x4 c) { return __builtin_amdgcn_mfma_f32_16x16x16bf16_1k(a, b, c, 0, 0, 0); }
; __device__ __forceinline__ bf16x4 pack4(f32x4 v) { u32x2 w; w.x = pk2(v[0], v[1]); w.y = pk2(v[2], v[3]); return __builtin_bit_cast(bf16x4, w); }
; __device__ __forceinline__ void hg_unit(const Ptrs& P, int l, int b, int hd, int ch, unsigned char* lds, int tid) {
;     ...
;     for (int j = 0; j < 8; ++j) {
;         if (j < nsub) {
;             const bf16x4 vf = *(const bf16x4*)(Vt + (j * 16 + lc) * 20 + 4 * g);
;             const bf16x4 atj = *(const bf16x4*)HG_ATT_SLOT(j);
;             f32x4 o = mfma16(vf, atj, (f32x4){0.f, 0.f, 0.f, 0.f});
;             if (j > 0) {
; #pragma unroll
;                 for (int kt = 0; kt < 8; ++kt) { const bf16x4 qf = *(const bf16x4*)(Qb + (16 * j + lc) * 136 + 16 * kt + 4 * g); o = mfma16(pack4(S[kt]), qf, o); } }
;             { u32x2 wv; wv.x = pk2(o[0], o[1]); wv.y = pk2(o[2], o[3]); *(u32x2*)(PJ + (row0 + 16 * j + lc) * PW + C_HI + hd * 128 + 16 * w + 4 * g) = wv; }
; #pragma unroll
;             for (int kt = 0; kt < 8; ++kt) { const f32x4 eb = *(const f32x4*)(EBE + j * 128 + 16 * kt + 4 * g);
;                 const bf16x4 kf = *(const bf16x4*)(Ket + (j * 128 + 16 * kt + lc) * 20 + 4 * g);
;                 S[kt] = mfma16(kf, vf, S[kt] * eb); }
;         }
;     }
.LBB0_614:
	v_or_b32_e32 v51, 32, v48
	v_mad_u32_u24 v54, v51, 40, v58
	ds_read_b64 v[54:55], v54
	ds_read_b64 v[72:73], v61 offset:8960
	v_mad_u32_u24 v51, v51, s26, v59
	ds_read2_b64 v[76:79], v51 offset1:4
	ds_read2_b64 v[80:83], v51 offset0:8 offset1:12
	ds_read2_b64 v[98:101], v51 offset0:16 offset1:20
	ds_read2_b64 v[102:105], v51 offset0:24 offset1:28
	ds_read_b128 v[112:115], v17 offset:1024
	s_nop 0
	s_nop 0
	s_nop 0
	s_nop 0
	s_mov_b32 s3, 0x87000
	s_waitcnt lgkmcnt(5)
	v_mfma_f32_16x16x16_bf16 v[62:65], v[54:55], v[72:73], 0
	v_cvt_pk_bf16_f32 v56, v10, v11
	v_cvt_pk_bf16_f32 v57, v12, v13
	s_waitcnt lgkmcnt(4)
	s_nop 0
	v_mfma_f32_16x16x16_bf16 v[62:65], v[56:57], v[76:77], v[62:65]
	v_cvt_pk_bf16_f32 v56, v18, v19
	v_cvt_pk_bf16_f32 v57, v20, v21
	s_nop 1
	v_mfma_f32_16x16x16_bf16 v[62:65], v[56:57], v[78:79], v[62:65]
	s_nop 0
	v_cvt_pk_bf16_f32 v56, v22, v23
	v_cvt_pk_bf16_f32 v57, v24, v25
	s_waitcnt lgkmcnt(3)
	s_nop 0
	v_mfma_f32_16x16x16_bf16 v[62:65], v[56:57], v[80:81], v[62:65]
	v_cvt_pk_bf16_f32 v56, v26, v27
	v_cvt_pk_bf16_f32 v57, v28, v29
	s_nop 1
	v_mfma_f32_16x16x16_bf16 v[62:65], v[56:57], v[82:83], v[62:65]
	s_nop 0
	v_cvt_pk_bf16_f32 v56, v30, v31
	v_cvt_pk_bf16_f32 v57, v32, v33
	s_waitcnt lgkmcnt(2)
	s_nop 0
	v_mfma_f32_16x16x16_bf16 v[62:65], v[56:57], v[98:99], v[62:65]
	v_cvt_pk_bf16_f32 v56, v34, v35
	v_cvt_pk_bf16_f32 v57, v36, v37
	s_nop 1
	v_mfma_f32_16x16x16_bf16 v[62:65], v[56:57], v[100:101], v[62:65]
	s_nop 0
	v_cvt_pk_bf16_f32 v56, v38, v39
	v_cvt_pk_bf16_f32 v57, v40, v41
	v_mov_b32_e32 v51, v16
	s_waitcnt lgkmcnt(1)
	v_mfma_f32_16x16x16_bf16 v[62:65], v[56:57], v[102:103], v[62:65]
	v_cvt_pk_bf16_f32 v56, v42, v43
	v_cvt_pk_bf16_f32 v57, v44, v45
	s_nop 1
	v_mfma_f32_16x16x16_bf16 v[62:65], v[56:57], v[104:105], v[62:65]
	s_nop 7
	v_cvt_pk_bf16_f32 v56, v62, v63
	v_lshl_add_u64 v[62:63], v[52:53], 0, s[96:97]
	v_lshl_add_u64 v[62:63], v[46:47], 1, v[62:63]
	v_lshl_add_u64 v[62:63], v[62:63], 0, v[50:51]
	v_add_co_u32_e32 v62, vcc, s3, v62
	v_cvt_pk_bf16_f32 v57, v64, v65
	s_nop 0
	v_addc_co_u32_e32 v63, vcc, 0, v63, vcc
	global_store_dwordx2 v[62:63], v[56:57], off offset:2560
	s_nop 0
	v_add_u32_e32 v51, 0x2800, v49
	ds_read2_b64 v[116:119], v51 offset1:80
	ds_read_b128 v[120:123], v17 offset:1088
	ds_read_b128 v[128:131], v17 offset:1152
	ds_read2_b64 v[132:135], v51 offset0:160 offset1:240
	ds_read_b128 v[136:139], v17 offset:1216
	ds_read_b128 v[140:143], v17 offset:1280
	s_nop 0
	s_nop 0
	s_nop 0
	s_nop 0
	s_nop 0
	s_waitcnt lgkmcnt(6)
	v_pk_mul_f32 v[12:13], v[12:13], v[114:115]
	v_pk_mul_f32 v[10:11], v[10:11], v[112:113]
	s_nop 0
	s_waitcnt lgkmcnt(4)
	v_pk_mul_f32 v[20:21], v[20:21], v[122:123]
	v_pk_mul_f32 v[18:19], v[18:19], v[120:121]
	v_mfma_f32_16x16x16_bf16 v[10:13], v[116:117], v[54:55], v[10:13]
	s_nop 0
	v_mfma_f32_16x16x16_bf16 v[18:21], v[118:119], v[54:55], v[18:21]
	s_nop 0
	s_nop 0
	v_add_u32_e32 v51, 0x3000, v49
	ds_read2_b64 v[144:147], v51 offset0:64 offset1:144
	ds_read_b128 v[216:219], v17 offset:1344
	ds_read_b128 v[220:223], v17 offset:1408
	s_nop 0
	s_nop 0
	s_waitcnt lgkmcnt(6)
	v_pk_mul_f32 v[24:25], v[24:25], v[130:131]
	v_pk_mul_f32 v[22:23], v[22:23], v[128:129]
	s_nop 0
	s_waitcnt lgkmcnt(4)
	v_pk_mul_f32 v[28:29], v[28:29], v[138:139]
	v_pk_mul_f32 v[26:27], v[26:27], v[136:137]
	s_nop 0
	v_mfma_f32_16x16x16_bf16 v[22:25], v[132:133], v[54:55], v[22:25]
	s_waitcnt lgkmcnt(3)
	v_pk_mul_f32 v[32:33], v[32:33], v[142:143]
	v_mfma_f32_16x16x16_bf16 v[26:29], v[134:135], v[54:55], v[26:29]
	s_nop 0
	v_pk_mul_f32 v[30:31], v[30:31], v[140:141]
	s_nop 0
	v_add_u32_e32 v51, 0x3400, v49
	s_waitcnt lgkmcnt(2)
	v_mfma_f32_16x16x16_bf16 v[30:33], v[144:145], v[54:55], v[30:33]
	s_waitcnt lgkmcnt(1)
	v_pk_mul_f32 v[36:37], v[36:37], v[218:219]
	v_pk_mul_f32 v[34:35], v[34:35], v[216:217]
	s_nop 0
	s_waitcnt lgkmcnt(0)
	v_pk_mul_f32 v[40:41], v[40:41], v[222:223]
	v_mfma_f32_16x16x16_bf16 v[34:37], v[146:147], v[54:55], v[34:37]
	ds_read2_b64 v[66:69], v51 offset0:96 offset1:176
	v_pk_mul_f32 v[38:39], v[38:39], v[220:221]
	ds_read_b128 v[62:65], v17 offset:1472
	s_waitcnt lgkmcnt(0)
	v_pk_mul_f32 v[44:45], v[44:45], v[64:65]
	v_pk_mul_f32 v[42:43], v[42:43], v[62:63]
	v_mfma_f32_16x16x16_bf16 v[38:41], v[66:67], v[54:55], v[38:41]
	s_nop 0
	v_mfma_f32_16x16x16_bf16 v[42:45], v[68:69], v[54:55], v[42:45]
	s_and_b64 vcc, exec, s[38:39]
	s_cbranch_vccnz .LBB0_606
; __device__ __forceinline__ unsigned pk2(float lo, float hi) { f32x2_t v = {lo, hi}; bf16x2_t b = __builtin_convertvector(v, bf16x2_t); return __builtin_bit_cast(unsigned, b); }
; __device__ __forceinline__ f32x4 mfma16(bf16x4 a, bf16x4 b, f32x4 c) { return __builtin_amdgcn_mfma_f32_16x16x16bf16_1k(a, b, c, 0, 0, 0); }
; __device__ __forceinline__ bf16x4 pack4(f32x4 v) { u32x2 w; w.x = pk2(v[0], v[1]); w.y = pk2(v[2], v[3]); return __builtin_bit_cast(bf16x4, w); }
; __device__ __forceinline__ void hg_unit(const Ptrs& P, int l, int b, int hd, int ch, unsigned char* lds, int tid) {
;     ...
;     for (int j = 0; j < 8; ++j) {
;         if (j < nsub) {
;             const bf16x4 vf = *(const bf16x4*)(Vt + (j * 16 + lc) * 20 + 4 * g);
;             const bf16x4 atj = *(const bf16x4*)HG_ATT_SLOT(j);
;             f32x4 o = mfma16(vf, atj, (f32x4){0.f, 0.f, 0.f, 0.f});
;             if (j > 0) {
; #pragma unroll
;                 for (int kt = 0; kt < 8; ++kt) { const bf16x4 qf = *(const bf16x4*)(Qb + (16 * j + lc) * 136 + 16 * kt + 4 * g); o = mfma16(pack4(S[kt]), qf, o); } }
;             { u32x2 wv; wv.x = pk2(o[0], o[1]); wv.y = pk2(o[2], o[3]); *(u32x2*)(PJ + (row0 + 16 * j + lc) * PW + C_HI + hd * 128 + 16 * w + 4 * g) = wv; }
; #pragma unroll
;             for (int kt = 0; kt < 8; ++kt) { const f32x4 eb = *(const f32x4*)(EBE + j * 128 + 16 * kt + 4 * g);
;                 const bf16x4 kf = *(const bf16x4*)(Ket + (j * 128 + 16 * kt + lc) * 20 + 4 * g);
;                 S[kt] = mfma16(kf, vf, S[kt] * eb); }
;         }
;     }
.LBB0_615:
	v_or_b32_e32 v51, 48, v48
	v_mad_u32_u24 v54, v51, 40, v58
	ds_read_b64 v[54:55], v54
	ds_read_b64 v[72:73], v61 offset:13312
	v_mad_u32_u24 v51, v51, s26, v59
	ds_read2_b64 v[76:79], v51 offset1:4
	ds_read2_b64 v[80:83], v51 offset0:8 offset1:12
	ds_read2_b64 v[98:101], v51 offset0:16 offset1:20
	ds_read2_b64 v[102:105], v51 offset0:24 offset1:28
	ds_read_b128 v[112:115], v17 offset:1536
	s_nop 0
	s_nop 0
	s_nop 0
	s_nop 0
	s_mov_b32 s3, 0xc9000
	s_waitcnt lgkmcnt(5)
	v_mfma_f32_16x16x16_bf16 v[62:65], v[54:55], v[72:73], 0
	v_cvt_pk_bf16_f32 v56, v10, v11
	v_cvt_pk_bf16_f32 v57, v12, v13
	s_waitcnt lgkmcnt(4)
	s_nop 0
	v_mfma_f32_16x16x16_bf16 v[62:65], v[56:57], v[76:77], v[62:65]
	v_cvt_pk_bf16_f32 v56, v18, v19
	v_cvt_pk_bf16_f32 v57, v20, v21
	s_nop 1
	v_mfma_f32_16x16x16_bf16 v[62:65], v[56:57], v[78:79], v[62:65]
	s_nop 0
	v_cvt_pk_bf16_f32 v56, v22, v23
	v_cvt_pk_bf16_f32 v57, v24, v25
	s_waitcnt lgkmcnt(3)
	s_nop 0
	v_mfma_f32_16x16x16_bf16 v[62:65], v[56:57], v[80:81], v[62:65]
	v_cvt_pk_bf16_f32 v56, v26, v27
	v_cvt_pk_bf16_f32 v57, v28, v29
	s_nop 1
	v_mfma_f32_16x16x16_bf16 v[62:65], v[56:57], v[82:83], v[62:65]
	s_nop 0
	v_cvt_pk_bf16_f32 v56, v30, v31
	v_cvt_pk_bf16_f32 v57, v32, v33
	s_waitcnt lgkmcnt(2)
	s_nop 0
	v_mfma_f32_16x16x16_bf16 v[62:65], v[56:57], v[98:99], v[62:65]
	v_cvt_pk_bf16_f32 v56, v34, v35
	v_cvt_pk_bf16_f32 v57, v36, v37
	s_nop 1
	v_mfma_f32_16x16x16_bf16 v[62:65], v[56:57], v[100:101], v[62:65]
	s_nop 0
	v_cvt_pk_bf16_f32 v56, v38, v39
	v_cvt_pk_bf16_f32 v57, v40, v41
	v_mov_b32_e32 v51, v16
	s_waitcnt lgkmcnt(1)
	v_mfma_f32_16x16x16_bf16 v[62:65], v[56:57], v[102:103], v[62:65]
	v_cvt_pk_bf16_f32 v56, v42, v43
	v_cvt_pk_bf16_f32 v57, v44, v45
	s_nop 1
	v_mfma_f32_16x16x16_bf16 v[62:65], v[56:57], v[104:105], v[62:65]
	s_nop 7
	v_cvt_pk_bf16_f32 v56, v62, v63
	v_lshl_add_u64 v[62:63], v[52:53], 0, s[96:97]
	v_lshl_add_u64 v[62:63], v[46:47], 1, v[62:63]
	v_lshl_add_u64 v[62:63], v[62:63], 0, v[50:51]
	v_add_co_u32_e32 v62, vcc, s3, v62
	v_cvt_pk_bf16_f32 v57, v64, v65
	s_nop 0
	v_addc_co_u32_e32 v63, vcc, 0, v63, vcc
	global_store_dwordx2 v[62:63], v[56:57], off offset:2560
	s_nop 0
	v_add_u32_e32 v51, 0x3800, v49
	ds_read2_b64 v[116:119], v51 offset0:128 offset1:208
	ds_read_b128 v[120:123], v17 offset:1600
	ds_read_b128 v[128:131], v17 offset:1664
	s_nop 0
	s_nop 0
	v_add_u32_e32 v51, 0x4000, v49
	ds_read2_b64 v[132:135], v51 offset0:32 offset1:112
	ds_read_b128 v[136:139], v17 offset:1728
	ds_read_b128 v[140:143], v17 offset:1792
	s_nop 0
	s_nop 0
	s_waitcnt lgkmcnt(6)
	v_pk_mul_f32 v[12:13], v[12:13], v[114:115]
	v_pk_mul_f32 v[10:11], v[10:11], v[112:113]
	s_nop 0
	s_waitcnt lgkmcnt(4)
	v_pk_mul_f32 v[20:21], v[20:21], v[122:123]
	v_pk_mul_f32 v[18:19], v[18:19], v[120:121]
	s_nop 0
	v_mfma_f32_16x16x16_bf16 v[10:13], v[116:117], v[54:55], v[10:13]
	s_waitcnt lgkmcnt(3)
	v_pk_mul_f32 v[24:25], v[24:25], v[130:131]
	v_mfma_f32_16x16x16_bf16 v[18:21], v[118:119], v[54:55], v[18:21]
	s_nop 0
	v_pk_mul_f32 v[22:23], v[22:23], v[128:129]
	s_nop 0
	v_add_u32_e32 v51, 0x4400, v49
	ds_read2_b64 v[144:147], v51 offset0:64 offset1:144
	ds_read_b128 v[216:219], v17 offset:1856
	ds_read_b128 v[220:223], v17 offset:1920
	s_nop 0
	s_nop 0
	s_waitcnt lgkmcnt(5)
	v_mfma_f32_16x16x16_bf16 v[22:25], v[132:133], v[54:55], v[22:25]
	s_waitcnt lgkmcnt(4)
	v_pk_mul_f32 v[28:29], v[28:29], v[138:139]
	v_pk_mul_f32 v[26:27], v[26:27], v[136:137]
	s_nop 0
	s_waitcnt lgkmcnt(3)
	v_pk_mul_f32 v[32:33], v[32:33], v[142:143]
	v_mfma_f32_16x16x16_bf16 v[26:29], v[134:135], v[54:55], v[26:29]
	s_nop 0
	v_pk_mul_f32 v[30:31], v[30:31], v[140:141]
	s_nop 0
	v_add_u32_e32 v51, 0x4800, v49
	s_waitcnt lgkmcnt(2)
	v_mfma_f32_16x16x16_bf16 v[30:33], v[144:145], v[54:55], v[30:33]
	s_waitcnt lgkmcnt(1)
	v_pk_mul_f32 v[36:37], v[36:37], v[218:219]
	v_pk_mul_f32 v[34:35], v[34:35], v[216:217]
	s_nop 0
	s_waitcnt lgkmcnt(0)
	v_pk_mul_f32 v[40:41], v[40:41], v[222:223]
	v_mfma_f32_16x16x16_bf16 v[34:37], v[146:147], v[54:55], v[34:37]
	ds_read2_b64 v[66:69], v51 offset0:96 offset1:176
	v_pk_mul_f32 v[38:39], v[38:39], v[220:221]
	ds_read_b128 v[62:65], v17 offset:1984
	s_waitcnt lgkmcnt(0)
	v_pk_mul_f32 v[44:45], v[44:45], v[64:65]
	v_pk_mul_f32 v[42:43], v[42:43], v[62:63]
	v_mfma_f32_16x16x16_bf16 v[38:41], v[66:67], v[54:55], v[38:41]
	s_nop 0
	v_mfma_f32_16x16x16_bf16 v[42:45], v[68:69], v[54:55], v[42:45]
	s_and_b64 vcc, exec, s[38:39]
	s_cbranch_vccnz .LBB0_607
; __device__ __forceinline__ unsigned pk2(float lo, float hi) { f32x2_t v = {lo, hi}; bf16x2_t b = __builtin_convertvector(v, bf16x2_t); return __builtin_bit_cast(unsigned, b); }
; __device__ __forceinline__ f32x4 mfma16(bf16x4 a, bf16x4 b, f32x4 c) { return __builtin_amdgcn_mfma_f32_16x16x16bf16_1k(a, b, c, 0, 0, 0); }
; __device__ __forceinline__ bf16x4 pack4(f32x4 v) { u32x2 w; w.x = pk2(v[0], v[1]); w.y = pk2(v[2], v[3]); return __builtin_bit_cast(bf16x4, w); }
; __device__ __forceinline__ void hg_unit(const Ptrs& P, int l, int b, int hd, int ch, unsigned char* lds, int tid) {
;     ...
;     for (int j = 0; j < 8; ++j) {
;         if (j < nsub) {
;             const bf16x4 vf = *(const bf16x4*)(Vt + (j * 16 + lc) * 20 + 4 * g);
;             const bf16x4 atj = *(const bf16x4*)HG_ATT_SLOT(j);
;             f32x4 o = mfma16(vf, atj, (f32x4){0.f, 0.f, 0.f, 0.f});
;             if (j > 0) {
; #pragma unroll
;                 for (int kt = 0; kt < 8; ++kt) { const bf16x4 qf = *(const bf16x4*)(Qb + (16 * j + lc) * 136 + 16 * kt + 4 * g); o = mfma16(pack4(S[kt]), qf, o); } }
;             { u32x2 wv; wv.x = pk2(o[0], o[1]); wv.y = pk2(o[2], o[3]); *(u32x2*)(PJ + (row0 + 16 * j + lc) * PW + C_HI + hd * 128 + 16 * w + 4 * g) = wv; }
; #pragma unroll
;             for (int kt = 0; kt < 8; ++kt) { const f32x4 eb = *(const f32x4*)(EBE + j * 128 + 16 * kt + 4 * g);
;                 const bf16x4 kf = *(const bf16x4*)(Ket + (j * 128 + 16 * kt + lc) * 20 + 4 * g);
;                 S[kt] = mfma16(kf, vf, S[kt] * eb); }
;         }
;     }
.LBB0_616:
	v_or_b32_e32 v51, 64, v48
	v_mad_u32_u24 v54, v51, 40, v58
	ds_read_b64 v[54:55], v54
	ds_read_b64 v[72:73], v61 offset:17664
	v_mad_u32_u24 v51, v51, s26, v59
	ds_read2_b64 v[76:79], v51 offset1:4
	ds_read2_b64 v[80:83], v51 offset0:8 offset1:12
	ds_read2_b64 v[98:101], v51 offset0:16 offset1:20
	ds_read2_b64 v[102:105], v51 offset0:24 offset1:28
	ds_read_b128 v[112:115], v17 offset:2048
	s_nop 0
	s_nop 0
	s_nop 0
	s_nop 0
	s_mov_b32 s3, 0x10b000
	s_waitcnt lgkmcnt(5)
	v_mfma_f32_16x16x16_bf16 v[62:65], v[54:55], v[72:73], 0
	v_cvt_pk_bf16_f32 v56, v10, v11
	v_cvt_pk_bf16_f32 v57, v12, v13
	s_waitcnt lgkmcnt(4)
	s_nop 0
	v_mfma_f32_16x16x16_bf16 v[62:65], v[56:57], v[76:77], v[62:65]
	v_cvt_pk_bf16_f32 v56, v18, v19
	v_cvt_pk_bf16_f32 v57, v20, v21
	s_nop 1
	v_mfma_f32_16x16x16_bf16 v[62:65], v[56:57], v[78:79], v[62:65]
	s_nop 0
	v_cvt_pk_bf16_f32 v56, v22, v23
	v_cvt_pk_bf16_f32 v57, v24, v25
	s_waitcnt lgkmcnt(3)
	s_nop 0
	v_mfma_f32_16x16x16_bf16 v[62:65], v[56:57], v[80:81], v[62:65]
	v_cvt_pk_bf16_f32 v56, v26, v27
	v_cvt_pk_bf16_f32 v57, v28, v29
	s_nop 1
	v_mfma_f32_16x16x16_bf16 v[62:65], v[56:57], v[82:83], v[62:65]
	s_nop 0
	v_cvt_pk_bf16_f32 v56, v30, v31
	v_cvt_pk_bf16_f32 v57, v32, v33
	s_waitcnt lgkmcnt(2)
	s_nop 0
	v_mfma_f32_16x16x16_bf16 v[62:65], v[56:57], v[98:99], v[62:65]
	v_cvt_pk_bf16_f32 v56, v34, v35
	v_cvt_pk_bf16_f32 v57, v36, v37
	s_nop 1
	v_mfma_f32_16x16x16_bf16 v[62:65], v[56:57], v[100:101], v[62:65]
	s_nop 0
	v_cvt_pk_bf16_f32 v56, v38, v39
	v_cvt_pk_bf16_f32 v57, v40, v41
	v_mov_b32_e32 v51, v16
	s_waitcnt lgkmcnt(1)
	v_mfma_f32_16x16x16_bf16 v[62:65], v[56:57], v[102:103], v[62:65]
	v_cvt_pk_bf16_f32 v56, v42, v43
	v_cvt_pk_bf16_f32 v57, v44, v45
	s_nop 1
	v_mfma_f32_16x16x16_bf16 v[62:65], v[56:57], v[104:105], v[62:65]
	s_nop 7
	v_cvt_pk_bf16_f32 v56, v62, v63
	v_lshl_add_u64 v[62:63], v[52:53], 0, s[96:97]
	v_lshl_add_u64 v[62:63], v[46:47], 1, v[62:63]
	v_lshl_add_u64 v[62:63], v[62:63], 0, v[50:51]
	v_add_co_u32_e32 v62, vcc, s3, v62
	v_cvt_pk_bf16_f32 v57, v64, v65
	s_nop 0
	v_addc_co_u32_e32 v63, vcc, 0, v63, vcc
	global_store_dwordx2 v[62:63], v[56:57], off offset:2560
	s_nop 0
	v_add_u32_e32 v51, 0x5000, v49
	ds_read2_b64 v[116:119], v51 offset1:80
	ds_read_b128 v[120:123], v17 offset:2112
	ds_read_b128 v[128:131], v17 offset:2176
	ds_read2_b64 v[132:135], v51 offset0:160 offset1:240
	ds_read_b128 v[136:139], v17 offset:2240
	ds_read_b128 v[140:143], v17 offset:2304
	s_nop 0
	s_nop 0
	s_nop 0
	s_nop 0
	s_nop 0
	s_waitcnt lgkmcnt(6)
	v_pk_mul_f32 v[12:13], v[12:13], v[114:115]
	v_pk_mul_f32 v[10:11], v[10:11], v[112:113]
	s_nop 0
	s_waitcnt lgkmcnt(4)
	v_pk_mul_f32 v[20:21], v[20:21], v[122:123]
	v_pk_mul_f32 v[18:19], v[18:19], v[120:121]
	v_mfma_f32_16x16x16_bf16 v[10:13], v[116:117], v[54:55], v[10:13]
	s_nop 0
	v_mfma_f32_16x16x16_bf16 v[18:21], v[118:119], v[54:55], v[18:21]
	s_nop 0
	s_nop 0
	v_add_u32_e32 v51, 0x5800, v49
	ds_read2_b64 v[144:147], v51 offset0:64 offset1:144
	ds_read_b128 v[216:219], v17 offset:2368
	ds_read_b128 v[220:223], v17 offset:2432
	s_nop 0
	s_nop 0
	s_waitcnt lgkmcnt(6)
	v_pk_mul_f32 v[24:25], v[24:25], v[130:131]
	v_pk_mul_f32 v[22:23], v[22:23], v[128:129]
	s_nop 0
	s_waitcnt lgkmcnt(4)
	v_pk_mul_f32 v[28:29], v[28:29], v[138:139]
	v_pk_mul_f32 v[26:27], v[26:27], v[136:137]
	s_nop 0
	v_mfma_f32_16x16x16_bf16 v[22:25], v[132:133], v[54:55], v[22:25]
	s_waitcnt lgkmcnt(3)
	v_pk_mul_f32 v[32:33], v[32:33], v[142:143]
	v_mfma_f32_16x16x16_bf16 v[26:29], v[134:135], v[54:55], v[26:29]
	s_nop 0
	v_pk_mul_f32 v[30:31], v[30:31], v[140:141]
	s_nop 0
	v_add_u32_e32 v51, 0x5c00, v49
	s_waitcnt lgkmcnt(2)
	v_mfma_f32_16x16x16_bf16 v[30:33], v[144:145], v[54:55], v[30:33]
	s_waitcnt lgkmcnt(1)
	v_pk_mul_f32 v[36:37], v[36:37], v[218:219]
	v_pk_mul_f32 v[34:35], v[34:35], v[216:217]
	s_nop 0
	s_waitcnt lgkmcnt(0)
	v_pk_mul_f32 v[40:41], v[40:41], v[222:223]
	v_mfma_f32_16x16x16_bf16 v[34:37], v[146:147], v[54:55], v[34:37]
	ds_read2_b64 v[66:69], v51 offset0:96 offset1:176
	v_pk_mul_f32 v[38:39], v[38:39], v[220:221]
	ds_read_b128 v[62:65], v17 offset:2496
	s_waitcnt lgkmcnt(0)
	v_pk_mul_f32 v[44:45], v[44:45], v[64:65]
	v_pk_mul_f32 v[42:43], v[42:43], v[62:63]
	v_mfma_f32_16x16x16_bf16 v[38:41], v[66:67], v[54:55], v[38:41]
	s_nop 0
	v_mfma_f32_16x16x16_bf16 v[42:45], v[68:69], v[54:55], v[42:45]
	s_and_b64 vcc, exec, s[38:39]
	s_cbranch_vccnz .LBB0_608
; __device__ __forceinline__ unsigned pk2(float lo, float hi) { f32x2_t v = {lo, hi}; bf16x2_t b = __builtin_convertvector(v, bf16x2_t); return __builtin_bit_cast(unsigned, b); }
; __device__ __forceinline__ f32x4 mfma16(bf16x4 a, bf16x4 b, f32x4 c) { return __builtin_amdgcn_mfma_f32_16x16x16bf16_1k(a, b, c, 0, 0, 0); }
; __device__ __forceinline__ bf16x4 pack4(f32x4 v) { u32x2 w; w.x = pk2(v[0], v[1]); w.y = pk2(v[2], v[3]); return __builtin_bit_cast(bf16x4, w); }
; __device__ __forceinline__ void hg_unit(const Ptrs& P, int l, int b, int hd, int ch, unsigned char* lds, int tid) {
;     ...
;     for (int j = 0; j < 8; ++j) {
;         if (j < nsub) {
;             const bf16x4 vf = *(const bf16x4*)(Vt + (j * 16 + lc) * 20 + 4 * g);
;             const bf16x4 atj = *(const bf16x4*)HG_ATT_SLOT(j);
;             f32x4 o = mfma16(vf, atj, (f32x4){0.f, 0.f, 0.f, 0.f});
;             if (j > 0) {
; #pragma unroll
;                 for (int kt = 0; kt < 8; ++kt) { const bf16x4 qf = *(const bf16x4*)(Qb + (16 * j + lc) * 136 + 16 * kt + 4 * g); o = mfma16(pack4(S[kt]), qf, o); } }
;             { u32x2 wv; wv.x = pk2(o[0], o[1]); wv.y = pk2(o[2], o[3]); *(u32x2*)(PJ + (row0 + 16 * j + lc) * PW + C_HI + hd * 128 + 16 * w + 4 * g) = wv; }
; #pragma unroll
;             for (int kt = 0; kt < 8; ++kt) { const f32x4 eb = *(const f32x4*)(EBE + j * 128 + 16 * kt + 4 * g);
;                 const bf16x4 kf = *(const bf16x4*)(Ket + (j * 128 + 16 * kt + lc) * 20 + 4 * g);
;                 S[kt] = mfma16(kf, vf, S[kt] * eb); }
;         }
;     }
.LBB0_617:
	v_or_b32_e32 v51, 0x50, v48
	v_mad_u32_u24 v54, v51, 40, v58
	ds_read_b64 v[54:55], v54
	ds_read_b64 v[72:73], v61 offset:22016
	v_mad_u32_u24 v51, v51, s26, v59
	ds_read2_b64 v[76:79], v51 offset1:4
	ds_read2_b64 v[80:83], v51 offset0:8 offset1:12
	ds_read2_b64 v[98:101], v51 offset0:16 offset1:20
	ds_read2_b64 v[102:105], v51 offset0:24 offset1:28
	ds_read_b128 v[112:115], v17 offset:2560
	s_nop 0
	s_nop 0
	s_nop 0
	s_nop 0
	s_mov_b32 s3, 0x14d000
	s_waitcnt lgkmcnt(5)
	v_mfma_f32_16x16x16_bf16 v[62:65], v[54:55], v[72:73], 0
	v_cvt_pk_bf16_f32 v56, v10, v11
	v_cvt_pk_bf16_f32 v57, v12, v13
	s_waitcnt lgkmcnt(4)
	s_nop 0
	v_mfma_f32_16x16x16_bf16 v[62:65], v[56:57], v[76:77], v[62:65]
	v_cvt_pk_bf16_f32 v56, v18, v19
	v_cvt_pk_bf16_f32 v57, v20, v21
	s_nop 1
	v_mfma_f32_16x16x16_bf16 v[62:65], v[56:57], v[78:79], v[62:65]
	s_nop 0
	v_cvt_pk_bf16_f32 v56, v22, v23
	v_cvt_pk_bf16_f32 v57, v24, v25
	s_waitcnt lgkmcnt(3)
	s_nop 0
	v_mfma_f32_16x16x16_bf16 v[62:65], v[56:57], v[80:81], v[62:65]
	v_cvt_pk_bf16_f32 v56, v26, v27
	v_cvt_pk_bf16_f32 v57, v28, v29
	s_nop 1
	v_mfma_f32_16x16x16_bf16 v[62:65], v[56:57], v[82:83], v[62:65]
	s_nop 0
	v_cvt_pk_bf16_f32 v56, v30, v31
	v_cvt_pk_bf16_f32 v57, v32, v33
	s_waitcnt lgkmcnt(2)
	s_nop 0
	v_mfma_f32_16x16x16_bf16 v[62:65], v[56:57], v[98:99], v[62:65]
	v_cvt_pk_bf16_f32 v56, v34, v35
	v_cvt_pk_bf16_f32 v57, v36, v37
	s_nop 1
	v_mfma_f32_16x16x16_bf16 v[62:65], v[56:57], v[100:101], v[62:65]
	s_nop 0
	v_cvt_pk_bf16_f32 v56, v38, v39
	v_cvt_pk_bf16_f32 v57, v40, v41
	v_mov_b32_e32 v51, v16
	s_waitcnt lgkmcnt(1)
	v_mfma_f32_16x16x16_bf16 v[62:65], v[56:57], v[102:103], v[62:65]
	v_cvt_pk_bf16_f32 v56, v42, v43
	v_cvt_pk_bf16_f32 v57, v44, v45
	s_nop 1
	v_mfma_f32_16x16x16_bf16 v[62:65], v[56:57], v[104:105], v[62:65]
	s_nop 7
	v_cvt_pk_bf16_f32 v56, v62, v63
	v_lshl_add_u64 v[62:63], v[52:53], 0, s[96:97]
	v_lshl_add_u64 v[62:63], v[46:47], 1, v[62:63]
	v_lshl_add_u64 v[62:63], v[62:63], 0, v[50:51]
	v_add_co_u32_e32 v62, vcc, s3, v62
	v_cvt_pk_bf16_f32 v57, v64, v65
	s_nop 0
	v_addc_co_u32_e32 v63, vcc, 0, v63, vcc
	global_store_dwordx2 v[62:63], v[56:57], off offset:2560
	s_nop 0
	v_add_u32_e32 v51, 0x6000, v49
	ds_read2_b64 v[116:119], v51 offset0:128 offset1:208
	ds_read_b128 v[120:123], v17 offset:2624
	ds_read_b128 v[128:131], v17 offset:2688
	s_nop 0
	s_nop 0
	v_add_u32_e32 v51, 0x6800, v49
	ds_read2_b64 v[132:135], v51 offset0:32 offset1:112
	ds_read_b128 v[136:139], v17 offset:2752
	ds_read_b128 v[140:143], v17 offset:2816
	s_nop 0
	s_nop 0
	s_waitcnt lgkmcnt(6)
	v_pk_mul_f32 v[12:13], v[12:13], v[114:115]
	v_pk_mul_f32 v[10:11], v[10:11], v[112:113]
	s_nop 0
	s_waitcnt lgkmcnt(4)
	v_pk_mul_f32 v[20:21], v[20:21], v[122:123]
	v_pk_mul_f32 v[18:19], v[18:19], v[120:121]
	s_nop 0
	v_mfma_f32_16x16x16_bf16 v[10:13], v[116:117], v[54:55], v[10:13]
	s_waitcnt lgkmcnt(3)
	v_pk_mul_f32 v[24:25], v[24:25], v[130:131]
	v_mfma_f32_16x16x16_bf16 v[18:21], v[118:119], v[54:55], v[18:21]
	s_nop 0
	v_pk_mul_f32 v[22:23], v[22:23], v[128:129]
	s_nop 0
	v_add_u32_e32 v51, 0x6c00, v49
	ds_read2_b64 v[144:147], v51 offset0:64 offset1:144
	ds_read_b128 v[216:219], v17 offset:2880
	ds_read_b128 v[220:223], v17 offset:2944
	s_nop 0
	s_nop 0
	s_waitcnt lgkmcnt(5)
	v_mfma_f32_16x16x16_bf16 v[22:25], v[132:133], v[54:55], v[22:25]
	s_waitcnt lgkmcnt(4)
	v_pk_mul_f32 v[28:29], v[28:29], v[138:139]
	v_pk_mul_f32 v[26:27], v[26:27], v[136:137]
	s_nop 0
	s_waitcnt lgkmcnt(3)
	v_pk_mul_f32 v[32:33], v[32:33], v[142:143]
	v_mfma_f32_16x16x16_bf16 v[26:29], v[134:135], v[54:55], v[26:29]
	s_nop 0
	v_pk_mul_f32 v[30:31], v[30:31], v[140:141]
	s_nop 0
	v_add_u32_e32 v51, 0x7000, v49
	s_waitcnt lgkmcnt(2)
	v_mfma_f32_16x16x16_bf16 v[30:33], v[144:145], v[54:55], v[30:33]
	s_waitcnt lgkmcnt(1)
	v_pk_mul_f32 v[36:37], v[36:37], v[218:219]
	v_pk_mul_f32 v[34:35], v[34:35], v[216:217]
	s_nop 0
	s_waitcnt lgkmcnt(0)
	v_pk_mul_f32 v[40:41], v[40:41], v[222:223]
	v_mfma_f32_16x16x16_bf16 v[34:37], v[146:147], v[54:55], v[34:37]
	ds_read2_b64 v[66:69], v51 offset0:96 offset1:176
	v_pk_mul_f32 v[38:39], v[38:39], v[220:221]
	ds_read_b128 v[62:65], v17 offset:3008
	s_waitcnt lgkmcnt(0)
	v_pk_mul_f32 v[44:45], v[44:45], v[64:65]
	v_pk_mul_f32 v[42:43], v[42:43], v[62:63]
	v_mfma_f32_16x16x16_bf16 v[38:41], v[66:67], v[54:55], v[38:41]
	s_nop 0
	v_mfma_f32_16x16x16_bf16 v[42:45], v[68:69], v[54:55], v[42:45]
	s_and_b64 vcc, exec, s[38:39]
	s_cbranch_vccnz .LBB0_609
; __device__ __forceinline__ unsigned pk2(float lo, float hi) { f32x2_t v = {lo, hi}; bf16x2_t b = __builtin_convertvector(v, bf16x2_t); return __builtin_bit_cast(unsigned, b); }
; __device__ __forceinline__ f32x4 mfma16(bf16x4 a, bf16x4 b, f32x4 c) { return __builtin_amdgcn_mfma_f32_16x16x16bf16_1k(a, b, c, 0, 0, 0); }
; __device__ __forceinline__ bf16x4 pack4(f32x4 v) { u32x2 w; w.x = pk2(v[0], v[1]); w.y = pk2(v[2], v[3]); return __builtin_bit_cast(bf16x4, w); }
; __device__ __forceinline__ void hg_unit(const Ptrs& P, int l, int b, int hd, int ch, unsigned char* lds, int tid) {
;     ...
;     for (int j = 0; j < 8; ++j) {
;         if (j < nsub) {
;             const bf16x4 vf = *(const bf16x4*)(Vt + (j * 16 + lc) * 20 + 4 * g);
;             const bf16x4 atj = *(const bf16x4*)HG_ATT_SLOT(j);
;             f32x4 o = mfma16(vf, atj, (f32x4){0.f, 0.f, 0.f, 0.f});
;             if (j > 0) {
; #pragma unroll
;                 for (int kt = 0; kt < 8; ++kt) { const bf16x4 qf = *(const bf16x4*)(Qb + (16 * j + lc) * 136 + 16 * kt + 4 * g); o = mfma16(pack4(S[kt]), qf, o); } }
;             { u32x2 wv; wv.x = pk2(o[0], o[1]); wv.y = pk2(o[2], o[3]); *(u32x2*)(PJ + (row0 + 16 * j + lc) * PW + C_HI + hd * 128 + 16 * w + 4 * g) = wv; }
; #pragma unroll
;             for (int kt = 0; kt < 8; ++kt) { const f32x4 eb = *(const f32x4*)(EBE + j * 128 + 16 * kt + 4 * g);
;                 const bf16x4 kf = *(const bf16x4*)(Ket + (j * 128 + 16 * kt + lc) * 20 + 4 * g);
;                 S[kt] = mfma16(kf, vf, S[kt] * eb); }
;         }
;     }
.LBB0_618:
	v_or_b32_e32 v51, 0x60, v48
	v_mad_u32_u24 v54, v51, 40, v58
	ds_read_b64 v[54:55], v54
	ds_read_b64 v[72:73], v61 offset:26368
	v_mad_u32_u24 v51, v51, s26, v59
	ds_read2_b64 v[76:79], v51 offset1:4
	ds_read2_b64 v[80:83], v51 offset0:8 offset1:12
	ds_read2_b64 v[98:101], v51 offset0:16 offset1:20
	ds_read2_b64 v[102:105], v51 offset0:24 offset1:28
	ds_read_b128 v[112:115], v17 offset:3072
	s_nop 0
	s_nop 0
	s_nop 0
	s_nop 0
	s_mov_b32 s3, 0x18f000
	s_waitcnt lgkmcnt(5)
	v_mfma_f32_16x16x16_bf16 v[62:65], v[54:55], v[72:73], 0
	v_cvt_pk_bf16_f32 v56, v10, v11
	v_cvt_pk_bf16_f32 v57, v12, v13
	s_waitcnt lgkmcnt(4)
	s_nop 0
	v_mfma_f32_16x16x16_bf16 v[62:65], v[56:57], v[76:77], v[62:65]
	v_cvt_pk_bf16_f32 v56, v18, v19
	v_cvt_pk_bf16_f32 v57, v20, v21
	s_nop 1
	v_mfma_f32_16x16x16_bf16 v[62:65], v[56:57], v[78:79], v[62:65]
	s_nop 0
	v_cvt_pk_bf16_f32 v56, v22, v23
	v_cvt_pk_bf16_f32 v57, v24, v25
	s_waitcnt lgkmcnt(3)
	s_nop 0
	v_mfma_f32_16x16x16_bf16 v[62:65], v[56:57], v[80:81], v[62:65]
	v_cvt_pk_bf16_f32 v56, v26, v27
	v_cvt_pk_bf16_f32 v57, v28, v29
	s_nop 1
	v_mfma_f32_16x16x16_bf16 v[62:65], v[56:57], v[82:83], v[62:65]
	s_nop 0
	v_cvt_pk_bf16_f32 v56, v30, v31
	v_cvt_pk_bf16_f32 v57, v32, v33
	s_waitcnt lgkmcnt(2)
	s_nop 0
	v_mfma_f32_16x16x16_bf16 v[62:65], v[56:57], v[98:99], v[62:65]
	v_cvt_pk_bf16_f32 v56, v34, v35
	v_cvt_pk_bf16_f32 v57, v36, v37
	s_nop 1
	v_mfma_f32_16x16x16_bf16 v[62:65], v[56:57], v[100:101], v[62:65]
	s_nop 0
	v_cvt_pk_bf16_f32 v56, v38, v39
	v_cvt_pk_bf16_f32 v57, v40, v41
	v_mov_b32_e32 v51, v16
	s_waitcnt lgkmcnt(1)
	v_mfma_f32_16x16x16_bf16 v[62:65], v[56:57], v[102:103], v[62:65]
	v_cvt_pk_bf16_f32 v56, v42, v43
	v_cvt_pk_bf16_f32 v57, v44, v45
	s_nop 1
	v_mfma_f32_16x16x16_bf16 v[62:65], v[56:57], v[104:105], v[62:65]
	s_nop 7
	v_cvt_pk_bf16_f32 v56, v62, v63
	v_lshl_add_u64 v[62:63], v[52:53], 0, s[96:97]
	v_lshl_add_u64 v[62:63], v[46:47], 1, v[62:63]
	v_lshl_add_u64 v[62:63], v[62:63], 0, v[50:51]
	v_add_co_u32_e32 v62, vcc, s3, v62
	v_cvt_pk_bf16_f32 v57, v64, v65
	s_nop 0
	v_addc_co_u32_e32 v63, vcc, 0, v63, vcc
	global_store_dwordx2 v[62:63], v[56:57], off offset:2560
	s_nop 0
	v_add_u32_e32 v51, 0x7800, v49
	ds_read2_b64 v[116:119], v51 offset1:80
	ds_read_b128 v[120:123], v17 offset:3136
	ds_read_b128 v[128:131], v17 offset:3200
	ds_read2_b64 v[132:135], v51 offset0:160 offset1:240
	ds_read_b128 v[136:139], v17 offset:3264
	ds_read_b128 v[140:143], v17 offset:3328
	s_nop 0
	s_nop 0
	s_nop 0
	s_nop 0
	s_nop 0
	s_waitcnt lgkmcnt(6)
	v_pk_mul_f32 v[12:13], v[12:13], v[114:115]
	v_pk_mul_f32 v[10:11], v[10:11], v[112:113]
	s_nop 0
	s_waitcnt lgkmcnt(4)
	v_pk_mul_f32 v[20:21], v[20:21], v[122:123]
	v_pk_mul_f32 v[18:19], v[18:19], v[120:121]
	v_mfma_f32_16x16x16_bf16 v[10:13], v[116:117], v[54:55], v[10:13]
	s_nop 0
	v_mfma_f32_16x16x16_bf16 v[18:21], v[118:119], v[54:55], v[18:21]
	s_nop 0
	s_nop 0
	v_add_u32_e32 v51, 0x8000, v49
	ds_read2_b64 v[144:147], v51 offset0:64 offset1:144
	ds_read_b128 v[216:219], v17 offset:3392
	ds_read_b128 v[220:223], v17 offset:3456
	s_nop 0
	s_nop 0
	s_waitcnt lgkmcnt(6)
	v_pk_mul_f32 v[24:25], v[24:25], v[130:131]
	v_pk_mul_f32 v[22:23], v[22:23], v[128:129]
	s_nop 0
	s_waitcnt lgkmcnt(4)
	v_pk_mul_f32 v[28:29], v[28:29], v[138:139]
	v_pk_mul_f32 v[26:27], v[26:27], v[136:137]
	s_nop 0
	v_mfma_f32_16x16x16_bf16 v[22:25], v[132:133], v[54:55], v[22:25]
	s_waitcnt lgkmcnt(3)
	v_pk_mul_f32 v[32:33], v[32:33], v[142:143]
	v_mfma_f32_16x16x16_bf16 v[26:29], v[134:135], v[54:55], v[26:29]
	s_nop 0
	v_pk_mul_f32 v[30:31], v[30:31], v[140:141]
	s_nop 0
	v_add_u32_e32 v51, 0x8400, v49
	s_waitcnt lgkmcnt(2)
	v_mfma_f32_16x16x16_bf16 v[30:33], v[144:145], v[54:55], v[30:33]
	s_waitcnt lgkmcnt(1)
	v_pk_mul_f32 v[36:37], v[36:37], v[218:219]
	v_pk_mul_f32 v[34:35], v[34:35], v[216:217]
	s_nop 0
	s_waitcnt lgkmcnt(0)
	v_pk_mul_f32 v[40:41], v[40:41], v[222:223]
	v_mfma_f32_16x16x16_bf16 v[34:37], v[146:147], v[54:55], v[34:37]
	ds_read2_b64 v[66:69], v51 offset0:96 offset1:176
	v_pk_mul_f32 v[38:39], v[38:39], v[220:221]
	ds_read_b128 v[62:65], v17 offset:3520
	s_waitcnt lgkmcnt(0)
	v_pk_mul_f32 v[44:45], v[44:45], v[64:65]
	v_pk_mul_f32 v[42:43], v[42:43], v[62:63]
	v_mfma_f32_16x16x16_bf16 v[38:41], v[66:67], v[54:55], v[38:41]
	s_nop 0
	v_mfma_f32_16x16x16_bf16 v[42:45], v[68:69], v[54:55], v[42:45]
	s_and_b64 vcc, exec, s[38:39]
	s_cbranch_vccz .LBB0_610
	s_branch .LBB0_611

; __device__ __forceinline__ unsigned pk2(float lo, float hi) { f32x2_t v = {lo, hi}; bf16x2_t b = __builtin_convertvector(v, bf16x2_t); return __builtin_bit_cast(unsigned, b); }
; __device__ __forceinline__ float siluf(float x) { return x * __builtin_amdgcn_rcpf(1.0f + __expf(-x)); }
; __device__ __forceinline__ void hg_passB(const Ptrs& P, int l, int b, int hd, int ch, unsigned char* lds, int tid, bool dost) {
;     ...
;     const f32x4 nw = *(const f32x4*)(P.hg_norm_w + l * 128 + 16 * w + 4 * g);
; #pragma unroll
;     for (int j = 0; j < 8; ++j) {
;         if (j < nsub) {
;             float tot = 0.f;
; #pragma unroll
;             for (int ww = 0; ww < 8; ++ww) tot += SSQ[ww * 128 + 16 * j + lc];
;             const float rstd = 1.0f / sqrtf(tot * (1.0f / 128.0f) + EPS);
;             bf16_t* gp = PJ + (row0 + 16 * j + lc) * PW + C_HG + hd * 128 + 16 * w + 4 * g;
;             const u32x2 gv = gv_[j];
;             u32x2 wv; wv.x = pk2(oo[j][0] * rstd * nw[0] * siluf(bflo(gv.x)), oo[j][1] * rstd * nw[1] * siluf(bfhi(gv.x)));
;             wv.y = pk2(oo[j][2] * rstd * nw[2] * siluf(bflo(gv.y)), oo[j][3] * rstd * nw[3] * siluf(bfhi(gv.y)));
;             if (dost) *(u32x2*)gp = wv;
;         }
.LBB0_871:
	s_or_b64 exec, exec, s[4:5]
	v_lshlrev_b32_e32 v58, 2, v195
	v_lshl_add_u64 v[12:13], v[188:189], 2, v[164:165]
	s_waitcnt lgkmcnt(0)
	v_lshlrev_b32_e32 v14, 2, v58
	v_mov_b32_e32 v15, v16
	v_lshl_add_u64 v[12:13], v[12:13], 0, v[14:15]
	s_barrier
	global_load_dwordx4 v[12:15], v[12:13], off
	v_lshl_add_u32 v17, v17, 2, 0
	v_add_u32_e32 v17, 0x26000, v17
	ds_read2st64_b32 v[72:73], v17 offset1:2
	ds_read2st64_b32 v[76:77], v17 offset0:4 offset1:6
	ds_read2st64_b32 v[78:79], v17 offset0:8 offset1:10
	ds_read2st64_b32 v[80:81], v17 offset0:12 offset1:14
	s_nop 0
	s_nop 0
	s_nop 0
	s_mov_b32 s22, 0xf800000
	s_waitcnt lgkmcnt(3)
	v_add_f32_e32 v36, 0, v72
	v_add_f32_e32 v36, v36, v73
	s_waitcnt lgkmcnt(2)
	v_add_f32_e32 v36, v36, v76
	v_add_f32_e32 v36, v36, v77
	s_waitcnt lgkmcnt(1)
	v_add_f32_e32 v36, v36, v78
	v_add_f32_e32 v36, v36, v79
	s_waitcnt lgkmcnt(0)
	v_add_f32_e32 v36, v36, v80
	v_add_f32_e32 v36, v36, v81
	v_fmamk_f32 v36, v36, 0x3c000000, v234
	v_mul_f32_e32 v37, 0x4f800000, v36
	v_cmp_gt_f32_e32 vcc, s22, v36
	v_lshlrev_b32_e32 v32, 16, v191
	v_and_b32_e32 v33, 0xffff0000, v191
	v_cndmask_b32_e32 v50, v36, v37, vcc
	v_sqrt_f32_e32 v51, v50
	v_mul_f32_e32 v59, 0xbfb8aa3b, v32
	v_mul_f32_e32 v60, 0xbfb8aa3b, v33
	v_exp_f32_e32 v59, v59
	v_add_u32_e32 v52, -1, v51
	v_add_u32_e32 v53, 1, v51
	v_fma_f32 v54, -v52, v51, v50
	v_fma_f32 v55, -v53, v51, v50
	v_cmp_ge_f32_e64 s[40:41], 0, v54
	v_exp_f32_e32 v60, v60
	v_add_f32_e32 v59, 1.0, v59
	v_cndmask_b32_e64 v51, v51, v52, s[40:41]
	v_cmp_lt_f32_e64 s[40:41], 0, v55
	v_add_f32_e32 v60, 1.0, v60
	v_rcp_f32_e32 v36, v59
	v_cndmask_b32_e64 v51, v51, v53, s[40:41]
	v_mul_f32_e32 v52, 0x37800000, v51
	v_cndmask_b32_e32 v51, v51, v52, vcc
	v_cmp_class_f32_e32 vcc, v50, v235
	v_rcp_f32_e32 v37, v60
	v_lshlrev_b32_e32 v30, 16, v190
	v_cndmask_b32_e32 v50, v51, v50, vcc
	v_div_scale_f32 v51, s[4:5], v50, v50, 1.0
	v_rcp_f32_e32 v52, v51
	v_and_b32_e32 v31, 0xffff0000, v190
	v_mul_f32_e32 v56, 0xbfb8aa3b, v30
	v_mul_f32_e32 v57, 0xbfb8aa3b, v31
	v_exp_f32_e32 v56, v56
	v_exp_f32_e32 v57, v57
	v_pk_mul_f32 v[32:33], v[36:37], v[32:33]
	v_fma_f32 v37, -v51, v52, 1.0
	v_div_scale_f32 v36, vcc, 1.0, v50, 1.0
	v_fmac_f32_e32 v52, v37, v52
	v_mul_f32_e32 v37, v36, v52
	v_fma_f32 v53, -v51, v37, v36
	v_add_f32_e32 v56, 1.0, v56
	v_add_f32_e32 v57, 1.0, v57
	v_fmac_f32_e32 v37, v53, v52
	v_rcp_f32_e32 v56, v56
	v_rcp_f32_e32 v57, v57
	v_fma_f32 v36, -v51, v37, v36
	v_div_fmas_f32 v36, v36, v52, v37
	v_div_fixup_f32 v36, v36, v50, 1.0
	v_pk_mul_f32 v[50:51], v[110:111], v[36:37] op_sel_hi:[1,0]
	v_pk_mul_f32 v[30:31], v[56:57], v[30:31]
	v_pk_mul_f32 v[36:37], v[112:113], v[36:37] op_sel_hi:[1,0]
	v_lshl_add_u64 v[34:35], v[192:193], 0, s[96:97]
	v_lshl_add_u64 v[34:35], v[188:189], 1, v[34:35]
	s_waitcnt vmcnt(0)
	v_pk_mul_f32 v[50:51], v[12:13], v[50:51]
	v_pk_mul_f32 v[36:37], v[14:15], v[36:37]
	v_pk_mul_f32 v[30:31], v[30:31], v[50:51]
	v_pk_mul_f32 v[32:33], v[32:33], v[36:37]
	v_cvt_pk_bf16_f32 v36, v30, v31
	v_lshlrev_b32_e32 v30, 1, v58
	v_mov_b32_e32 v31, v16
	v_lshl_add_u64 v[30:31], v[34:35], 0, v[30:31]
	v_cvt_pk_bf16_f32 v37, v32, v33
	v_add_co_u32_e32 v32, vcc, 0x1000, v30
	s_nop 1
	v_addc_co_u32_e32 v33, vcc, 0, v31, vcc
	s_and_b64 vcc, exec, s[38:39]
	global_store_dwordx2 v[32:33], v[36:37], off
	s_cbranch_vccnz .LBB0_873
	ds_read2_b32 v[58:59], v17 offset0:16 offset1:32
	ds_read2_b32 v[82:83], v17 offset0:112 offset1:144
	v_and_b32_e32 v61, 0xffff0000, v186
	s_mov_b32 s3, 0x43000
	s_waitcnt lgkmcnt(1)
	v_add_f32_e32 v34, 0, v58
	s_waitcnt lgkmcnt(0)
	v_add_f32_e32 v34, v34, v83
	v_add_u32_e32 v33, 0x400, v17
	ds_read2_b32 v[52:53], v33 offset0:16 offset1:32
	v_add_u32_e32 v58, 0x800, v17
	ds_read2_b32 v[84:85], v58 offset0:16 offset1:32
	s_waitcnt lgkmcnt(1)
	v_add_f32_e32 v36, v34, v52
	ds_read2_b32 v[34:35], v33 offset0:112 offset1:144
	ds_read2_b32 v[86:87], v58 offset0:112 offset1:144
	s_waitcnt lgkmcnt(1)
	v_add_f32_e32 v35, v36, v35
	s_nop 0
	v_add_f32_e32 v35, v35, v84
	s_waitcnt lgkmcnt(0)
	v_add_f32_e32 v37, v35, v87
	v_add_u32_e32 v35, 0xc00, v17
	ds_read2_b32 v[90:91], v35 offset0:16 offset1:32
	ds_read2_b32 v[50:51], v35 offset0:112 offset1:144
	ds_read2_b32 v[92:93], v17 offset0:160 offset1:176
	s_waitcnt lgkmcnt(2)
	v_add_f32_e32 v37, v37, v90
	s_waitcnt lgkmcnt(1)
	v_add_f32_e32 v37, v37, v51
	v_fmamk_f32 v37, v37, 0x3c000000, v234
	v_cmp_gt_f32_e32 vcc, s22, v37
	v_mul_f32_e32 v51, 0x4f800000, v37
	s_nop 0
	v_cndmask_b32_e32 v37, v37, v51, vcc
	v_sqrt_f32_e32 v51, v37
	s_nop 0
	v_add_u32_e32 v52, -1, v51
	v_fma_f32 v54, -v52, v51, v37
	v_cmp_ge_f32_e64 s[38:39], 0, v54
	v_add_u32_e32 v54, 1, v51
	s_nop 0
	v_cndmask_b32_e64 v52, v51, v52, s[38:39]
	v_fma_f32 v51, -v54, v51, v37
	v_cmp_lt_f32_e64 s[38:39], 0, v51
	s_nop 1
	v_cndmask_b32_e64 v51, v52, v54, s[38:39]
	v_mul_f32_e32 v52, 0x37800000, v51
	v_cndmask_b32_e32 v51, v51, v52, vcc
	v_cmp_class_f32_e32 vcc, v37, v235
	s_nop 1
	v_cndmask_b32_e32 v37, v51, v37, vcc
	v_div_scale_f32 v51, s[4:5], v37, v37, 1.0
	v_rcp_f32_e32 v52, v51
	s_nop 0
	v_fma_f32 v54, -v51, v52, 1.0
	v_fmac_f32_e32 v52, v54, v52
	v_div_scale_f32 v54, vcc, 1.0, v37, 1.0
	v_mul_f32_e32 v56, v54, v52
	v_fma_f32 v60, -v51, v56, v54
	v_fmac_f32_e32 v56, v60, v52
	v_fma_f32 v51, -v51, v56, v54
	v_div_fmas_f32 v51, v51, v52, v56
	v_lshlrev_b32_e32 v60, 16, v186
	v_div_fixup_f32 v52, v51, v37, 1.0
	v_mul_f32_e32 v37, 0xbfb8aa3b, v60
	v_exp_f32_e32 v37, v37
	v_pk_mul_f32 v[46:47], v[46:47], v[52:53] op_sel_hi:[1,0]
	v_pk_mul_f32 v[48:49], v[48:49], v[52:53] op_sel_hi:[1,0]
	v_pk_mul_f32 v[46:47], v[12:13], v[46:47]
	v_add_f32_e32 v37, 1.0, v37
	v_rcp_f32_e32 v62, v37
	v_mul_f32_e32 v37, 0xbfb8aa3b, v61
	v_exp_f32_e32 v37, v37
	v_pk_mul_f32 v[48:49], v[14:15], v[48:49]
	v_lshlrev_b32_e32 v56, 16, v184
	v_add_f32_e32 v37, 1.0, v37
	v_rcp_f32_e32 v63, v37
	s_nop 0
	v_pk_mul_f32 v[60:61], v[62:63], v[60:61]
	s_nop 0
	v_pk_mul_f32 v[46:47], v[60:61], v[46:47]
	v_lshlrev_b32_e32 v60, 16, v187
	v_mul_f32_e32 v37, 0xbfb8aa3b, v60
	v_exp_f32_e32 v37, v37
	v_and_b32_e32 v61, 0xffff0000, v187
	v_cvt_pk_bf16_f32 v46, v46, v47
	v_add_f32_e32 v37, 1.0, v37
	v_rcp_f32_e32 v62, v37
	v_mul_f32_e32 v37, 0xbfb8aa3b, v61
	v_exp_f32_e32 v37, v37
	s_nop 0
	v_add_f32_e32 v37, 1.0, v37
	v_rcp_f32_e32 v63, v37
	v_add_f32_e32 v37, 0, v59
	v_pk_mul_f32 v[60:61], v[62:63], v[60:61]
	s_nop 0
	v_pk_mul_f32 v[48:49], v[60:61], v[48:49]
	s_nop 0
	v_cvt_pk_bf16_f32 v47, v48, v49
	v_add_co_u32_e32 v48, vcc, s3, v30
	s_mov_b32 s3, 0x85000
	s_nop 0
	v_addc_co_u32_e32 v49, vcc, 0, v31, vcc
	global_store_dwordx2 v[48:49], v[46:47], off
	s_nop 0
	ds_read2_b32 v[46:47], v35 offset0:160 offset1:176
	ds_read2_b32 v[94:95], v33 offset0:160 offset1:176
	s_waitcnt lgkmcnt(2)
; __device__ __forceinline__ unsigned pk2(float lo, float hi) { f32x2_t v = {lo, hi}; bf16x2_t b = __builtin_convertvector(v, bf16x2_t); return __builtin_bit_cast(unsigned, b); }
; __device__ __forceinline__ float siluf(float x) { return x * __builtin_amdgcn_rcpf(1.0f + __expf(-x)); }
; __device__ __forceinline__ void hg_passB(const Ptrs& P, int l, int b, int hd, int ch, unsigned char* lds, int tid, bool dost) {
;     ...
;     const f32x4 nw = *(const f32x4*)(P.hg_norm_w + l * 128 + 16 * w + 4 * g);
; #pragma unroll
;     for (int j = 0; j < 8; ++j) {
;         if (j < nsub) {
;             float tot = 0.f;
; #pragma unroll
;             for (int ww = 0; ww < 8; ++ww) tot += SSQ[ww * 128 + 16 * j + lc];
;             const float rstd = 1.0f / sqrtf(tot * (1.0f / 128.0f) + EPS);
;             bf16_t* gp = PJ + (row0 + 16 * j + lc) * PW + C_HG + hd * 128 + 16 * w + 4 * g;
;             const u32x2 gv = gv_[j];
;             u32x2 wv; wv.x = pk2(oo[j][0] * rstd * nw[0] * siluf(bflo(gv.x)), oo[j][1] * rstd * nw[1] * siluf(bfhi(gv.x)));
;             wv.y = pk2(oo[j][2] * rstd * nw[2] * siluf(bflo(gv.y)), oo[j][3] * rstd * nw[3] * siluf(bfhi(gv.y)));
;             if (dost) *(u32x2*)gp = wv;
;         }
	v_add_f32_e32 v37, v37, v92
	v_add_f32_e32 v37, v37, v53
	s_nop 0
	s_waitcnt lgkmcnt(0)
	v_add_f32_e32 v37, v37, v94
	v_add_f32_e32 v37, v37, v85
	ds_read2_b32 v[54:55], v58 offset0:160 offset1:176
	s_waitcnt lgkmcnt(0)
	v_add_f32_e32 v37, v37, v54
	v_add_f32_e32 v37, v37, v91
	v_add_f32_e32 v37, v37, v46
	v_fmamk_f32 v37, v37, 0x3c000000, v234
	v_cmp_gt_f32_e32 vcc, s22, v37
	v_mul_f32_e32 v46, 0x4f800000, v37
	v_and_b32_e32 v57, 0xffff0000, v184
	v_cndmask_b32_e32 v37, v37, v46, vcc
	v_sqrt_f32_e32 v46, v37
	s_nop 0
	v_add_u32_e32 v48, -1, v46
	v_fma_f32 v51, -v48, v46, v37
	v_cmp_ge_f32_e64 s[38:39], 0, v51
	v_add_u32_e32 v51, 1, v46
	s_nop 0
	v_cndmask_b32_e64 v48, v46, v48, s[38:39]
	v_fma_f32 v46, -v51, v46, v37
	v_cmp_lt_f32_e64 s[38:39], 0, v46
	s_nop 1
	v_cndmask_b32_e64 v46, v48, v51, s[38:39]
	v_mul_f32_e32 v48, 0x37800000, v46
	v_cndmask_b32_e32 v46, v46, v48, vcc
	v_cmp_class_f32_e32 vcc, v37, v235
	s_nop 1
	v_cndmask_b32_e32 v37, v46, v37, vcc
	v_div_scale_f32 v46, s[4:5], v37, v37, 1.0
	v_rcp_f32_e32 v48, v46
	s_nop 0
	v_fma_f32 v51, -v46, v48, 1.0
	v_fmac_f32_e32 v48, v51, v48
	v_div_scale_f32 v51, vcc, 1.0, v37, 1.0
	v_mul_f32_e32 v52, v51, v48
	v_fma_f32 v54, -v46, v52, v51
	v_fmac_f32_e32 v52, v54, v48
	v_fma_f32 v46, -v46, v52, v51
	v_div_fmas_f32 v46, v46, v48, v52
	v_div_fixup_f32 v46, v46, v37, 1.0
	v_mul_f32_e32 v37, 0xbfb8aa3b, v56
	v_exp_f32_e32 v37, v37
	v_pk_mul_f32 v[42:43], v[42:43], v[46:47] op_sel_hi:[1,0]
	v_pk_mul_f32 v[44:45], v[44:45], v[46:47] op_sel_hi:[1,0]
	v_pk_mul_f32 v[42:43], v[12:13], v[42:43]
	v_add_f32_e32 v37, 1.0, v37
	v_rcp_f32_e32 v60, v37
	v_mul_f32_e32 v37, 0xbfb8aa3b, v57
	v_exp_f32_e32 v37, v37
	v_pk_mul_f32 v[44:45], v[14:15], v[44:45]
	v_add_f32_e32 v37, 1.0, v37
	v_rcp_f32_e32 v61, v37
	s_nop 0
	v_pk_mul_f32 v[56:57], v[60:61], v[56:57]
	s_nop 0
	v_pk_mul_f32 v[42:43], v[56:57], v[42:43]
	v_lshlrev_b32_e32 v56, 16, v185
	v_mul_f32_e32 v37, 0xbfb8aa3b, v56
	v_exp_f32_e32 v37, v37
	v_and_b32_e32 v57, 0xffff0000, v185
	v_cvt_pk_bf16_f32 v42, v42, v43
	v_add_f32_e32 v37, 1.0, v37
	v_rcp_f32_e32 v60, v37
	v_mul_f32_e32 v37, 0xbfb8aa3b, v57
	v_exp_f32_e32 v37, v37
	s_nop 0
	v_add_f32_e32 v37, 1.0, v37
	v_rcp_f32_e32 v61, v37
	s_nop 0
	v_pk_mul_f32 v[56:57], v[60:61], v[56:57]
	s_nop 0
	v_pk_mul_f32 v[44:45], v[56:57], v[44:45]
	ds_read2_b32 v[56:57], v17 offset0:48 offset1:64
	v_cvt_pk_bf16_f32 v43, v44, v45
	v_add_co_u32_e32 v44, vcc, s3, v30
	s_mov_b32 s3, 0xc7000
	s_nop 0
	v_addc_co_u32_e32 v45, vcc, 0, v31, vcc
	global_store_dwordx2 v[44:45], v[42:43], off
	ds_read2_b32 v[42:43], v33 offset0:48 offset1:64
	ds_read2_b32 v[96:97], v58 offset0:48 offset1:64
	ds_read2_b32 v[98:99], v35 offset0:48 offset1:64
	ds_read2_b32 v[100:101], v17 offset0:192 offset1:208
	s_waitcnt lgkmcnt(4)
	v_add_f32_e32 v37, 0, v56
	v_add_f32_e32 v37, v37, v93
	s_nop 0
	s_waitcnt lgkmcnt(3)
	v_add_f32_e32 v37, v37, v42
	v_add_f32_e32 v37, v37, v95
	s_waitcnt lgkmcnt(2)
	v_add_f32_e32 v37, v37, v96
	v_add_f32_e32 v37, v37, v55
	s_waitcnt lgkmcnt(1)
	v_add_f32_e32 v37, v37, v98
	v_add_f32_e32 v37, v37, v47
	v_fmamk_f32 v37, v37, 0x3c000000, v234
	v_cmp_gt_f32_e32 vcc, s22, v37
	v_mul_f32_e32 v42, 0x4f800000, v37
	s_nop 0
	v_cndmask_b32_e32 v37, v37, v42, vcc
	v_sqrt_f32_e32 v42, v37
	s_nop 0
	v_add_u32_e32 v44, -1, v42
	v_fma_f32 v46, -v44, v42, v37
	v_cmp_ge_f32_e64 s[38:39], 0, v46
	v_add_u32_e32 v46, 1, v42
	s_nop 0
	v_cndmask_b32_e64 v44, v42, v44, s[38:39]
	v_fma_f32 v42, -v46, v42, v37
	v_cmp_lt_f32_e64 s[38:39], 0, v42
	s_nop 1
	v_cndmask_b32_e64 v42, v44, v46, s[38:39]
	v_mul_f32_e32 v44, 0x37800000, v42
	v_cndmask_b32_e32 v42, v42, v44, vcc
	v_cmp_class_f32_e32 vcc, v37, v235
	s_nop 1
	v_cndmask_b32_e32 v37, v42, v37, vcc
	v_div_scale_f32 v42, s[4:5], v37, v37, 1.0
	v_rcp_f32_e32 v44, v42
	s_nop 0
	v_fma_f32 v46, -v42, v44, 1.0
	v_fmac_f32_e32 v44, v46, v44
	v_div_scale_f32 v46, vcc, 1.0, v37, 1.0
	v_mul_f32_e32 v47, v46, v44
	v_fma_f32 v48, -v42, v47, v46
	v_fmac_f32_e32 v47, v48, v44
	v_fma_f32 v42, -v42, v47, v46
	v_div_fmas_f32 v42, v42, v44, v47
	v_lshlrev_b32_e32 v46, 16, v182
	v_div_fixup_f32 v42, v42, v37, 1.0
	v_mul_f32_e32 v37, 0xbfb8aa3b, v46
	v_exp_f32_e32 v37, v37
	v_and_b32_e32 v47, 0xffff0000, v182
	v_pk_mul_f32 v[38:39], v[38:39], v[42:43] op_sel_hi:[1,0]
	v_pk_mul_f32 v[40:41], v[40:41], v[42:43] op_sel_hi:[1,0]
	v_add_f32_e32 v37, 1.0, v37
	v_rcp_f32_e32 v52, v37
	v_mul_f32_e32 v37, 0xbfb8aa3b, v47
	v_exp_f32_e32 v37, v37
	v_pk_mul_f32 v[38:39], v[12:13], v[38:39]
	v_pk_mul_f32 v[40:41], v[14:15], v[40:41]
	v_add_f32_e32 v37, 1.0, v37
	v_rcp_f32_e32 v53, v37
	s_nop 0
	v_pk_mul_f32 v[46:47], v[52:53], v[46:47]
	s_nop 0
	v_pk_mul_f32 v[38:39], v[46:47], v[38:39]
	v_lshlrev_b32_e32 v46, 16, v183
	v_mul_f32_e32 v37, 0xbfb8aa3b, v46
	v_exp_f32_e32 v37, v37
	v_and_b32_e32 v47, 0xffff0000, v183
	v_cvt_pk_bf16_f32 v38, v38, v39
	v_add_f32_e32 v37, 1.0, v37
	v_rcp_f32_e32 v52, v37
	v_mul_f32_e32 v37, 0xbfb8aa3b, v47
	v_exp_f32_e32 v37, v37
	s_nop 0
	v_add_f32_e32 v37, 1.0, v37
	v_rcp_f32_e32 v53, v37
	v_add_f32_e32 v37, 0, v57
	v_pk_mul_f32 v[46:47], v[52:53], v[46:47]
	s_nop 0
	v_pk_mul_f32 v[40:41], v[46:47], v[40:41]
	v_and_b32_e32 v47, 0xffff0000, v180
	v_cvt_pk_bf16_f32 v39, v40, v41
	v_add_co_u32_e32 v40, vcc, s3, v30
	s_mov_b32 s3, 0x109000
	s_nop 0
	v_addc_co_u32_e32 v41, vcc, 0, v31, vcc
	global_store_dwordx2 v[40:41], v[38:39], off
	s_nop 0
	ds_read2_b32 v[38:39], v35 offset0:192 offset1:208
	ds_read2_b32 v[102:103], v33 offset0:192 offset1:208
	s_waitcnt lgkmcnt(2)
	v_add_f32_e32 v37, v37, v100
	v_add_f32_e32 v37, v37, v43
	s_nop 0
	s_waitcnt lgkmcnt(0)
; __device__ __forceinline__ unsigned pk2(float lo, float hi) { f32x2_t v = {lo, hi}; bf16x2_t b = __builtin_convertvector(v, bf16x2_t); return __builtin_bit_cast(unsigned, b); }
; __device__ __forceinline__ float siluf(float x) { return x * __builtin_amdgcn_rcpf(1.0f + __expf(-x)); }
; __device__ __forceinline__ void hg_passB(const Ptrs& P, int l, int b, int hd, int ch, unsigned char* lds, int tid, bool dost) {
;     ...
;     const f32x4 nw = *(const f32x4*)(P.hg_norm_w + l * 128 + 16 * w + 4 * g);
; #pragma unroll
;     for (int j = 0; j < 8; ++j) {
;         if (j < nsub) {
;             float tot = 0.f;
; #pragma unroll
;             for (int ww = 0; ww < 8; ++ww) tot += SSQ[ww * 128 + 16 * j + lc];
;             const float rstd = 1.0f / sqrtf(tot * (1.0f / 128.0f) + EPS);
;             bf16_t* gp = PJ + (row0 + 16 * j + lc) * PW + C_HG + hd * 128 + 16 * w + 4 * g;
;             const u32x2 gv = gv_[j];
;             u32x2 wv; wv.x = pk2(oo[j][0] * rstd * nw[0] * siluf(bflo(gv.x)), oo[j][1] * rstd * nw[1] * siluf(bfhi(gv.x)));
;             wv.y = pk2(oo[j][2] * rstd * nw[2] * siluf(bflo(gv.y)), oo[j][3] * rstd * nw[3] * siluf(bfhi(gv.y)));
;             if (dost) *(u32x2*)gp = wv;
;         }
	v_add_f32_e32 v37, v37, v102
	v_add_f32_e32 v37, v37, v97
	ds_read2_b32 v[44:45], v58 offset0:192 offset1:208
	s_waitcnt lgkmcnt(0)
	v_add_f32_e32 v37, v37, v44
	v_add_f32_e32 v37, v37, v99
	v_add_f32_e32 v37, v37, v38
	v_fmamk_f32 v37, v37, 0x3c000000, v234
	v_cmp_gt_f32_e32 vcc, s22, v37
	v_mul_f32_e32 v38, 0x4f800000, v37
	s_nop 0
	v_cndmask_b32_e32 v37, v37, v38, vcc
	v_sqrt_f32_e32 v38, v37
	s_nop 0
	v_add_u32_e32 v40, -1, v38
	v_fma_f32 v42, -v40, v38, v37
	v_cmp_ge_f32_e64 s[38:39], 0, v42
	v_add_u32_e32 v42, 1, v38
	s_nop 0
	v_cndmask_b32_e64 v40, v38, v40, s[38:39]
	v_fma_f32 v38, -v42, v38, v37
	v_cmp_lt_f32_e64 s[38:39], 0, v38
	s_nop 1
	v_cndmask_b32_e64 v38, v40, v42, s[38:39]
	v_mul_f32_e32 v40, 0x37800000, v38
	v_cndmask_b32_e32 v38, v38, v40, vcc
	v_cmp_class_f32_e32 vcc, v37, v235
	s_nop 1
	v_cndmask_b32_e32 v37, v38, v37, vcc
	v_div_scale_f32 v38, s[4:5], v37, v37, 1.0
	v_rcp_f32_e32 v40, v38
	s_nop 0
	v_fma_f32 v42, -v38, v40, 1.0
	v_fmac_f32_e32 v40, v42, v40
	v_div_scale_f32 v42, vcc, 1.0, v37, 1.0
	v_mul_f32_e32 v44, v42, v40
	v_fma_f32 v46, -v38, v44, v42
	v_fmac_f32_e32 v44, v46, v40
	v_fma_f32 v38, -v38, v44, v42
	v_div_fmas_f32 v38, v38, v40, v44
	v_lshlrev_b32_e32 v46, 16, v180
	v_div_fixup_f32 v38, v38, v37, 1.0
	v_mul_f32_e32 v37, 0xbfb8aa3b, v46
	v_exp_f32_e32 v37, v37
	v_pk_mul_f32 v[26:27], v[26:27], v[38:39] op_sel_hi:[1,0]
	v_pk_mul_f32 v[28:29], v[28:29], v[38:39] op_sel_hi:[1,0]
	v_pk_mul_f32 v[26:27], v[12:13], v[26:27]
	v_add_f32_e32 v37, 1.0, v37
	v_rcp_f32_e32 v48, v37
	v_mul_f32_e32 v37, 0xbfb8aa3b, v47
	v_exp_f32_e32 v37, v37
	v_pk_mul_f32 v[28:29], v[14:15], v[28:29]
	v_add_f32_e32 v37, 1.0, v37
	v_rcp_f32_e32 v49, v37
	s_nop 0
	v_pk_mul_f32 v[46:47], v[48:49], v[46:47]
	s_nop 0
	v_pk_mul_f32 v[26:27], v[46:47], v[26:27]
	v_lshlrev_b32_e32 v46, 16, v181
	v_cvt_pk_bf16_f32 v26, v26, v27
	v_mul_f32_e32 v27, 0xbfb8aa3b, v46
	v_exp_f32_e32 v27, v27
	v_and_b32_e32 v47, 0xffff0000, v181
	v_add_f32_e32 v27, 1.0, v27
	v_rcp_f32_e32 v48, v27
	v_mul_f32_e32 v27, 0xbfb8aa3b, v47
	v_exp_f32_e32 v27, v27
	s_nop 0
	v_add_f32_e32 v27, 1.0, v27
	v_rcp_f32_e32 v49, v27
	s_nop 0
	v_pk_mul_f32 v[46:47], v[48:49], v[46:47]
	s_nop 0
	v_pk_mul_f32 v[28:29], v[46:47], v[28:29]
	ds_read2_b32 v[46:47], v17 offset0:80 offset1:96
	ds_read2_b32 v[104:105], v33 offset0:80 offset1:96
	v_cvt_pk_bf16_f32 v27, v28, v29
	v_add_co_u32_e32 v28, vcc, s3, v30
	s_mov_b32 s3, 0x14b000
	s_nop 0
	v_addc_co_u32_e32 v29, vcc, 0, v31, vcc
	global_store_dwordx2 v[28:29], v[26:27], off
	s_waitcnt lgkmcnt(1)
	v_add_f32_e32 v26, 0, v46
	v_add_f32_e32 v26, v26, v101
	s_nop 0
	s_waitcnt lgkmcnt(0)
	v_add_f32_e32 v26, v26, v104
	v_add_f32_e32 v28, v26, v103
	ds_read2_b32 v[26:27], v58 offset0:80 offset1:96
	ds_read2_b32 v[106:107], v35 offset0:80 offset1:96
	s_waitcnt lgkmcnt(1)
	v_add_f32_e32 v26, v28, v26
	s_nop 0
	v_add_f32_e32 v26, v26, v45
	s_waitcnt lgkmcnt(0)
	v_add_f32_e32 v26, v26, v106
	v_add_f32_e32 v26, v26, v39
	v_fmamk_f32 v26, v26, 0x3c000000, v234
	v_cmp_gt_f32_e32 vcc, s22, v26
	v_mul_f32_e32 v28, 0x4f800000, v26
	s_nop 0
	v_cndmask_b32_e32 v26, v26, v28, vcc
	v_sqrt_f32_e32 v28, v26
	s_nop 0
	v_add_u32_e32 v37, -1, v28
	v_fma_f32 v38, -v37, v28, v26
	v_cmp_ge_f32_e64 s[38:39], 0, v38
	v_add_u32_e32 v38, 1, v28
	s_nop 0
	v_cndmask_b32_e64 v37, v28, v37, s[38:39]
	v_fma_f32 v28, -v38, v28, v26
	v_cmp_lt_f32_e64 s[38:39], 0, v28
	s_nop 1
	v_cndmask_b32_e64 v28, v37, v38, s[38:39]
	v_mul_f32_e32 v37, 0x37800000, v28
	v_cndmask_b32_e32 v28, v28, v37, vcc
	v_cmp_class_f32_e32 vcc, v26, v235
	s_nop 1
	v_cndmask_b32_e32 v26, v28, v26, vcc
	v_div_scale_f32 v28, s[4:5], v26, v26, 1.0
	v_rcp_f32_e32 v37, v28
	s_nop 0
	v_fma_f32 v38, -v28, v37, 1.0
	v_fmac_f32_e32 v37, v38, v37
	v_div_scale_f32 v38, vcc, 1.0, v26, 1.0
	v_mul_f32_e32 v39, v38, v37
	v_fma_f32 v40, -v28, v39, v38
	v_fmac_f32_e32 v39, v40, v37
	v_fma_f32 v28, -v28, v39, v38
	v_div_fmas_f32 v28, v28, v37, v39
	v_lshlrev_b32_e32 v38, 16, v178
	v_div_fixup_f32 v26, v28, v26, 1.0
	v_mul_f32_e32 v28, 0xbfb8aa3b, v38
	v_exp_f32_e32 v28, v28
	v_and_b32_e32 v39, 0xffff0000, v178
	v_pk_mul_f32 v[22:23], v[22:23], v[26:27] op_sel_hi:[1,0]
	v_pk_mul_f32 v[24:25], v[24:25], v[26:27] op_sel_hi:[1,0]
	v_add_f32_e32 v28, 1.0, v28
	v_rcp_f32_e32 v42, v28
	v_mul_f32_e32 v28, 0xbfb8aa3b, v39
	v_exp_f32_e32 v28, v28
	v_pk_mul_f32 v[22:23], v[12:13], v[22:23]
	v_pk_mul_f32 v[24:25], v[14:15], v[24:25]
	v_add_f32_e32 v28, 1.0, v28
	v_rcp_f32_e32 v43, v28
	s_nop 0
	v_pk_mul_f32 v[38:39], v[42:43], v[38:39]
	s_nop 0
	v_pk_mul_f32 v[22:23], v[38:39], v[22:23]
	v_lshlrev_b32_e32 v38, 16, v179
	v_cvt_pk_bf16_f32 v22, v22, v23
	v_mul_f32_e32 v23, 0xbfb8aa3b, v38
	v_exp_f32_e32 v23, v23
	v_and_b32_e32 v39, 0xffff0000, v179
	v_add_f32_e32 v23, 1.0, v23
	v_rcp_f32_e32 v42, v23
	v_mul_f32_e32 v23, 0xbfb8aa3b, v39
	v_exp_f32_e32 v23, v23
	s_nop 0
	v_add_f32_e32 v23, 1.0, v23
	v_rcp_f32_e32 v43, v23
	s_nop 0
	v_pk_mul_f32 v[38:39], v[42:43], v[38:39]
	s_nop 0
	v_pk_mul_f32 v[24:25], v[38:39], v[24:25]
	v_lshlrev_b32_e32 v38, 16, v176
	v_cvt_pk_bf16_f32 v23, v24, v25
	v_add_co_u32_e32 v24, vcc, s3, v30
	v_and_b32_e32 v39, 0xffff0000, v176
	s_nop 0
	v_addc_co_u32_e32 v25, vcc, 0, v31, vcc
	global_store_dwordx2 v[24:25], v[22:23], off
	ds_read2_b32 v[22:23], v17 offset0:224 offset1:240
	ds_read2_b32 v[114:115], v33 offset0:224 offset1:240
	v_add_f32_e32 v24, 0, v47
	s_mov_b32 s3, 0x18d000
	s_waitcnt lgkmcnt(1)
; __device__ __forceinline__ unsigned pk2(float lo, float hi) { f32x2_t v = {lo, hi}; bf16x2_t b = __builtin_convertvector(v, bf16x2_t); return __builtin_bit_cast(unsigned, b); }
; __device__ __forceinline__ float siluf(float x) { return x * __builtin_amdgcn_rcpf(1.0f + __expf(-x)); }
; __device__ __forceinline__ void hg_passB(const Ptrs& P, int l, int b, int hd, int ch, unsigned char* lds, int tid, bool dost) {
;     ...
;     const f32x4 nw = *(const f32x4*)(P.hg_norm_w + l * 128 + 16 * w + 4 * g);
; #pragma unroll
;     for (int j = 0; j < 8; ++j) {
;         if (j < nsub) {
;             float tot = 0.f;
; #pragma unroll
;             for (int ww = 0; ww < 8; ++ww) tot += SSQ[ww * 128 + 16 * j + lc];
;             const float rstd = 1.0f / sqrtf(tot * (1.0f / 128.0f) + EPS);
;             bf16_t* gp = PJ + (row0 + 16 * j + lc) * PW + C_HG + hd * 128 + 16 * w + 4 * g;
;             const u32x2 gv = gv_[j];
;             u32x2 wv; wv.x = pk2(oo[j][0] * rstd * nw[0] * siluf(bflo(gv.x)), oo[j][1] * rstd * nw[1] * siluf(bfhi(gv.x)));
;             wv.y = pk2(oo[j][2] * rstd * nw[2] * siluf(bflo(gv.y)), oo[j][3] * rstd * nw[3] * siluf(bfhi(gv.y)));
;             if (dost) *(u32x2*)gp = wv;
;         }
	v_add_f32_e32 v17, v24, v22
	s_nop 0
	v_add_f32_e32 v17, v17, v105
	s_waitcnt lgkmcnt(0)
	v_add_f32_e32 v17, v17, v114
	v_add_f32_e32 v17, v17, v27
	ds_read2_b32 v[26:27], v58 offset0:224 offset1:240
	ds_read2_b32 v[116:117], v35 offset0:224 offset1:240
	s_waitcnt lgkmcnt(1)
	v_add_f32_e32 v17, v17, v26
	v_add_f32_e32 v17, v17, v107
	s_nop 0
	s_waitcnt lgkmcnt(0)
	v_add_f32_e32 v17, v17, v116
	v_fmamk_f32 v17, v17, 0x3c000000, v234
	v_cmp_gt_f32_e32 vcc, s22, v17
	v_mul_f32_e32 v22, 0x4f800000, v17
	s_nop 0
	v_cndmask_b32_e32 v17, v17, v22, vcc
	v_sqrt_f32_e32 v22, v17
	s_nop 0
	v_add_u32_e32 v24, -1, v22
	v_fma_f32 v26, -v24, v22, v17
	v_cmp_ge_f32_e64 s[38:39], 0, v26
	v_add_u32_e32 v26, 1, v22
	s_nop 0
	v_cndmask_b32_e64 v24, v22, v24, s[38:39]
	v_fma_f32 v22, -v26, v22, v17
	v_cmp_lt_f32_e64 s[38:39], 0, v22
	s_nop 1
	v_cndmask_b32_e64 v22, v24, v26, s[38:39]
	v_mul_f32_e32 v24, 0x37800000, v22
	v_cndmask_b32_e32 v22, v22, v24, vcc
	v_cmp_class_f32_e32 vcc, v17, v235
	s_nop 1
	v_cndmask_b32_e32 v17, v22, v17, vcc
	v_div_scale_f32 v22, s[4:5], v17, v17, 1.0
	v_rcp_f32_e32 v24, v22
	s_nop 0
	v_fma_f32 v26, -v22, v24, 1.0
	v_fmac_f32_e32 v24, v26, v24
	v_div_scale_f32 v26, vcc, 1.0, v17, 1.0
	v_mul_f32_e32 v28, v26, v24
	v_fma_f32 v33, -v22, v28, v26
	v_fmac_f32_e32 v28, v33, v24
	v_fma_f32 v22, -v22, v28, v26
	v_div_fmas_f32 v22, v22, v24, v28
	v_div_fixup_f32 v22, v22, v17, 1.0
	v_mul_f32_e32 v17, 0xbfb8aa3b, v38
	v_exp_f32_e32 v17, v17
	v_pk_mul_f32 v[18:19], v[18:19], v[22:23] op_sel_hi:[1,0]
	v_pk_mul_f32 v[20:21], v[20:21], v[22:23] op_sel_hi:[1,0]
	v_pk_mul_f32 v[18:19], v[12:13], v[18:19]
	v_add_f32_e32 v17, 1.0, v17
	v_rcp_f32_e32 v40, v17
	v_mul_f32_e32 v17, 0xbfb8aa3b, v39
	v_exp_f32_e32 v17, v17
	v_pk_mul_f32 v[20:21], v[14:15], v[20:21]
	v_add_f32_e32 v17, 1.0, v17
	v_rcp_f32_e32 v41, v17
	s_nop 0
	v_pk_mul_f32 v[38:39], v[40:41], v[38:39]
	s_nop 0
	v_pk_mul_f32 v[18:19], v[38:39], v[18:19]
	v_lshlrev_b32_e32 v38, 16, v177
	v_mul_f32_e32 v17, 0xbfb8aa3b, v38
	v_exp_f32_e32 v17, v17
	v_and_b32_e32 v39, 0xffff0000, v177
	v_cvt_pk_bf16_f32 v18, v18, v19
	v_add_f32_e32 v17, 1.0, v17
	v_rcp_f32_e32 v40, v17
	v_mul_f32_e32 v17, 0xbfb8aa3b, v39
	v_exp_f32_e32 v17, v17
	s_nop 0
	v_add_f32_e32 v17, 1.0, v17
	v_rcp_f32_e32 v41, v17
	v_add_f32_e32 v17, 0, v82
	v_add_f32_e32 v17, v17, v23
	v_add_f32_e32 v17, v17, v34
	v_add_f32_e32 v17, v17, v115
	v_add_f32_e32 v17, v17, v86
	v_pk_mul_f32 v[38:39], v[40:41], v[38:39]
	v_add_f32_e32 v17, v17, v27
	v_pk_mul_f32 v[20:21], v[38:39], v[20:21]
	v_add_f32_e32 v17, v17, v50
	v_cvt_pk_bf16_f32 v19, v20, v21
	v_add_co_u32_e32 v20, vcc, s3, v30
	v_add_f32_e32 v17, v17, v117
	s_nop 0
	v_addc_co_u32_e32 v21, vcc, 0, v31, vcc
	v_fmamk_f32 v17, v17, 0x3c000000, v234
	global_store_dwordx2 v[20:21], v[18:19], off
	v_cmp_gt_f32_e32 vcc, s22, v17
	v_mul_f32_e32 v18, 0x4f800000, v17
	s_nop 0
	v_cndmask_b32_e32 v17, v17, v18, vcc
	v_sqrt_f32_e32 v18, v17
	s_nop 0
	v_add_u32_e32 v19, -1, v18
	v_fma_f32 v20, -v19, v18, v17
	v_cmp_ge_f32_e64 s[38:39], 0, v20
	v_add_u32_e32 v20, 1, v18
	s_nop 0
	v_cndmask_b32_e64 v19, v18, v19, s[38:39]
	v_fma_f32 v18, -v20, v18, v17
	v_cmp_lt_f32_e64 s[38:39], 0, v18
	s_nop 1
	v_cndmask_b32_e64 v18, v19, v20, s[38:39]
	v_mul_f32_e32 v19, 0x37800000, v18
	v_cndmask_b32_e32 v18, v18, v19, vcc
	v_cmp_class_f32_e32 vcc, v17, v235
	s_nop 1
	v_cndmask_b32_e32 v17, v18, v17, vcc
	v_div_scale_f32 v18, s[4:5], v17, v17, 1.0
	v_rcp_f32_e32 v19, v18
	s_nop 0
	v_fma_f32 v20, -v18, v19, 1.0
	v_fmac_f32_e32 v19, v20, v19
	v_div_scale_f32 v20, vcc, 1.0, v17, 1.0
	v_mul_f32_e32 v21, v20, v19
	v_fma_f32 v22, -v18, v21, v20
	v_fmac_f32_e32 v21, v22, v19
	v_fma_f32 v18, -v18, v21, v20
	v_div_fmas_f32 v18, v18, v19, v21
	v_div_fixup_f32 v18, v18, v17, 1.0
	v_lshlrev_b32_e32 v20, 16, v174
	v_and_b32_e32 v21, 0xffff0000, v174
	v_pk_mul_f32 v[8:9], v[8:9], v[18:19] op_sel_hi:[1,0]
	v_mul_f32_e32 v17, 0xbfb8aa3b, v20
	v_pk_mul_f32 v[8:9], v[12:13], v[8:9]
	v_mul_f32_e32 v12, 0xbfb8aa3b, v21
	v_exp_f32_e32 v17, v17
	v_exp_f32_e32 v12, v12
	v_pk_mul_f32 v[10:11], v[10:11], v[18:19] op_sel_hi:[1,0]
	v_add_f32_e32 v17, 1.0, v17
	v_add_f32_e32 v12, 1.0, v12
	v_rcp_f32_e32 v22, v17
	v_rcp_f32_e32 v23, v12
	v_pk_mul_f32 v[10:11], v[14:15], v[10:11]
	v_pk_mul_f32 v[12:13], v[22:23], v[20:21]
	s_nop 0
	v_pk_mul_f32 v[8:9], v[12:13], v[8:9]
	v_lshlrev_b32_e32 v12, 16, v175
	v_cvt_pk_bf16_f32 v8, v8, v9
	v_mul_f32_e32 v9, 0xbfb8aa3b, v12
	v_exp_f32_e32 v9, v9
	v_and_b32_e32 v13, 0xffff0000, v175
	v_add_f32_e32 v9, 1.0, v9
	v_rcp_f32_e32 v20, v9
	v_mul_f32_e32 v9, 0xbfb8aa3b, v13
	v_exp_f32_e32 v9, v9
	s_nop 0
	v_add_f32_e32 v9, 1.0, v9
	v_rcp_f32_e32 v21, v9
	s_nop 0
	v_pk_mul_f32 v[12:13], v[20:21], v[12:13]
	s_nop 0
	v_pk_mul_f32 v[10:11], v[12:13], v[10:11]
	s_nop 0
	v_cvt_pk_bf16_f32 v9, v10, v11
	v_add_co_u32_e32 v10, vcc, 0x1cf000, v30
	s_nop 1
	v_addc_co_u32_e32 v11, vcc, 0, v31, vcc
	global_store_dwordx2 v[10:11], v[8:9], off

; __device__ __forceinline__ float siluf(float x) { return x * __builtin_amdgcn_rcpf(1.0f + __expf(-x)); }
; __device__ __forceinline__ float shx(float v, int o, int lane) { return __builtin_bit_cast(float, __builtin_amdgcn_ds_bpermute((lane ^ o) << 2, __builtin_bit_cast(int, v))); }
; __device__ __forceinline__ void ssd_passB(const Ptrs& P, int l, int b, int ch, int gg, unsigned char* lds, int tid, bool dost) {
;     ...
;             for (int pt = 0; pt < 4; ++pt) { const u32x2 zw = zwv[lti][pt];
;                 const float zf[4] = {bflo(zw.x), bfhi(zw.x), bflo(zw.y), bfhi(zw.y)};
; #pragma unroll
;                 for (int r = 0; r < 4; ++r) { const float xs = bf2f(Xt[sdz(hh * 64 + 16 * pt + 4 * g + r, li)]); const float y = o[pt][r] + xs * dsk; const float v = y * siluf(zf[r]); gz[lti][pt][r] = v; part += v * v; } }
;             part += shx(part, 16, lane); part += shx(part, 32, lane);
;             if (g == 0) SSQ[li * 4 + hh] = part;
.LBB0_997:
	s_or_b64 exec, exec, s[6:7]
	s_movk_i32 s3, 0x48
	v_bitop3_b32 v92, v196, v191, s3 bitop3:0x6c
	v_lshlrev_b32_e32 v92, 1, v92
	v_mul_u32_u24_e32 v98, 0x110, v196
	v_add3_u32 v99, 0, v92, v98
	ds_read_u16 v100, v99
	ds_read_u16 v101, v99 offset:272
	ds_read_u16 v102, v99 offset:544
	ds_read_u16 v103, v99 offset:816
	s_nop 0
	v_lshlrev_b32_e32 v92, 16, v186
	v_and_b32_e32 v93, 0xffff0000, v186
	v_mul_f32_e32 v94, 0xbfb8aa3b, v92
	v_exp_f32_e32 v94, v94
	s_waitcnt lgkmcnt(2)
	v_lshlrev_b32_e32 v97, 16, v101
	v_lshlrev_b32_e32 v96, 16, v100
	v_mul_f32_e32 v95, 0xbfb8aa3b, v93
	v_exp_f32_e32 v95, v95
	v_add_f32_e32 v94, 1.0, v94
	v_rcp_f32_e32 v94, v94
	v_lshlrev_b32_e32 v91, 16, v187
	v_add_f32_e32 v95, 1.0, v95
	v_rcp_f32_e32 v95, v95
	v_pk_fma_f32 v[86:87], v[120:121], v[96:97], v[86:87] op_sel_hi:[0,1,1]
	v_and_b32_e32 v90, 0xffff0000, v187
	v_mov_b32_e32 v97, v120
	v_pk_mul_f32 v[92:93], v[94:95], v[92:93]
	s_movk_i32 s3, 0x58
	v_pk_mul_f32 v[128:129], v[92:93], v[86:87]
	v_mul_f32_e32 v93, 0xbfb8aa3b, v91
	v_exp_f32_e32 v93, v93
	s_nop 0
	v_pk_mul_f32 v[86:87], v[128:129], v[128:129]
	v_add_f32_e32 v93, 1.0, v93
	v_rcp_f32_e32 v93, v93
	v_add_f32_e32 v86, v86, v87
	v_mul_f32_e32 v94, v93, v91
	v_mul_f32_e32 v93, 0xbfb8aa3b, v90
	v_exp_f32_e32 v93, v93
	s_nop 0
	s_waitcnt lgkmcnt(1)
	v_lshlrev_b32_e32 v92, 16, v102
	v_mul_f32_e32 v92, v120, v92
	v_add_f32_e32 v93, 1.0, v93
	v_rcp_f32_e32 v96, v93
	s_waitcnt lgkmcnt(0)
	v_lshlrev_b32_e32 v91, 16, v103
	v_pk_mul_f32 v[90:91], v[96:97], v[90:91]
	s_nop 0
	v_mov_b32_e32 v93, v91
	v_pk_add_f32 v[88:89], v[88:89], v[92:93]
	v_or_b32_e32 v92, 16, v196
	v_bitop3_b32 v92, v92, v191, s3 bitop3:0x6c
	v_lshlrev_b32_e32 v92, 1, v92
	v_mov_b32_e32 v95, v90
	v_add3_u32 v98, 0, v92, v98
	ds_read_u16 v104, v98 offset:4352
	ds_read_u16 v105, v98 offset:4624
	ds_read_u16 v106, v98 offset:4896
	ds_read_u16 v112, v98 offset:5168
	v_pk_mul_f32 v[130:131], v[94:95], v[88:89]
	s_nop 0
	s_nop 0
	v_lshlrev_b32_e32 v92, 16, v182
	v_and_b32_e32 v93, 0xffff0000, v182
	v_mul_f32_e32 v94, 0xbfb8aa3b, v92
	v_exp_f32_e32 v94, v94
	s_waitcnt lgkmcnt(2)
	v_lshlrev_b32_e32 v97, 16, v105
	v_lshlrev_b32_e32 v96, 16, v104
	v_mul_f32_e32 v95, 0xbfb8aa3b, v93
	v_exp_f32_e32 v95, v95
	v_add_f32_e32 v94, 1.0, v94
	v_rcp_f32_e32 v94, v94
	v_lshlrev_b32_e32 v91, 16, v183
	v_add_f32_e32 v95, 1.0, v95
	v_rcp_f32_e32 v95, v95
	v_pk_fma_f32 v[82:83], v[120:121], v[96:97], v[82:83] op_sel_hi:[0,1,1]
	v_and_b32_e32 v90, 0xffff0000, v183
	v_mov_b32_e32 v97, v120
	v_pk_mul_f32 v[92:93], v[94:95], v[92:93]
	s_movk_i32 s3, 0x68
	v_pk_mul_f32 v[134:135], v[92:93], v[82:83]
	v_mul_f32_e32 v93, 0xbfb8aa3b, v91
	v_exp_f32_e32 v93, v93
	s_nop 0
	v_pk_mul_f32 v[88:89], v[130:131], v[130:131]
	v_pk_mul_f32 v[82:83], v[134:135], v[134:135]
	v_add_f32_e32 v93, 1.0, v93
	v_rcp_f32_e32 v93, v93
	v_add_f32_e32 v86, v86, v88
	v_add_f32_e32 v86, v86, v89
	v_add_f32_e32 v82, v86, v82
	v_mul_f32_e32 v94, v93, v91
	v_mul_f32_e32 v93, 0xbfb8aa3b, v90
	v_exp_f32_e32 v93, v93
	s_nop 0
	s_waitcnt lgkmcnt(1)
	v_lshlrev_b32_e32 v92, 16, v106
	v_mul_f32_e32 v92, v120, v92
	v_add_f32_e32 v93, 1.0, v93
	v_rcp_f32_e32 v96, v93
	s_waitcnt lgkmcnt(0)
	v_lshlrev_b32_e32 v91, 16, v112
	v_mad_u32_u24 v98, v196, s26, v242
	v_add_f32_e32 v82, v82, v83
	v_pk_mul_f32 v[90:91], v[96:97], v[90:91]
	s_nop 0
	v_mov_b32_e32 v93, v91
	v_pk_add_f32 v[84:85], v[84:85], v[92:93]
	v_or_b32_e32 v92, 32, v196
	v_bitop3_b32 v92, v92, v191, s3 bitop3:0x6c
	v_mov_b32_e32 v95, v90
	v_lshl_add_u32 v92, v92, 1, 0
	v_pk_mul_f32 v[136:137], v[94:95], v[84:85]
	v_add_u32_e32 v95, v92, v98
	ds_read_u16 v113, v95
	v_mad_u32_u24 v99, v196, s26, v92
	ds_read_u16 v205, v99 offset:8976
	ds_read_u16 v206, v99 offset:9248
	ds_read_u16 v207, v99 offset:9520
	s_nop 0
	s_nop 0
	v_lshlrev_b32_e32 v92, 16, v178
	v_and_b32_e32 v93, 0xffff0000, v178
	v_mul_f32_e32 v94, 0xbfb8aa3b, v92
	s_waitcnt lgkmcnt(3)
; __device__ __forceinline__ float siluf(float x) { return x * __builtin_amdgcn_rcpf(1.0f + __expf(-x)); }
; __device__ __forceinline__ float shx(float v, int o, int lane) { return __builtin_bit_cast(float, __builtin_amdgcn_ds_bpermute((lane ^ o) << 2, __builtin_bit_cast(int, v))); }
; __device__ __forceinline__ void ssd_passB(const Ptrs& P, int l, int b, int ch, int gg, unsigned char* lds, int tid, bool dost) {
;     ...
;             for (int pt = 0; pt < 4; ++pt) { const u32x2 zw = zwv[lti][pt];
;                 const float zf[4] = {bflo(zw.x), bfhi(zw.x), bflo(zw.y), bfhi(zw.y)};
; #pragma unroll
;                 for (int r = 0; r < 4; ++r) { const float xs = bf2f(Xt[sdz(hh * 64 + 16 * pt + 4 * g + r, li)]); const float y = o[pt][r] + xs * dsk; const float v = y * siluf(zf[r]); gz[lti][pt][r] = v; part += v * v; } }
;             part += shx(part, 16, lane); part += shx(part, 32, lane);
;             if (g == 0) SSQ[li * 4 + hh] = part;
	v_lshlrev_b32_e32 v96, 16, v113
	v_mul_f32_e32 v95, 0xbfb8aa3b, v93
	v_exp_f32_e32 v94, v94
	v_exp_f32_e32 v95, v95
	s_waitcnt lgkmcnt(2)
	v_lshlrev_b32_e32 v97, 16, v205
	v_lshlrev_b32_e32 v91, 16, v179
	v_add_f32_e32 v94, 1.0, v94
	v_add_f32_e32 v95, 1.0, v95
	v_rcp_f32_e32 v94, v94
	v_rcp_f32_e32 v95, v95
	v_pk_fma_f32 v[78:79], v[120:121], v[96:97], v[78:79] op_sel_hi:[0,1,1]
	v_and_b32_e32 v90, 0xffff0000, v179
	v_mov_b32_e32 v97, v120
	v_pk_mul_f32 v[92:93], v[94:95], v[92:93]
	v_pk_mul_f32 v[84:85], v[136:137], v[136:137]
	v_pk_mul_f32 v[138:139], v[92:93], v[78:79]
	v_mul_f32_e32 v93, 0xbfb8aa3b, v91
	v_exp_f32_e32 v93, v93
	s_nop 0
	v_add_f32_e32 v82, v82, v84
	v_pk_mul_f32 v[78:79], v[138:139], v[138:139]
	v_add_f32_e32 v93, 1.0, v93
	v_rcp_f32_e32 v93, v93
	v_add_f32_e32 v82, v82, v85
	v_add_f32_e32 v78, v82, v78
	v_add_f32_e32 v78, v78, v79
	v_mul_f32_e32 v94, v93, v91
	v_mul_f32_e32 v93, 0xbfb8aa3b, v90
	v_exp_f32_e32 v93, v93
	s_nop 0
	s_waitcnt lgkmcnt(1)
	v_lshlrev_b32_e32 v92, 16, v206
	v_mul_f32_e32 v92, v120, v92
	v_add_f32_e32 v93, 1.0, v93
	v_rcp_f32_e32 v96, v93
	s_waitcnt lgkmcnt(0)
	v_lshlrev_b32_e32 v91, 16, v207
	v_pk_mul_f32 v[90:91], v[96:97], v[90:91]
	s_nop 0
	v_mov_b32_e32 v93, v91
	v_pk_add_f32 v[80:81], v[80:81], v[92:93]
	v_or_b32_e32 v92, 48, v196
	v_bitop3_b32 v92, v92, v191, s16 bitop3:0x6c
	v_mov_b32_e32 v95, v90
	v_lshl_add_u32 v92, v92, 1, 0
	v_pk_mul_f32 v[140:141], v[94:95], v[80:81]
	v_add_u32_e32 v95, v98, v92
	ds_read_u16 v208, v95 offset:4352
	v_mad_u32_u24 v98, v196, s26, v92
	ds_read_u16 v209, v98 offset:13328
	ds_read_u16 v211, v98 offset:13600
	ds_read_u16 v212, v98 offset:13872
	s_nop 0
	s_nop 0
	v_lshlrev_b32_e32 v92, 16, v156
	v_and_b32_e32 v93, 0xffff0000, v156
	v_mul_f32_e32 v94, 0xbfb8aa3b, v92
	s_waitcnt lgkmcnt(3)
	v_lshlrev_b32_e32 v96, 16, v208
	v_mul_f32_e32 v95, 0xbfb8aa3b, v93
	v_exp_f32_e32 v94, v94
	v_exp_f32_e32 v95, v95
	s_waitcnt lgkmcnt(2)
	v_lshlrev_b32_e32 v97, 16, v209
	v_lshlrev_b32_e32 v91, 16, v157
	v_add_f32_e32 v94, 1.0, v94
	v_add_f32_e32 v95, 1.0, v95
	v_rcp_f32_e32 v94, v94
	v_rcp_f32_e32 v95, v95
	v_pk_fma_f32 v[74:75], v[120:121], v[96:97], v[74:75] op_sel_hi:[0,1,1]
	v_and_b32_e32 v90, 0xffff0000, v157
	v_mov_b32_e32 v97, v120
	v_pk_mul_f32 v[92:93], v[94:95], v[92:93]
	v_pk_mul_f32 v[80:81], v[140:141], v[140:141]
	v_pk_mul_f32 v[142:143], v[92:93], v[74:75]
	v_mul_f32_e32 v93, 0xbfb8aa3b, v91
	v_exp_f32_e32 v93, v93
	s_nop 0
	v_add_f32_e32 v78, v78, v80
	v_pk_mul_f32 v[74:75], v[142:143], v[142:143]
	v_add_f32_e32 v93, 1.0, v93
	v_rcp_f32_e32 v93, v93
	v_add_f32_e32 v78, v78, v81
	v_add_f32_e32 v74, v78, v74
	v_add_f32_e32 v74, v74, v75
	v_mul_f32_e32 v94, v93, v91
	v_mul_f32_e32 v93, 0xbfb8aa3b, v90
	v_exp_f32_e32 v93, v93
	s_nop 0
	s_waitcnt lgkmcnt(1)
	v_lshlrev_b32_e32 v92, 16, v211
	v_mul_f32_e32 v92, v120, v92
	v_add_f32_e32 v93, 1.0, v93
	v_rcp_f32_e32 v96, v93
	s_waitcnt lgkmcnt(0)
	v_lshlrev_b32_e32 v91, 16, v212
	v_pk_mul_f32 v[90:91], v[96:97], v[90:91]
	s_nop 0
	v_mov_b32_e32 v93, v91
	v_pk_add_f32 v[76:77], v[76:77], v[92:93]
	v_mov_b32_e32 v95, v90
	v_pk_mul_f32 v[144:145], v[94:95], v[76:77]
	s_nop 0
	v_pk_mul_f32 v[76:77], v[144:145], v[144:145]
	s_nop 0
	v_add_f32_e32 v74, v74, v76
	v_add_f32_e32 v74, v74, v77
	ds_bpermute_b32 v75, v195, v74
	s_waitcnt lgkmcnt(0)
	v_add_f32_e32 v74, v74, v75
	ds_bpermute_b32 v75, v117, v74
	s_and_saveexec_b64 s[6:7], s[40:41]
	s_cbranch_execz .LBB0_999
	s_waitcnt lgkmcnt(0)
	v_add_f32_e32 v74, v74, v75
	v_lshl_add_u32 v75, v191, 4, v115
	ds_write_b32 v75, v74

; __device__ __forceinline__ float siluf(float x) { return x * __builtin_amdgcn_rcpf(1.0f + __expf(-x)); }
; __device__ __forceinline__ float shx(float v, int o, int lane) { return __builtin_bit_cast(float, __builtin_amdgcn_ds_bpermute((lane ^ o) << 2, __builtin_bit_cast(int, v))); }
; __device__ __forceinline__ void ssd_passB(const Ptrs& P, int l, int b, int ch, int gg, unsigned char* lds, int tid, bool dost) {
;     ...
;             for (int pt = 0; pt < 4; ++pt) { const u32x2 zw = zwv[lti][pt];
;                 const float zf[4] = {bflo(zw.x), bfhi(zw.x), bflo(zw.y), bfhi(zw.y)};
; #pragma unroll
;                 for (int r = 0; r < 4; ++r) { const float xs = bf2f(Xt[sdz(hh * 64 + 16 * pt + 4 * g + r, li)]); const float y = o[pt][r] + xs * dsk; const float v = y * siluf(zf[r]); gz[lti][pt][r] = v; part += v * v; } }
;             part += shx(part, 16, lane); part += shx(part, 32, lane);
;             if (g == 0) SSQ[li * 4 + hh] = part;
.LBB0_1024:
	s_or_b64 exec, exec, s[4:5]
	s_movk_i32 s3, 0x48
	v_bitop3_b32 v92, v196, v190, s3 bitop3:0x6c
	v_lshlrev_b32_e32 v92, 1, v92
	v_mul_u32_u24_e32 v98, 0x110, v196
	v_add3_u32 v99, 0, v92, v98
	ds_read_u16 v100, v99
	ds_read_u16 v101, v99 offset:272
	ds_read_u16 v102, v99 offset:544
	ds_read_u16 v103, v99 offset:816
	s_nop 0
	v_lshlrev_b32_e32 v92, 16, v154
	v_and_b32_e32 v93, 0xffff0000, v154
	v_mul_f32_e32 v94, 0xbfb8aa3b, v92
	v_exp_f32_e32 v94, v94
	s_waitcnt lgkmcnt(2)
	v_lshlrev_b32_e32 v97, 16, v101
	v_lshlrev_b32_e32 v96, 16, v100
	v_mul_f32_e32 v95, 0xbfb8aa3b, v93
	v_exp_f32_e32 v95, v95
	v_add_f32_e32 v94, 1.0, v94
	v_rcp_f32_e32 v94, v94
	v_lshlrev_b32_e32 v91, 16, v155
	v_add_f32_e32 v95, 1.0, v95
	v_rcp_f32_e32 v95, v95
	v_pk_fma_f32 v[86:87], v[120:121], v[96:97], v[86:87] op_sel_hi:[0,1,1]
	v_and_b32_e32 v90, 0xffff0000, v155
	v_mov_b32_e32 v97, v120
	v_pk_mul_f32 v[92:93], v[94:95], v[92:93]
	s_movk_i32 s3, 0x58
	v_pk_mul_f32 v[154:155], v[92:93], v[86:87]
	v_mul_f32_e32 v93, 0xbfb8aa3b, v91
	v_exp_f32_e32 v93, v93
	s_nop 0
	v_pk_mul_f32 v[86:87], v[154:155], v[154:155]
	v_add_f32_e32 v93, 1.0, v93
	v_rcp_f32_e32 v93, v93
	v_add_f32_e32 v86, v86, v87
	v_mul_f32_e32 v94, v93, v91
	v_mul_f32_e32 v93, 0xbfb8aa3b, v90
	v_exp_f32_e32 v93, v93
	s_nop 0
	s_waitcnt lgkmcnt(1)
	v_lshlrev_b32_e32 v92, 16, v102
	v_mul_f32_e32 v92, v120, v92
	v_add_f32_e32 v93, 1.0, v93
	v_rcp_f32_e32 v96, v93
	s_waitcnt lgkmcnt(0)
	v_lshlrev_b32_e32 v91, 16, v103
	v_pk_mul_f32 v[90:91], v[96:97], v[90:91]
	s_nop 0
	v_mov_b32_e32 v93, v91
	v_pk_add_f32 v[88:89], v[88:89], v[92:93]
	v_or_b32_e32 v92, 16, v196
	v_bitop3_b32 v92, v92, v190, s3 bitop3:0x6c
	v_lshlrev_b32_e32 v92, 1, v92
	v_mov_b32_e32 v95, v90
	v_add3_u32 v98, 0, v92, v98
	ds_read_u16 v104, v98 offset:4352
	ds_read_u16 v105, v98 offset:4624
	ds_read_u16 v106, v98 offset:4896
	ds_read_u16 v112, v98 offset:5168
	v_pk_mul_f32 v[156:157], v[94:95], v[88:89]
	s_nop 0
	s_nop 0
	v_lshlrev_b32_e32 v92, 16, v174
	v_and_b32_e32 v93, 0xffff0000, v174
	v_mul_f32_e32 v94, 0xbfb8aa3b, v92
	v_exp_f32_e32 v94, v94
	s_waitcnt lgkmcnt(2)
	v_lshlrev_b32_e32 v97, 16, v105
	v_lshlrev_b32_e32 v96, 16, v104
	v_mul_f32_e32 v95, 0xbfb8aa3b, v93
	v_exp_f32_e32 v95, v95
	v_add_f32_e32 v94, 1.0, v94
	v_rcp_f32_e32 v94, v94
	v_lshlrev_b32_e32 v91, 16, v175
	v_add_f32_e32 v95, 1.0, v95
	v_rcp_f32_e32 v95, v95
	v_pk_fma_f32 v[82:83], v[120:121], v[96:97], v[82:83] op_sel_hi:[0,1,1]
	v_and_b32_e32 v90, 0xffff0000, v175
	v_mov_b32_e32 v97, v120
	v_pk_mul_f32 v[92:93], v[94:95], v[92:93]
	s_movk_i32 s3, 0x68
	v_pk_mul_f32 v[174:175], v[92:93], v[82:83]
	v_mul_f32_e32 v93, 0xbfb8aa3b, v91
	v_exp_f32_e32 v93, v93
	s_nop 0
	v_pk_mul_f32 v[88:89], v[156:157], v[156:157]
	v_pk_mul_f32 v[82:83], v[174:175], v[174:175]
	v_add_f32_e32 v93, 1.0, v93
	v_rcp_f32_e32 v93, v93
	v_add_f32_e32 v86, v86, v88
	v_add_f32_e32 v86, v86, v89
	v_add_f32_e32 v82, v86, v82
	v_mul_f32_e32 v94, v93, v91
	v_mul_f32_e32 v93, 0xbfb8aa3b, v90
	v_exp_f32_e32 v93, v93
	s_nop 0
	s_waitcnt lgkmcnt(1)
	v_lshlrev_b32_e32 v92, 16, v106
	v_mul_f32_e32 v92, v120, v92
	v_add_f32_e32 v93, 1.0, v93
	v_rcp_f32_e32 v96, v93
	s_waitcnt lgkmcnt(0)
	v_lshlrev_b32_e32 v91, 16, v112
	v_mad_u32_u24 v98, v196, s26, v242
	v_add_f32_e32 v82, v82, v83
	v_pk_mul_f32 v[90:91], v[96:97], v[90:91]
	s_nop 0
	v_mov_b32_e32 v93, v91
	v_pk_add_f32 v[84:85], v[84:85], v[92:93]
	v_or_b32_e32 v92, 32, v196
	v_bitop3_b32 v92, v92, v190, s3 bitop3:0x6c
	v_mov_b32_e32 v95, v90
	v_lshl_add_u32 v92, v92, 1, 0
	v_pk_mul_f32 v[178:179], v[94:95], v[84:85]
	v_add_u32_e32 v95, v92, v98
	ds_read_u16 v113, v95
	v_mad_u32_u24 v99, v196, s26, v92
	ds_read_u16 v204, v99 offset:8976
	ds_read_u16 v205, v99 offset:9248
	ds_read_u16 v206, v99 offset:9520
	s_nop 0
	s_nop 0
	v_lshlrev_b32_e32 v92, 16, v180
	v_and_b32_e32 v93, 0xffff0000, v180
	v_mul_f32_e32 v94, 0xbfb8aa3b, v92
	s_waitcnt lgkmcnt(3)
; __device__ __forceinline__ float siluf(float x) { return x * __builtin_amdgcn_rcpf(1.0f + __expf(-x)); }
; __device__ __forceinline__ float shx(float v, int o, int lane) { return __builtin_bit_cast(float, __builtin_amdgcn_ds_bpermute((lane ^ o) << 2, __builtin_bit_cast(int, v))); }
; __device__ __forceinline__ void ssd_passB(const Ptrs& P, int l, int b, int ch, int gg, unsigned char* lds, int tid, bool dost) {
;     ...
;             for (int pt = 0; pt < 4; ++pt) { const u32x2 zw = zwv[lti][pt];
;                 const float zf[4] = {bflo(zw.x), bfhi(zw.x), bflo(zw.y), bfhi(zw.y)};
; #pragma unroll
;                 for (int r = 0; r < 4; ++r) { const float xs = bf2f(Xt[sdz(hh * 64 + 16 * pt + 4 * g + r, li)]); const float y = o[pt][r] + xs * dsk; const float v = y * siluf(zf[r]); gz[lti][pt][r] = v; part += v * v; } }
;             part += shx(part, 16, lane); part += shx(part, 32, lane);
;             if (g == 0) SSQ[li * 4 + hh] = part;
	v_lshlrev_b32_e32 v96, 16, v113
	v_mul_f32_e32 v95, 0xbfb8aa3b, v93
	v_exp_f32_e32 v94, v94
	v_exp_f32_e32 v95, v95
	s_waitcnt lgkmcnt(2)
	v_lshlrev_b32_e32 v97, 16, v204
	v_lshlrev_b32_e32 v91, 16, v181
	v_add_f32_e32 v94, 1.0, v94
	v_add_f32_e32 v95, 1.0, v95
	v_rcp_f32_e32 v94, v94
	v_rcp_f32_e32 v95, v95
	v_pk_fma_f32 v[78:79], v[120:121], v[96:97], v[78:79] op_sel_hi:[0,1,1]
	v_and_b32_e32 v90, 0xffff0000, v181
	v_mov_b32_e32 v97, v120
	v_pk_mul_f32 v[92:93], v[94:95], v[92:93]
	v_pk_mul_f32 v[84:85], v[178:179], v[178:179]
	v_pk_mul_f32 v[180:181], v[92:93], v[78:79]
	v_mul_f32_e32 v93, 0xbfb8aa3b, v91
	v_exp_f32_e32 v93, v93
	s_nop 0
	v_add_f32_e32 v82, v82, v84
	v_pk_mul_f32 v[78:79], v[180:181], v[180:181]
	v_add_f32_e32 v93, 1.0, v93
	v_rcp_f32_e32 v93, v93
	v_add_f32_e32 v82, v82, v85
	v_add_f32_e32 v78, v82, v78
	v_add_f32_e32 v78, v78, v79
	v_mul_f32_e32 v94, v93, v91
	v_mul_f32_e32 v93, 0xbfb8aa3b, v90
	v_exp_f32_e32 v93, v93
	s_nop 0
	s_waitcnt lgkmcnt(1)
	v_lshlrev_b32_e32 v92, 16, v205
	v_mul_f32_e32 v92, v120, v92
	v_add_f32_e32 v93, 1.0, v93
	v_rcp_f32_e32 v96, v93
	s_waitcnt lgkmcnt(0)
	v_lshlrev_b32_e32 v91, 16, v206
	v_pk_mul_f32 v[90:91], v[96:97], v[90:91]
	s_nop 0
	v_mov_b32_e32 v93, v91
	v_pk_add_f32 v[80:81], v[80:81], v[92:93]
	v_or_b32_e32 v92, 48, v196
	v_bitop3_b32 v92, v92, v190, s16 bitop3:0x6c
	v_mov_b32_e32 v95, v90
	v_lshl_add_u32 v92, v92, 1, 0
	v_pk_mul_f32 v[182:183], v[94:95], v[80:81]
	v_add_u32_e32 v95, v98, v92
	ds_read_u16 v207, v95 offset:4352
	v_mad_u32_u24 v98, v196, s26, v92
	ds_read_u16 v208, v98 offset:13328
	ds_read_u16 v209, v98 offset:13600
	ds_read_u16 v211, v98 offset:13872
	s_nop 0
	s_nop 0
	v_lshlrev_b32_e32 v92, 16, v184
	v_and_b32_e32 v93, 0xffff0000, v184
	v_mul_f32_e32 v94, 0xbfb8aa3b, v92
	s_waitcnt lgkmcnt(3)
	v_lshlrev_b32_e32 v96, 16, v207
	v_mul_f32_e32 v95, 0xbfb8aa3b, v93
	v_exp_f32_e32 v94, v94
	v_exp_f32_e32 v95, v95
	s_waitcnt lgkmcnt(2)
	v_lshlrev_b32_e32 v97, 16, v208
	v_lshlrev_b32_e32 v91, 16, v185
	v_add_f32_e32 v94, 1.0, v94
	v_add_f32_e32 v95, 1.0, v95
	v_rcp_f32_e32 v94, v94
	v_rcp_f32_e32 v95, v95
	v_pk_fma_f32 v[74:75], v[120:121], v[96:97], v[74:75] op_sel_hi:[0,1,1]
	v_and_b32_e32 v90, 0xffff0000, v185
	v_mov_b32_e32 v97, v120
	v_pk_mul_f32 v[92:93], v[94:95], v[92:93]
	v_pk_mul_f32 v[80:81], v[182:183], v[182:183]
	v_pk_mul_f32 v[184:185], v[92:93], v[74:75]
	v_mul_f32_e32 v93, 0xbfb8aa3b, v91
	v_exp_f32_e32 v93, v93
	s_nop 0
	v_add_f32_e32 v78, v78, v80
	v_pk_mul_f32 v[74:75], v[184:185], v[184:185]
	v_add_f32_e32 v93, 1.0, v93
	v_rcp_f32_e32 v93, v93
	v_add_f32_e32 v78, v78, v81
	v_add_f32_e32 v74, v78, v74
	v_add_f32_e32 v74, v74, v75
	v_mul_f32_e32 v94, v93, v91
	v_mul_f32_e32 v93, 0xbfb8aa3b, v90
	v_exp_f32_e32 v93, v93
	s_nop 0
	s_waitcnt lgkmcnt(1)
	v_lshlrev_b32_e32 v92, 16, v209
	v_mul_f32_e32 v92, v120, v92
	v_add_f32_e32 v93, 1.0, v93
	v_rcp_f32_e32 v96, v93
	s_waitcnt lgkmcnt(0)
	v_lshlrev_b32_e32 v91, 16, v211
	v_pk_mul_f32 v[90:91], v[96:97], v[90:91]
	s_nop 0
	v_mov_b32_e32 v93, v91
	v_pk_add_f32 v[76:77], v[76:77], v[92:93]
	v_mov_b32_e32 v95, v90
	v_pk_mul_f32 v[186:187], v[94:95], v[76:77]
	s_nop 0
	v_pk_mul_f32 v[76:77], v[186:187], v[186:187]
	s_nop 0
	v_add_f32_e32 v74, v74, v76
	v_add_f32_e32 v74, v74, v77
	ds_bpermute_b32 v75, v195, v74
	s_waitcnt lgkmcnt(0)
	v_add_f32_e32 v74, v74, v75
	ds_bpermute_b32 v75, v117, v74
	s_and_saveexec_b64 s[4:5], s[40:41]
	s_cbranch_execz .LBB0_1026
	s_waitcnt lgkmcnt(0)
	v_add_f32_e32 v74, v74, v75
	v_lshl_add_u32 v75, v190, 4, v115
	ds_write_b32 v75, v74

; __device__ __forceinline__ float siluf(float x) { return x * __builtin_amdgcn_rcpf(1.0f + __expf(-x)); }
; __device__ __forceinline__ float shx(float v, int o, int lane) { return __builtin_bit_cast(float, __builtin_amdgcn_ds_bpermute((lane ^ o) << 2, __builtin_bit_cast(int, v))); }
; __device__ __forceinline__ void ssd_passB(const Ptrs& P, int l, int b, int ch, int gg, unsigned char* lds, int tid, bool dost) {
;     ...
;             for (int pt = 0; pt < 4; ++pt) { const u32x2 zw = zwv[lti][pt];
;                 const float zf[4] = {bflo(zw.x), bfhi(zw.x), bflo(zw.y), bfhi(zw.y)};
; #pragma unroll
;                 for (int r = 0; r < 4; ++r) { const float xs = bf2f(Xt[sdz(hh * 64 + 16 * pt + 4 * g + r, li)]); const float y = o[pt][r] + xs * dsk; const float v = y * siluf(zf[r]); gz[lti][pt][r] = v; part += v * v; } }
;             part += shx(part, 16, lane); part += shx(part, 32, lane);
;             if (g == 0) SSQ[li * 4 + hh] = part;
.LBB0_1047:
	s_or_b64 exec, exec, s[4:5]
	s_movk_i32 s3, 0x48
	v_bitop3_b32 v92, v196, v188, s3 bitop3:0x6c
	v_lshlrev_b32_e32 v92, 1, v92
	v_mul_u32_u24_e32 v100, 0x110, v196
	v_add3_u32 v98, 0, v92, v100
	ds_read_u16 v112, v98
	ds_read_u16 v113, v98 offset:272
	ds_read_u16 v203, v98 offset:544
	ds_read_u16 v204, v98 offset:816
	s_nop 0
	v_lshlrev_b32_e32 v92, 16, v176
	v_and_b32_e32 v93, 0xffff0000, v176
	v_mul_f32_e32 v94, 0xbfb8aa3b, v92
	v_exp_f32_e32 v94, v94
	s_waitcnt lgkmcnt(2)
	v_lshlrev_b32_e32 v97, 16, v113
	v_lshlrev_b32_e32 v96, 16, v112
	v_mul_f32_e32 v95, 0xbfb8aa3b, v93
	v_exp_f32_e32 v95, v95
	v_add_f32_e32 v94, 1.0, v94
	v_rcp_f32_e32 v94, v94
	v_lshlrev_b32_e32 v91, 16, v177
	v_add_f32_e32 v95, 1.0, v95
	v_rcp_f32_e32 v95, v95
	v_pk_fma_f32 v[86:87], v[120:121], v[96:97], v[86:87] op_sel_hi:[0,1,1]
	v_and_b32_e32 v90, 0xffff0000, v177
	v_mov_b32_e32 v99, v120
	v_pk_mul_f32 v[92:93], v[94:95], v[92:93]
	s_movk_i32 s3, 0x58
	v_pk_mul_f32 v[86:87], v[92:93], v[86:87]
	v_mul_f32_e32 v93, 0xbfb8aa3b, v91
	v_exp_f32_e32 v93, v93
	s_nop 0
	v_mov_b32_e32 v103, v120
	v_mad_u32_u24 v108, v196, s26, v242
	v_add_f32_e32 v93, 1.0, v93
	v_rcp_f32_e32 v93, v93
	v_mov_b32_e32 v107, v120
	v_pk_mul_f32 v[94:95], v[86:87], v[86:87]
	v_mov_b32_e32 v111, v120
	v_mul_f32_e32 v96, v93, v91
	v_mul_f32_e32 v93, 0xbfb8aa3b, v90
	v_exp_f32_e32 v93, v93
	s_nop 0
	s_waitcnt lgkmcnt(1)
	v_lshlrev_b32_e32 v92, 16, v203
	v_mul_f32_e32 v92, v120, v92
	v_add_f32_e32 v93, 1.0, v93
	v_rcp_f32_e32 v98, v93
	s_waitcnt lgkmcnt(0)
	v_lshlrev_b32_e32 v91, 16, v204
	v_add_f32_e32 v94, v94, v95
	v_pk_mul_f32 v[90:91], v[98:99], v[90:91]
	s_nop 0
	v_mov_b32_e32 v93, v91
	v_pk_add_f32 v[88:89], v[88:89], v[92:93]
	v_or_b32_e32 v92, 16, v196
	v_bitop3_b32 v92, v92, v188, s3 bitop3:0x6c
	v_lshlrev_b32_e32 v92, 1, v92
	v_add3_u32 v102, 0, v92, v100
	ds_read_u16 v205, v102 offset:4352
	ds_read_u16 v206, v102 offset:4624
	ds_read_u16 v207, v102 offset:4896
	ds_read_u16 v208, v102 offset:5168
	s_nop 0
	v_lshlrev_b32_e32 v92, 16, v152
	v_and_b32_e32 v93, 0xffff0000, v152
	v_mul_f32_e32 v98, 0xbfb8aa3b, v92
	v_exp_f32_e32 v98, v98
	s_waitcnt lgkmcnt(2)
	v_lshlrev_b32_e32 v101, 16, v206
	v_lshlrev_b32_e32 v100, 16, v205
	v_mul_f32_e32 v99, 0xbfb8aa3b, v93
	v_exp_f32_e32 v99, v99
	v_add_f32_e32 v98, 1.0, v98
	v_rcp_f32_e32 v98, v98
	v_lshlrev_b32_e32 v91, 16, v153
	v_add_f32_e32 v99, 1.0, v99
	v_rcp_f32_e32 v99, v99
	v_pk_fma_f32 v[82:83], v[120:121], v[100:101], v[82:83] op_sel_hi:[0,1,1]
	v_mov_b32_e32 v97, v90
	v_and_b32_e32 v90, 0xffff0000, v153
	v_pk_mul_f32 v[92:93], v[98:99], v[92:93]
	s_movk_i32 s3, 0x68
	v_pk_mul_f32 v[82:83], v[92:93], v[82:83]
	v_mul_f32_e32 v93, 0xbfb8aa3b, v91
	v_exp_f32_e32 v93, v93
	s_nop 0
	v_pk_mul_f32 v[88:89], v[96:97], v[88:89]
	v_pk_mul_f32 v[98:99], v[82:83], v[82:83]
	v_add_f32_e32 v93, 1.0, v93
	v_rcp_f32_e32 v93, v93
	v_pk_mul_f32 v[96:97], v[88:89], v[88:89]
	v_mul_f32_e32 v100, v93, v91
	v_mul_f32_e32 v93, 0xbfb8aa3b, v90
	v_exp_f32_e32 v93, v93
	s_nop 0
	s_waitcnt lgkmcnt(1)
	v_lshlrev_b32_e32 v92, 16, v207
	v_mul_f32_e32 v92, v120, v92
	v_add_f32_e32 v93, 1.0, v93
	v_rcp_f32_e32 v102, v93
	s_waitcnt lgkmcnt(0)
	v_lshlrev_b32_e32 v91, 16, v208
	v_add_f32_e32 v94, v94, v96
	v_add_f32_e32 v94, v94, v97
	v_pk_mul_f32 v[90:91], v[102:103], v[90:91]
	v_add_f32_e32 v94, v94, v98
	v_mov_b32_e32 v93, v91
	v_pk_add_f32 v[84:85], v[84:85], v[92:93]
	v_or_b32_e32 v92, 32, v196
	v_bitop3_b32 v92, v92, v188, s3 bitop3:0x6c
	v_lshl_add_u32 v92, v92, 1, 0
	v_add_u32_e32 v103, v92, v108
	ds_read_u16 v209, v103
	v_mad_u32_u24 v106, v196, s26, v92
	ds_read_u16 v211, v106 offset:8976
	ds_read_u16 v212, v106 offset:9248
	ds_read_u16 v216, v106 offset:9520
	s_nop 0
	s_nop 0
	v_lshlrev_b32_e32 v92, 16, v150
	v_and_b32_e32 v93, 0xffff0000, v150
	v_mul_f32_e32 v102, 0xbfb8aa3b, v92
	s_waitcnt lgkmcnt(3)
; __device__ __forceinline__ float siluf(float x) { return x * __builtin_amdgcn_rcpf(1.0f + __expf(-x)); }
; __device__ __forceinline__ float shx(float v, int o, int lane) { return __builtin_bit_cast(float, __builtin_amdgcn_ds_bpermute((lane ^ o) << 2, __builtin_bit_cast(int, v))); }
; __device__ __forceinline__ void ssd_passB(const Ptrs& P, int l, int b, int ch, int gg, unsigned char* lds, int tid, bool dost) {
;     ...
;             for (int pt = 0; pt < 4; ++pt) { const u32x2 zw = zwv[lti][pt];
;                 const float zf[4] = {bflo(zw.x), bfhi(zw.x), bflo(zw.y), bfhi(zw.y)};
; #pragma unroll
;                 for (int r = 0; r < 4; ++r) { const float xs = bf2f(Xt[sdz(hh * 64 + 16 * pt + 4 * g + r, li)]); const float y = o[pt][r] + xs * dsk; const float v = y * siluf(zf[r]); gz[lti][pt][r] = v; part += v * v; } }
;             part += shx(part, 16, lane); part += shx(part, 32, lane);
;             if (g == 0) SSQ[li * 4 + hh] = part;
	v_lshlrev_b32_e32 v104, 16, v209
	v_mul_f32_e32 v103, 0xbfb8aa3b, v93
	v_exp_f32_e32 v102, v102
	v_exp_f32_e32 v103, v103
	s_waitcnt lgkmcnt(2)
	v_lshlrev_b32_e32 v105, 16, v211
	v_lshlrev_b32_e32 v91, 16, v151
	v_add_f32_e32 v102, 1.0, v102
	v_add_f32_e32 v103, 1.0, v103
	v_rcp_f32_e32 v102, v102
	v_rcp_f32_e32 v103, v103
	v_pk_fma_f32 v[78:79], v[120:121], v[104:105], v[78:79] op_sel_hi:[0,1,1]
	v_mov_b32_e32 v101, v90
	v_and_b32_e32 v90, 0xffff0000, v151
	v_pk_mul_f32 v[92:93], v[102:103], v[92:93]
	v_pk_mul_f32 v[84:85], v[100:101], v[84:85]
	v_pk_mul_f32 v[78:79], v[92:93], v[78:79]
	v_mul_f32_e32 v93, 0xbfb8aa3b, v91
	v_exp_f32_e32 v93, v93
	s_nop 0
	v_pk_mul_f32 v[100:101], v[84:85], v[84:85]
	v_add_f32_e32 v94, v94, v99
	v_add_f32_e32 v93, 1.0, v93
	v_rcp_f32_e32 v93, v93
	v_add_f32_e32 v94, v94, v100
	v_pk_mul_f32 v[102:103], v[78:79], v[78:79]
	v_add_f32_e32 v94, v94, v101
	v_mul_f32_e32 v104, v93, v91
	v_mul_f32_e32 v93, 0xbfb8aa3b, v90
	v_exp_f32_e32 v93, v93
	s_nop 0
	s_waitcnt lgkmcnt(1)
	v_lshlrev_b32_e32 v92, 16, v212
	v_mul_f32_e32 v92, v120, v92
	v_add_f32_e32 v93, 1.0, v93
	v_rcp_f32_e32 v106, v93
	s_waitcnt lgkmcnt(0)
	v_lshlrev_b32_e32 v91, 16, v216
	v_add_f32_e32 v94, v94, v102
	v_add_f32_e32 v94, v94, v103
	v_pk_mul_f32 v[90:91], v[106:107], v[90:91]
	s_nop 0
	v_mov_b32_e32 v105, v90
	v_or_b32_e32 v90, 48, v196
	v_bitop3_b32 v90, v90, v188, s16 bitop3:0x6c
	v_lshl_add_u32 v90, v90, 1, 0
	v_add_u32_e32 v107, v108, v90
	ds_read_u16 v217, v107 offset:4352
	v_mad_u32_u24 v110, v196, s26, v90
	ds_read_u16 v218, v110 offset:13328
	ds_read_u16 v219, v110 offset:13600
	ds_read_u16 v220, v110 offset:13872
	s_nop 0
	s_nop 0
	v_mov_b32_e32 v93, v91
	v_lshlrev_b32_e32 v90, 16, v148
	v_and_b32_e32 v91, 0xffff0000, v148
	v_mul_f32_e32 v106, 0xbfb8aa3b, v90
	s_waitcnt lgkmcnt(3)
	v_lshlrev_b32_e32 v108, 16, v217
	v_mul_f32_e32 v107, 0xbfb8aa3b, v91
	v_exp_f32_e32 v106, v106
	v_exp_f32_e32 v107, v107
	v_pk_add_f32 v[80:81], v[80:81], v[92:93]
	v_lshlrev_b32_e32 v93, 16, v149
	v_add_f32_e32 v106, 1.0, v106
	v_add_f32_e32 v107, 1.0, v107
	v_rcp_f32_e32 v106, v106
	v_rcp_f32_e32 v107, v107
	v_and_b32_e32 v92, 0xffff0000, v149
	s_waitcnt lgkmcnt(2)
	v_lshlrev_b32_e32 v109, 16, v218
	v_pk_fma_f32 v[74:75], v[120:121], v[108:109], v[74:75] op_sel_hi:[0,1,1]
	v_pk_mul_f32 v[90:91], v[106:107], v[90:91]
	v_mul_f32_e32 v107, 0xbfb8aa3b, v93
	v_exp_f32_e32 v107, v107
	s_nop 0
	v_pk_mul_f32 v[80:81], v[104:105], v[80:81]
	v_pk_mul_f32 v[90:91], v[90:91], v[74:75]
	v_add_f32_e32 v107, 1.0, v107
	v_rcp_f32_e32 v107, v107
	v_pk_mul_f32 v[104:105], v[80:81], v[80:81]
	v_pk_mul_f32 v[74:75], v[90:91], v[90:91]
	v_add_f32_e32 v94, v94, v104
	v_mul_f32_e32 v108, v107, v93
	v_mul_f32_e32 v107, 0xbfb8aa3b, v92
	v_exp_f32_e32 v107, v107
	s_nop 0
	s_waitcnt lgkmcnt(1)
	v_lshlrev_b32_e32 v106, 16, v219
	v_mul_f32_e32 v106, v120, v106
	v_add_f32_e32 v107, 1.0, v107
	v_rcp_f32_e32 v110, v107
	s_waitcnt lgkmcnt(0)
	v_lshlrev_b32_e32 v93, 16, v220
	v_add_f32_e32 v94, v94, v105
	v_add_f32_e32 v74, v94, v74
	v_pk_mul_f32 v[92:93], v[110:111], v[92:93]
	v_add_f32_e32 v74, v74, v75
	v_mov_b32_e32 v107, v93
	v_pk_add_f32 v[76:77], v[76:77], v[106:107]
	v_mov_b32_e32 v109, v92
	v_pk_mul_f32 v[92:93], v[108:109], v[76:77]
	s_nop 0
	v_pk_mul_f32 v[76:77], v[92:93], v[92:93]
	s_nop 0
	v_add_f32_e32 v74, v74, v76
	v_add_f32_e32 v74, v74, v77
	ds_bpermute_b32 v75, v195, v74
	s_waitcnt lgkmcnt(0)
	v_add_f32_e32 v74, v74, v75
	ds_bpermute_b32 v75, v117, v74
	s_and_saveexec_b64 s[4:5], s[40:41]
	s_cbranch_execz .LBB0_1049
	s_waitcnt lgkmcnt(0)
	v_add_f32_e32 v74, v74, v75
	v_lshl_add_u32 v75, v188, 4, v115
	ds_write_b32 v75, v74

; __device__ __forceinline__ float siluf(float x) { return x * __builtin_amdgcn_rcpf(1.0f + __expf(-x)); }
; __device__ __forceinline__ float shx(float v, int o, int lane) { return __builtin_bit_cast(float, __builtin_amdgcn_ds_bpermute((lane ^ o) << 2, __builtin_bit_cast(int, v))); }
; __device__ __forceinline__ void ssd_passB(const Ptrs& P, int l, int b, int ch, int gg, unsigned char* lds, int tid, bool dost) {
;     ...
;             for (int pt = 0; pt < 4; ++pt) { const u32x2 zw = zwv[lti][pt];
;                 const float zf[4] = {bflo(zw.x), bfhi(zw.x), bflo(zw.y), bfhi(zw.y)};
; #pragma unroll
;                 for (int r = 0; r < 4; ++r) { const float xs = bf2f(Xt[sdz(hh * 64 + 16 * pt + 4 * g + r, li)]); const float y = o[pt][r] + xs * dsk; const float v = y * siluf(zf[r]); gz[lti][pt][r] = v; part += v * v; } }
;             part += shx(part, 16, lane); part += shx(part, 32, lane);
;             if (g == 0) SSQ[li * 4 + hh] = part;
.LBB0_1070:
	s_or_b64 exec, exec, s[4:5]
	s_movk_i32 s3, 0x48
	v_bitop3_b32 v26, v196, v121, s3 bitop3:0x6c
	v_lshlrev_b32_e32 v26, 1, v26
	v_mul_u32_u24_e32 v36, 0x110, v196
	v_add3_u32 v34, 0, v26, v36
	ds_read_u16 v62, v34
	ds_read_u16 v70, v34 offset:272
	ds_read_u16 v72, v34 offset:544
	ds_read_u16 v73, v34 offset:816
	s_nop 0
	v_lshlrev_b32_e32 v26, 16, v132
	v_and_b32_e32 v27, 0xffff0000, v132
	v_mul_f32_e32 v30, 0xbfb8aa3b, v26
	v_exp_f32_e32 v30, v30
	s_waitcnt lgkmcnt(2)
	v_lshlrev_b32_e32 v33, 16, v70
	v_lshlrev_b32_e32 v32, 16, v62
	v_mul_f32_e32 v31, 0xbfb8aa3b, v27
	v_exp_f32_e32 v31, v31
	v_add_f32_e32 v30, 1.0, v30
	v_rcp_f32_e32 v30, v30
	v_lshlrev_b32_e32 v29, 16, v133
	v_add_f32_e32 v31, 1.0, v31
	v_rcp_f32_e32 v31, v31
	v_and_b32_e32 v28, 0xffff0000, v133
	v_pk_fma_f32 v[22:23], v[120:121], v[32:33], v[22:23] op_sel_hi:[0,1,1]
	v_mov_b32_e32 v35, v120
	v_pk_mul_f32 v[26:27], v[30:31], v[26:27]
	v_mul_f32_e32 v31, 0xbfb8aa3b, v29
	v_exp_f32_e32 v31, v31
	s_nop 0
	s_movk_i32 s3, 0x58
	v_mov_b32_e32 v39, v120
	v_add_f32_e32 v31, 1.0, v31
	v_rcp_f32_e32 v31, v31
	v_mad_u32_u24 v44, v196, s26, v242
	v_mov_b32_e32 v43, v120
	v_pk_mul_f32 v[26:27], v[26:27], v[22:23]
	v_mul_f32_e32 v32, v31, v29
	v_mul_f32_e32 v31, 0xbfb8aa3b, v28
	v_exp_f32_e32 v31, v31
	s_nop 0
	s_waitcnt lgkmcnt(1)
	v_lshlrev_b32_e32 v30, 16, v72
	v_mul_f32_e32 v30, v120, v30
	v_add_f32_e32 v31, 1.0, v31
	v_rcp_f32_e32 v34, v31
	s_waitcnt lgkmcnt(0)
	v_lshlrev_b32_e32 v29, 16, v73
	v_pk_mul_f32 v[22:23], v[26:27], v[26:27]
	v_mov_b32_e32 v47, v120
	v_pk_mul_f32 v[28:29], v[34:35], v[28:29]
	v_add_f32_e32 v22, v22, v23
	v_mov_b32_e32 v31, v29
	v_pk_add_f32 v[24:25], v[24:25], v[30:31]
	v_or_b32_e32 v30, 16, v196
	v_bitop3_b32 v30, v30, v121, s3 bitop3:0x6c
	v_lshlrev_b32_e32 v30, 1, v30
	v_add3_u32 v38, 0, v30, v36
	ds_read_u16 v76, v38 offset:4352
	ds_read_u16 v77, v38 offset:4624
	ds_read_u16 v94, v38 offset:4896
	ds_read_u16 v95, v38 offset:5168
	s_nop 0
	v_lshlrev_b32_e32 v30, 16, v126
	v_and_b32_e32 v31, 0xffff0000, v126
	v_mul_f32_e32 v34, 0xbfb8aa3b, v30
	v_exp_f32_e32 v34, v34
	s_waitcnt lgkmcnt(2)
	v_lshlrev_b32_e32 v37, 16, v77
	v_lshlrev_b32_e32 v36, 16, v76
	v_mul_f32_e32 v35, 0xbfb8aa3b, v31
	v_exp_f32_e32 v35, v35
	v_add_f32_e32 v34, 1.0, v34
	v_rcp_f32_e32 v34, v34
	v_mov_b32_e32 v33, v28
	v_add_f32_e32 v35, 1.0, v35
	v_rcp_f32_e32 v35, v35
	v_pk_mul_f32 v[28:29], v[32:33], v[24:25]
	v_lshlrev_b32_e32 v33, 16, v127
	v_and_b32_e32 v32, 0xffff0000, v127
	v_pk_mul_f32 v[30:31], v[34:35], v[30:31]
	v_mul_f32_e32 v35, 0xbfb8aa3b, v33
	v_exp_f32_e32 v35, v35
	v_pk_fma_f32 v[18:19], v[120:121], v[36:37], v[18:19] op_sel_hi:[0,1,1]
	s_nop 0
	s_movk_i32 s3, 0x68
	v_add_f32_e32 v35, 1.0, v35
	v_rcp_f32_e32 v35, v35
	v_pk_mul_f32 v[24:25], v[28:29], v[28:29]
	v_pk_mul_f32 v[30:31], v[30:31], v[18:19]
	v_add_f32_e32 v22, v22, v24
	v_mul_f32_e32 v36, v35, v33
	v_mul_f32_e32 v35, 0xbfb8aa3b, v32
	v_exp_f32_e32 v35, v35
	s_nop 0
	s_waitcnt lgkmcnt(1)
	v_lshlrev_b32_e32 v34, 16, v94
	v_mul_f32_e32 v34, v120, v34
	v_add_f32_e32 v35, 1.0, v35
	v_rcp_f32_e32 v38, v35
	s_waitcnt lgkmcnt(0)
	v_lshlrev_b32_e32 v33, 16, v95
	v_pk_mul_f32 v[18:19], v[30:31], v[30:31]
	v_add_f32_e32 v22, v22, v25
	v_pk_mul_f32 v[32:33], v[38:39], v[32:33]
	v_add_f32_e32 v18, v22, v18
	v_mov_b32_e32 v35, v33
	v_pk_add_f32 v[20:21], v[20:21], v[34:35]
	v_or_b32_e32 v34, 32, v196
	v_bitop3_b32 v34, v34, v121, s3 bitop3:0x6c
	v_lshl_add_u32 v34, v34, 1, 0
	v_add_u32_e32 v39, v34, v44
	ds_read_u16 v96, v39
	v_mad_u32_u24 v42, v196, s26, v34
	ds_read_u16 v97, v42 offset:8976
	ds_read_u16 v98, v42 offset:9248
	ds_read_u16 v99, v42 offset:9520
	s_nop 0
	s_nop 0
	v_lshlrev_b32_e32 v34, 16, v124
	v_and_b32_e32 v35, 0xffff0000, v124
	v_mul_f32_e32 v38, 0xbfb8aa3b, v34
	s_waitcnt lgkmcnt(3)
; __device__ __forceinline__ float siluf(float x) { return x * __builtin_amdgcn_rcpf(1.0f + __expf(-x)); }
; __device__ __forceinline__ float shx(float v, int o, int lane) { return __builtin_bit_cast(float, __builtin_amdgcn_ds_bpermute((lane ^ o) << 2, __builtin_bit_cast(int, v))); }
; __device__ __forceinline__ void ssd_passB(const Ptrs& P, int l, int b, int ch, int gg, unsigned char* lds, int tid, bool dost) {
;     ...
;             for (int pt = 0; pt < 4; ++pt) { const u32x2 zw = zwv[lti][pt];
;                 const float zf[4] = {bflo(zw.x), bfhi(zw.x), bflo(zw.y), bfhi(zw.y)};
; #pragma unroll
;                 for (int r = 0; r < 4; ++r) { const float xs = bf2f(Xt[sdz(hh * 64 + 16 * pt + 4 * g + r, li)]); const float y = o[pt][r] + xs * dsk; const float v = y * siluf(zf[r]); gz[lti][pt][r] = v; part += v * v; } }
;             part += shx(part, 16, lane); part += shx(part, 32, lane);
;             if (g == 0) SSQ[li * 4 + hh] = part;
	v_lshlrev_b32_e32 v40, 16, v96
	v_mul_f32_e32 v39, 0xbfb8aa3b, v35
	v_exp_f32_e32 v38, v38
	v_exp_f32_e32 v39, v39
	v_mov_b32_e32 v37, v32
	v_pk_mul_f32 v[32:33], v[36:37], v[20:21]
	v_add_f32_e32 v38, 1.0, v38
	v_add_f32_e32 v39, 1.0, v39
	v_rcp_f32_e32 v38, v38
	v_rcp_f32_e32 v39, v39
	v_lshlrev_b32_e32 v37, 16, v125
	v_and_b32_e32 v36, 0xffff0000, v125
	s_waitcnt lgkmcnt(2)
	v_lshlrev_b32_e32 v41, 16, v97
	v_pk_mul_f32 v[34:35], v[38:39], v[34:35]
	v_mul_f32_e32 v39, 0xbfb8aa3b, v37
	v_exp_f32_e32 v39, v39
	v_pk_fma_f32 v[12:13], v[120:121], v[40:41], v[12:13] op_sel_hi:[0,1,1]
	s_nop 0
	v_pk_mul_f32 v[20:21], v[32:33], v[32:33]
	v_add_f32_e32 v39, 1.0, v39
	v_rcp_f32_e32 v39, v39
	v_add_f32_e32 v18, v18, v19
	v_pk_mul_f32 v[34:35], v[34:35], v[12:13]
	v_add_f32_e32 v18, v18, v20
	v_mul_f32_e32 v40, v39, v37
	v_mul_f32_e32 v39, 0xbfb8aa3b, v36
	v_exp_f32_e32 v39, v39
	s_nop 0
	s_waitcnt lgkmcnt(1)
	v_lshlrev_b32_e32 v38, 16, v98
	v_mul_f32_e32 v38, v120, v38
	v_add_f32_e32 v39, 1.0, v39
	v_rcp_f32_e32 v42, v39
	s_waitcnt lgkmcnt(0)
	v_lshlrev_b32_e32 v37, 16, v99
	v_pk_mul_f32 v[12:13], v[34:35], v[34:35]
	v_add_f32_e32 v18, v18, v21
	v_pk_mul_f32 v[36:37], v[42:43], v[36:37]
	v_add_f32_e32 v12, v18, v12
	v_mov_b32_e32 v39, v37
	v_pk_add_f32 v[14:15], v[14:15], v[38:39]
	v_or_b32_e32 v38, 48, v196
	v_bitop3_b32 v38, v38, v121, s16 bitop3:0x6c
	v_lshl_add_u32 v38, v38, 1, 0
	v_add_u32_e32 v43, v44, v38
	ds_read_u16 v100, v43 offset:4352
	v_mad_u32_u24 v46, v196, s26, v38
	ds_read_u16 v101, v46 offset:13328
	ds_read_u16 v102, v46 offset:13600
	ds_read_u16 v103, v46 offset:13872
	s_nop 0
	s_nop 0
	v_lshlrev_b32_e32 v38, 16, v122
	v_and_b32_e32 v39, 0xffff0000, v122
	v_mul_f32_e32 v42, 0xbfb8aa3b, v38
	s_waitcnt lgkmcnt(3)
	v_lshlrev_b32_e32 v44, 16, v100
	v_mul_f32_e32 v43, 0xbfb8aa3b, v39
	v_exp_f32_e32 v42, v42
	v_exp_f32_e32 v43, v43
	v_mov_b32_e32 v41, v36
	v_pk_mul_f32 v[36:37], v[40:41], v[14:15]
	v_add_f32_e32 v42, 1.0, v42
	v_add_f32_e32 v43, 1.0, v43
	v_rcp_f32_e32 v42, v42
	v_rcp_f32_e32 v43, v43
	v_lshlrev_b32_e32 v41, 16, v123
	v_and_b32_e32 v40, 0xffff0000, v123
	s_waitcnt lgkmcnt(2)
	v_lshlrev_b32_e32 v45, 16, v101
	v_pk_mul_f32 v[38:39], v[42:43], v[38:39]
	v_mul_f32_e32 v43, 0xbfb8aa3b, v41
	v_exp_f32_e32 v43, v43
	v_pk_fma_f32 v[8:9], v[120:121], v[44:45], v[8:9] op_sel_hi:[0,1,1]
	s_nop 0
	v_pk_mul_f32 v[14:15], v[36:37], v[36:37]
	v_add_f32_e32 v43, 1.0, v43
	v_rcp_f32_e32 v43, v43
	v_add_f32_e32 v12, v12, v13
	v_pk_mul_f32 v[38:39], v[38:39], v[8:9]
	v_add_f32_e32 v12, v12, v14
	v_mul_f32_e32 v44, v43, v41
	v_mul_f32_e32 v43, 0xbfb8aa3b, v40
	v_exp_f32_e32 v43, v43
	s_nop 0
	s_waitcnt lgkmcnt(1)
	v_lshlrev_b32_e32 v42, 16, v102
	v_mul_f32_e32 v42, v120, v42
	v_add_f32_e32 v43, 1.0, v43
	v_rcp_f32_e32 v46, v43
	s_waitcnt lgkmcnt(0)
	v_lshlrev_b32_e32 v41, 16, v103
	v_pk_mul_f32 v[8:9], v[38:39], v[38:39]
	v_add_f32_e32 v12, v12, v15
	v_pk_mul_f32 v[40:41], v[46:47], v[40:41]
	v_add_f32_e32 v8, v12, v8
	v_mov_b32_e32 v43, v41
	v_pk_add_f32 v[10:11], v[10:11], v[42:43]
	v_mov_b32_e32 v45, v40
	v_pk_mul_f32 v[40:41], v[44:45], v[10:11]
	v_add_f32_e32 v8, v8, v9
	v_pk_mul_f32 v[10:11], v[40:41], v[40:41]
	s_nop 0
	v_add_f32_e32 v8, v8, v10
	v_add_f32_e32 v8, v8, v11
	ds_bpermute_b32 v9, v195, v8
	s_waitcnt lgkmcnt(0)
	v_add_f32_e32 v8, v8, v9
	ds_bpermute_b32 v9, v117, v8
	s_and_saveexec_b64 s[4:5], s[40:41]
	s_cbranch_execz .LBB0_1072
	s_waitcnt lgkmcnt(0)
	v_add_f32_e32 v8, v8, v9
	v_lshl_add_u32 v9, v121, 4, v115
	ds_write_b32 v9, v8
